# K-loops: MMA-segment priority set in the loader path (s_setprio 1 before the pre-MMA barrier, s_setprio 0 after the post-MMA barrier), no setprio between MFMAs
# speedup vs baseline: 1.0088x; 1.0088x over previous
; #define PG8_STAGE(bufoff, gbase, voff) do { _Pragma("unroll") for (int _i = 0; _i < 2; ++_i) \
;         __builtin_amdgcn_global_load_lds((const unsigned*)((const char*)(gbase) + (voff)[_i]), (LAS unsigned*)(lds + (bufoff) + ldsw + _i * 8192), 16, 0, 0); } while (0)
; #define PG8_LDA(dst, b, h) do { _Pragma("unroll") for (int m = 0; m < 4; ++m) _Pragma("unroll") for (int k = 0; k < 2; ++k) dst[m][k] = *(const LAS bf16x8*)(lds + PG8_SA(b, h) + aoff + m * 2048 + k * 1024); } while (0)
; #define PG8_LDB(dst, b, h) do { _Pragma("unroll") for (int n = 0; n < 2; ++n) _Pragma("unroll") for (int k = 0; k < 2; ++k) dst[n][k] = *(const LAS bf16x8*)(lds + PG8_SB(b, h) + boff + n * 2048 + k * 1024); } while (0)
; #define PG8_MMA(ai, bj, At, Bt) do { __builtin_amdgcn_s_setprio(1); _Pragma("unroll") for (int m = 0; m < 4; ++m) _Pragma("unroll") for (int n = 0; n < 2; ++n) _Pragma("unroll") for (int k = 0; k < 2; ++k) \
;         acc[ai][bj][m][n] = __builtin_amdgcn_mfma_f32_16x16x32_bf16(Bt[n][k], At[m][k], acc[ai][bj][m][n], 0, 0, 0); __builtin_amdgcn_s_setprio(0); } while (0)
; #define PG8_WAIT_V(n) asm volatile("s_waitcnt vmcnt(" #n ")" ::: "memory")
; #define PG8_WAIT_L(n) asm volatile("s_waitcnt lgkmcnt(" #n ")" ::: "memory")
; #define PG8_BAR __builtin_amdgcn_s_barrier()
; #define PG8_SCHED __builtin_amdgcn_sched_barrier(0)
; template <class Epi, bool PERMA = false, bool DUAL = false, bool ALIGN_EPI = true, bool SP2 = true>
; __device__ __forceinline__ void gemm_phase(LAS unsigned char* lds, const Gemm g, const StaticOrder& S, const Epi& E) {
;     ...
;             const bool last = (t == nt - 2);
;             const char* a1 = cA + (size_t)(t + 1) * kstep;
;             const char* a2 = last ? nA : cA + (size_t)(t + 2) * kstep; const char* b2 = last ? nB : cB + (size_t)(t + 2) * kstep;
;             const char* a3 = a2 + kstep; const char* b3 = b2 + kstep;
;             if constexpr (SP2) {
;             PG8_LDB(B0, 0, 0); PG8_LDB(B1, 0, 1); PG8_SCHED; PG8_LDA(At, 0, 0); PG8_STAGE(PG8_SA(1, 1), a1 + hstepA, voffA);
;             PG8_WAIT_V(8); PG8_WAIT_L(0); PG8_BAR; PG8_MMA(0, 0, At, B0); PG8_MMA(0, 1, At, B1); PG8_BAR; PG8_SCHED;
;             PG8_LDA(At, 0, 1); PG8_STAGE(PG8_SB(0, 0), b2, voffB); PG8_STAGE(PG8_SB(0, 1), b2 + hstepB, voffB); PG8_STAGE(PG8_SA(0, 0), a2, voffA);
.LBB0_130:
	s_add_u32 s16, s14, 0xfff80080
	s_addc_u32 s17, s15, -1
	s_add_i32 s38, 0, 0x10000
	s_cmp_eq_u32 s37, 28
	s_cselect_b32 s19, s9, s17
	s_cselect_b32 s18, s33, s16
	s_cselect_b32 s17, s7, s36
	s_cselect_b32 s16, s34, s35
	s_add_i32 s40, 0, 0x14000
	v_add_u32_e32 v156, s38, v141
	v_add_u32_e32 v172, s40, v141
	ds_read_b128 v[144:147], v156
	ds_read_b128 v[148:151], v156 offset:1024
	ds_read_b128 v[152:155], v156 offset:2048
	ds_read_b128 v[156:159], v156 offset:3072
	ds_read_b128 v[160:163], v172
	ds_read_b128 v[164:167], v172 offset:1024
	ds_read_b128 v[168:171], v172 offset:2048
	ds_read_b128 v[172:175], v172 offset:3072
	v_lshl_add_u64 v[222:223], s[14:15], 0, v[136:137]
	s_add_i32 m0, s21, 0xc000
	ds_read_b128 v[176:179], v143
	ds_read_b128 v[180:183], v143 offset:1024
	ds_read_b128 v[184:187], v143 offset:2048
	ds_read_b128 v[188:191], v143 offset:3072
	ds_read_b128 v[206:209], v143 offset:4096
	ds_read_b128 v[210:213], v143 offset:5120
	ds_read_b128 v[214:217], v143 offset:6144
	ds_read_b128 v[218:221], v143 offset:7168
	global_load_lds_dwordx4 v[222:223], off
	v_lshl_add_u64 v[222:223], s[14:15], 0, v[138:139]
	s_add_i32 m0, s21, 0xe000
	s_nop 0
	global_load_lds_dwordx4 v[222:223], off
	s_waitcnt vmcnt(8)
	s_waitcnt lgkmcnt(0)
	s_setprio 1
	s_barrier
	s_waitcnt lgkmcnt(0)
	v_mfma_f32_16x16x32_bf16 v[124:127], v[144:147], v[176:179], v[124:127]
	v_mfma_f32_16x16x32_bf16 v[120:123], v[152:155], v[176:179], v[120:123]
	v_mfma_f32_16x16x32_bf16 v[116:119], v[144:147], v[184:187], v[116:119]
	v_mfma_f32_16x16x32_bf16 v[108:111], v[152:155], v[184:187], v[108:111]
	v_mfma_f32_16x16x32_bf16 v[100:103], v[144:147], v[206:209], v[100:103]
	v_mfma_f32_16x16x32_bf16 v[92:95], v[152:155], v[206:209], v[92:95]
	v_mfma_f32_16x16x32_bf16 v[84:87], v[144:147], v[214:217], v[84:87]
	v_mfma_f32_16x16x32_bf16 v[76:79], v[152:155], v[214:217], v[76:79]
	v_mfma_f32_16x16x32_bf16 v[124:127], v[148:151], v[180:183], v[124:127]
	v_mfma_f32_16x16x32_bf16 v[120:123], v[156:159], v[180:183], v[120:123]
	v_mfma_f32_16x16x32_bf16 v[116:119], v[148:151], v[188:191], v[116:119]
	v_mfma_f32_16x16x32_bf16 v[108:111], v[156:159], v[188:191], v[108:111]
	v_mfma_f32_16x16x32_bf16 v[100:103], v[148:151], v[210:213], v[100:103]
	v_mfma_f32_16x16x32_bf16 v[92:95], v[156:159], v[210:213], v[92:95]
	v_mfma_f32_16x16x32_bf16 v[84:87], v[148:151], v[218:221], v[84:87]
	v_mfma_f32_16x16x32_bf16 v[76:79], v[156:159], v[218:221], v[76:79]
	v_mfma_f32_16x16x32_bf16 v[112:115], v[160:163], v[176:179], v[112:115]
	v_mfma_f32_16x16x32_bf16 v[104:107], v[168:171], v[176:179], v[104:107]
	v_mfma_f32_16x16x32_bf16 v[96:99], v[160:163], v[184:187], v[96:99]
	v_mfma_f32_16x16x32_bf16 v[88:91], v[168:171], v[184:187], v[88:91]
	v_mfma_f32_16x16x32_bf16 v[80:83], v[160:163], v[206:209], v[80:83]
	v_mfma_f32_16x16x32_bf16 v[72:75], v[168:171], v[206:209], v[72:75]
	v_mfma_f32_16x16x32_bf16 v[68:71], v[160:163], v[214:217], v[68:71]
	v_mfma_f32_16x16x32_bf16 v[64:67], v[168:171], v[214:217], v[64:67]
	v_mfma_f32_16x16x32_bf16 v[112:115], v[164:167], v[180:183], v[112:115]
	v_mfma_f32_16x16x32_bf16 v[104:107], v[172:175], v[180:183], v[104:107]
	v_mfma_f32_16x16x32_bf16 v[96:99], v[164:167], v[188:191], v[96:99]
	v_mfma_f32_16x16x32_bf16 v[88:91], v[172:175], v[188:191], v[88:91]
	v_mfma_f32_16x16x32_bf16 v[80:83], v[164:167], v[210:213], v[80:83]
	v_mfma_f32_16x16x32_bf16 v[72:75], v[172:175], v[210:213], v[72:75]
	v_mfma_f32_16x16x32_bf16 v[68:71], v[164:167], v[218:221], v[68:71]
	v_mfma_f32_16x16x32_bf16 v[64:67], v[172:175], v[218:221], v[64:67]
	s_barrier
	s_setprio 0
	s_add_i32 s38, s38, s20
	v_lshl_add_u64 v[222:223], s[16:17], 0, v[132:133]
	s_mov_b32 m0, s38
	ds_read_b128 v[176:179], v143 offset:16384
	ds_read_b128 v[180:183], v143 offset:17408
	ds_read_b128 v[184:187], v143 offset:18432
	ds_read_b128 v[188:191], v143 offset:19456
	ds_read_b128 v[206:209], v143 offset:20480
	ds_read_b128 v[210:213], v143 offset:21504
	ds_read_b128 v[214:217], v143 offset:22528
	ds_read_b128 v[218:221], v143 offset:23552
	global_load_lds_dwordx4 v[222:223], off
	s_add_i32 m0, s38, 0x2000
	s_add_u32 s38, s16, 0x80000
	v_lshl_add_u64 v[224:225], s[16:17], 0, v[128:129]
	s_addc_u32 s39, s17, 0
	s_add_i32 s40, s40, s20
	global_load_lds_dwordx4 v[224:225], off
	v_lshl_add_u64 v[226:227], s[38:39], 0, v[132:133]
	s_mov_b32 m0, s40
	v_lshl_add_u64 v[228:229], s[18:19], 0, v[130:131]
	global_load_lds_dwordx4 v[226:227], off
	v_lshl_add_u64 v[226:227], s[38:39], 0, v[128:129]
	s_add_i32 m0, s40, 0x2000
	s_nop 0
	global_load_lds_dwordx4 v[226:227], off
	v_lshl_add_u64 v[226:227], s[18:19], 0, v[134:135]
	s_mov_b32 m0, s21
	s_nop 0
	global_load_lds_dwordx4 v[226:227], off
	s_mov_b32 m0, s22
	s_nop 0
	global_load_lds_dwordx4 v[228:229], off
	s_waitcnt vmcnt(8)
	s_waitcnt lgkmcnt(0)
	s_setprio 1
	s_barrier
; #define PG8_STAGE(bufoff, gbase, voff) do { _Pragma("unroll") for (int _i = 0; _i < 2; ++_i) \
;         __builtin_amdgcn_global_load_lds((const unsigned*)((const char*)(gbase) + (voff)[_i]), (LAS unsigned*)(lds + (bufoff) + ldsw + _i * 8192), 16, 0, 0); } while (0)
; #define PG8_LDA(dst, b, h) do { _Pragma("unroll") for (int m = 0; m < 4; ++m) _Pragma("unroll") for (int k = 0; k < 2; ++k) dst[m][k] = *(const LAS bf16x8*)(lds + PG8_SA(b, h) + aoff + m * 2048 + k * 1024); } while (0)
; #define PG8_LDB(dst, b, h) do { _Pragma("unroll") for (int n = 0; n < 2; ++n) _Pragma("unroll") for (int k = 0; k < 2; ++k) dst[n][k] = *(const LAS bf16x8*)(lds + PG8_SB(b, h) + boff + n * 2048 + k * 1024); } while (0)
; #define PG8_MMA(ai, bj, At, Bt) do { __builtin_amdgcn_s_setprio(1); _Pragma("unroll") for (int m = 0; m < 4; ++m) _Pragma("unroll") for (int n = 0; n < 2; ++n) _Pragma("unroll") for (int k = 0; k < 2; ++k) \
;         acc[ai][bj][m][n] = __builtin_amdgcn_mfma_f32_16x16x32_bf16(Bt[n][k], At[m][k], acc[ai][bj][m][n], 0, 0, 0); __builtin_amdgcn_s_setprio(0); } while (0)
; #define PG8_WAIT_V(n) asm volatile("s_waitcnt vmcnt(" #n ")" ::: "memory")
; #define PG8_WAIT_L(n) asm volatile("s_waitcnt lgkmcnt(" #n ")" ::: "memory")
; #define PG8_BAR __builtin_amdgcn_s_barrier()
; #define PG8_SCHED __builtin_amdgcn_sched_barrier(0)
; template <class Epi, bool PERMA = false, bool DUAL = false, bool ALIGN_EPI = true, bool SP2 = true>
; __device__ __forceinline__ void gemm_phase(LAS unsigned char* lds, const Gemm g, const StaticOrder& S, const Epi& E) {
;     ...
;             PG8_WAIT_V(8); PG8_WAIT_L(0); PG8_BAR; PG8_MMA(1, 0, At, B0); PG8_MMA(1, 1, At, B1); PG8_BAR; PG8_SCHED;
;             PG8_LDB(B0, 1, 0); PG8_LDB(B1, 1, 1); PG8_SCHED; PG8_LDA(At, 1, 0); PG8_STAGE(PG8_SA(0, 1), a2 + hstepA, voffA);
;             PG8_WAIT_V(8); PG8_WAIT_L(0); PG8_BAR; PG8_MMA(0, 0, At, B0); PG8_MMA(0, 1, At, B1); PG8_BAR; PG8_SCHED;
	s_waitcnt lgkmcnt(0)
	v_mfma_f32_16x16x32_bf16 v[60:63], v[144:147], v[176:179], v[60:63]
	v_mfma_f32_16x16x32_bf16 v[56:59], v[152:155], v[176:179], v[56:59]
	v_mfma_f32_16x16x32_bf16 v[52:55], v[144:147], v[184:187], v[52:55]
	v_mfma_f32_16x16x32_bf16 v[44:47], v[152:155], v[184:187], v[44:47]
	v_mfma_f32_16x16x32_bf16 v[36:39], v[144:147], v[206:209], v[36:39]
	v_mfma_f32_16x16x32_bf16 v[28:31], v[152:155], v[206:209], v[28:31]
	v_mfma_f32_16x16x32_bf16 v[20:23], v[144:147], v[214:217], v[20:23]
	v_mfma_f32_16x16x32_bf16 v[12:15], v[152:155], v[214:217], v[12:15]
	v_mfma_f32_16x16x32_bf16 v[60:63], v[148:151], v[180:183], v[60:63]
	v_mfma_f32_16x16x32_bf16 v[56:59], v[156:159], v[180:183], v[56:59]
	v_mfma_f32_16x16x32_bf16 v[52:55], v[148:151], v[188:191], v[52:55]
	v_mfma_f32_16x16x32_bf16 v[44:47], v[156:159], v[188:191], v[44:47]
	v_mfma_f32_16x16x32_bf16 v[36:39], v[148:151], v[210:213], v[36:39]
	v_mfma_f32_16x16x32_bf16 v[28:31], v[156:159], v[210:213], v[28:31]
	v_mfma_f32_16x16x32_bf16 v[20:23], v[148:151], v[218:221], v[20:23]
	v_mfma_f32_16x16x32_bf16 v[12:15], v[156:159], v[218:221], v[12:15]
	v_mfma_f32_16x16x32_bf16 v[48:51], v[160:163], v[176:179], v[48:51]
	v_mfma_f32_16x16x32_bf16 v[40:43], v[168:171], v[176:179], v[40:43]
	v_mfma_f32_16x16x32_bf16 v[32:35], v[160:163], v[184:187], v[32:35]
	v_mfma_f32_16x16x32_bf16 v[24:27], v[168:171], v[184:187], v[24:27]
	v_mfma_f32_16x16x32_bf16 v[16:19], v[160:163], v[206:209], v[16:19]
	v_mfma_f32_16x16x32_bf16 v[8:11], v[168:171], v[206:209], v[8:11]
	v_mfma_f32_16x16x32_bf16 v[4:7], v[160:163], v[214:217], v[4:7]
	v_mfma_f32_16x16x32_bf16 v[0:3], v[168:171], v[214:217], v[0:3]
	v_mfma_f32_16x16x32_bf16 v[48:51], v[164:167], v[180:183], v[48:51]
	v_mfma_f32_16x16x32_bf16 v[40:43], v[172:175], v[180:183], v[40:43]
	v_mfma_f32_16x16x32_bf16 v[32:35], v[164:167], v[188:191], v[32:35]
	v_mfma_f32_16x16x32_bf16 v[24:27], v[172:175], v[188:191], v[24:27]
	v_mfma_f32_16x16x32_bf16 v[16:19], v[164:167], v[210:213], v[16:19]
	v_mfma_f32_16x16x32_bf16 v[8:11], v[172:175], v[210:213], v[8:11]
	v_mfma_f32_16x16x32_bf16 v[4:7], v[164:167], v[218:221], v[4:7]
	v_mfma_f32_16x16x32_bf16 v[0:3], v[172:175], v[218:221], v[0:3]
	s_barrier
	s_setprio 0
	s_add_i32 s38, 0, 0x18000
	s_add_i32 s39, 0, 0x1c000
	v_add_u32_e32 v156, s38, v141
	v_add_u32_e32 v172, s39, v141
	ds_read_b128 v[144:147], v156
	ds_read_b128 v[148:151], v156 offset:1024
	ds_read_b128 v[152:155], v156 offset:2048
	ds_read_b128 v[156:159], v156 offset:3072
	ds_read_b128 v[160:163], v172
	ds_read_b128 v[164:167], v172 offset:1024
	ds_read_b128 v[168:171], v172 offset:2048
	ds_read_b128 v[172:175], v172 offset:3072
	s_add_u32 s18, s18, 0x80000
	s_addc_u32 s19, s19, 0
	s_mov_b32 m0, s23
	v_lshl_add_u64 v[238:239], s[18:19], 0, v[134:135]
	ds_read_b128 v[176:179], v143 offset:32768
	ds_read_b128 v[180:183], v143 offset:33792
	ds_read_b128 v[184:187], v143 offset:34816
	ds_read_b128 v[188:191], v143 offset:35840
	ds_read_b128 v[206:209], v143 offset:36864
	ds_read_b128 v[210:213], v143 offset:37888
	ds_read_b128 v[214:217], v143 offset:38912
	ds_read_b128 v[218:221], v143 offset:39936
	global_load_lds_dwordx4 v[238:239], off
	v_lshl_add_u64 v[238:239], s[18:19], 0, v[130:131]
	s_mov_b32 m0, s24
	s_nop 0
	global_load_lds_dwordx4 v[238:239], off
	s_waitcnt vmcnt(8)
	s_waitcnt lgkmcnt(0)
	s_setprio 1
	s_barrier
	s_waitcnt lgkmcnt(0)
	v_mfma_f32_16x16x32_bf16 v[124:127], v[144:147], v[176:179], v[124:127]
	v_mfma_f32_16x16x32_bf16 v[120:123], v[152:155], v[176:179], v[120:123]
	v_mfma_f32_16x16x32_bf16 v[116:119], v[144:147], v[184:187], v[116:119]
	v_mfma_f32_16x16x32_bf16 v[108:111], v[152:155], v[184:187], v[108:111]
	v_mfma_f32_16x16x32_bf16 v[100:103], v[144:147], v[206:209], v[100:103]
	v_mfma_f32_16x16x32_bf16 v[92:95], v[152:155], v[206:209], v[92:95]
	v_mfma_f32_16x16x32_bf16 v[84:87], v[144:147], v[214:217], v[84:87]
	v_mfma_f32_16x16x32_bf16 v[76:79], v[152:155], v[214:217], v[76:79]
	v_mfma_f32_16x16x32_bf16 v[124:127], v[148:151], v[180:183], v[124:127]
	v_mfma_f32_16x16x32_bf16 v[120:123], v[156:159], v[180:183], v[120:123]
	v_mfma_f32_16x16x32_bf16 v[116:119], v[148:151], v[188:191], v[116:119]
	v_mfma_f32_16x16x32_bf16 v[108:111], v[156:159], v[188:191], v[108:111]
	v_mfma_f32_16x16x32_bf16 v[100:103], v[148:151], v[210:213], v[100:103]
	v_mfma_f32_16x16x32_bf16 v[92:95], v[156:159], v[210:213], v[92:95]
	v_mfma_f32_16x16x32_bf16 v[84:87], v[148:151], v[218:221], v[84:87]
	v_mfma_f32_16x16x32_bf16 v[76:79], v[156:159], v[218:221], v[76:79]
	v_mfma_f32_16x16x32_bf16 v[112:115], v[160:163], v[176:179], v[112:115]
	v_mfma_f32_16x16x32_bf16 v[104:107], v[168:171], v[176:179], v[104:107]
	v_mfma_f32_16x16x32_bf16 v[96:99], v[160:163], v[184:187], v[96:99]
	v_mfma_f32_16x16x32_bf16 v[88:91], v[168:171], v[184:187], v[88:91]
	v_mfma_f32_16x16x32_bf16 v[80:83], v[160:163], v[206:209], v[80:83]
	v_mfma_f32_16x16x32_bf16 v[72:75], v[168:171], v[206:209], v[72:75]
	v_mfma_f32_16x16x32_bf16 v[68:71], v[160:163], v[214:217], v[68:71]
	v_mfma_f32_16x16x32_bf16 v[64:67], v[168:171], v[214:217], v[64:67]
	v_mfma_f32_16x16x32_bf16 v[112:115], v[164:167], v[180:183], v[112:115]
	v_mfma_f32_16x16x32_bf16 v[104:107], v[172:175], v[180:183], v[104:107]
	v_mfma_f32_16x16x32_bf16 v[96:99], v[164:167], v[188:191], v[96:99]
	v_mfma_f32_16x16x32_bf16 v[88:91], v[172:175], v[188:191], v[88:91]
	v_mfma_f32_16x16x32_bf16 v[80:83], v[164:167], v[210:213], v[80:83]
	v_mfma_f32_16x16x32_bf16 v[72:75], v[172:175], v[210:213], v[72:75]
	v_mfma_f32_16x16x32_bf16 v[68:71], v[164:167], v[218:221], v[68:71]
	v_mfma_f32_16x16x32_bf16 v[64:67], v[172:175], v[218:221], v[64:67]
	s_barrier
; #define PG8_STAGE(bufoff, gbase, voff) do { _Pragma("unroll") for (int _i = 0; _i < 2; ++_i) \
;         __builtin_amdgcn_global_load_lds((const unsigned*)((const char*)(gbase) + (voff)[_i]), (LAS unsigned*)(lds + (bufoff) + ldsw + _i * 8192), 16, 0, 0); } while (0)
; #define PG8_LDA(dst, b, h) do { _Pragma("unroll") for (int m = 0; m < 4; ++m) _Pragma("unroll") for (int k = 0; k < 2; ++k) dst[m][k] = *(const LAS bf16x8*)(lds + PG8_SA(b, h) + aoff + m * 2048 + k * 1024); } while (0)
; #define PG8_MMA(ai, bj, At, Bt) do { __builtin_amdgcn_s_setprio(1); _Pragma("unroll") for (int m = 0; m < 4; ++m) _Pragma("unroll") for (int n = 0; n < 2; ++n) _Pragma("unroll") for (int k = 0; k < 2; ++k) \
;         acc[ai][bj][m][n] = __builtin_amdgcn_mfma_f32_16x16x32_bf16(Bt[n][k], At[m][k], acc[ai][bj][m][n], 0, 0, 0); __builtin_amdgcn_s_setprio(0); } while (0)
; #define PG8_WAIT_V(n) asm volatile("s_waitcnt vmcnt(" #n ")" ::: "memory")
; #define PG8_WAIT_L(n) asm volatile("s_waitcnt lgkmcnt(" #n ")" ::: "memory")
; #define PG8_BAR __builtin_amdgcn_s_barrier()
; #define PG8_SCHED __builtin_amdgcn_sched_barrier(0)
; template <class Epi, bool PERMA = false, bool DUAL = false, bool ALIGN_EPI = true, bool SP2 = true>
; __device__ __forceinline__ void gemm_phase(LAS unsigned char* lds, const Gemm g, const StaticOrder& S, const Epi& E) {
;     ...
;             PG8_LDA(At, 1, 1); PG8_STAGE(PG8_SB(1, 0), b3, voffB); PG8_STAGE(PG8_SB(1, 1), b3 + hstepB, voffB); PG8_STAGE(PG8_SA(1, 0), a3, voffA);
;             PG8_WAIT_V(8); PG8_WAIT_L(0); PG8_BAR; PG8_MMA(1, 0, At, B0); PG8_MMA(1, 1, At, B1); PG8_BAR; PG8_SCHED;
;     ...
;         if constexpr (ALIGN_EPI) { if (wr == 0) PG8_BAR; }
	s_setprio 0
	s_add_i32 s18, s38, s20
	v_lshl_add_u64 v[222:223], v[222:223], 0, s[46:47]
	s_mov_b32 m0, s18
	ds_read_b128 v[176:179], v143 offset:49152
	ds_read_b128 v[180:183], v143 offset:50176
	ds_read_b128 v[184:187], v143 offset:51200
	ds_read_b128 v[188:191], v143 offset:52224
	ds_read_b128 v[206:209], v143 offset:53248
	ds_read_b128 v[210:213], v143 offset:54272
	ds_read_b128 v[214:217], v143 offset:55296
	ds_read_b128 v[218:221], v143 offset:56320
	global_load_lds_dwordx4 v[222:223], off
	s_add_i32 m0, s18, 0x2000
	s_add_u32 s16, s16, 0x80080
	v_lshl_add_u64 v[222:223], v[224:225], 0, s[46:47]
	s_addc_u32 s17, s17, 0
	s_add_i32 s18, s39, s20
	global_load_lds_dwordx4 v[222:223], off
	v_lshl_add_u64 v[222:223], s[16:17], 0, v[132:133]
	s_mov_b32 m0, s18
	s_nop 0
	global_load_lds_dwordx4 v[222:223], off
	v_lshl_add_u64 v[222:223], s[16:17], 0, v[128:129]
	s_add_i32 m0, s18, 0x2000
	s_nop 0
	global_load_lds_dwordx4 v[222:223], off
	v_lshl_add_u64 v[222:223], v[226:227], 0, s[46:47]
	s_mov_b32 m0, s25
	s_nop 0
	global_load_lds_dwordx4 v[222:223], off
	v_lshl_add_u64 v[222:223], v[228:229], 0, s[46:47]
	s_mov_b32 m0, s26
	s_nop 0
	global_load_lds_dwordx4 v[222:223], off
	s_waitcnt vmcnt(8)
	s_waitcnt lgkmcnt(0)
	s_setprio 1
	s_barrier
	s_waitcnt lgkmcnt(0)
	v_mfma_f32_16x16x32_bf16 v[60:63], v[144:147], v[176:179], v[60:63]
	v_mfma_f32_16x16x32_bf16 v[56:59], v[152:155], v[176:179], v[56:59]
	v_mfma_f32_16x16x32_bf16 v[52:55], v[144:147], v[184:187], v[52:55]
	v_mfma_f32_16x16x32_bf16 v[44:47], v[152:155], v[184:187], v[44:47]
	v_mfma_f32_16x16x32_bf16 v[36:39], v[144:147], v[206:209], v[36:39]
	v_mfma_f32_16x16x32_bf16 v[28:31], v[152:155], v[206:209], v[28:31]
	v_mfma_f32_16x16x32_bf16 v[20:23], v[144:147], v[214:217], v[20:23]
	v_mfma_f32_16x16x32_bf16 v[12:15], v[152:155], v[214:217], v[12:15]
	v_mfma_f32_16x16x32_bf16 v[60:63], v[148:151], v[180:183], v[60:63]
	v_mfma_f32_16x16x32_bf16 v[56:59], v[156:159], v[180:183], v[56:59]
	v_mfma_f32_16x16x32_bf16 v[52:55], v[148:151], v[188:191], v[52:55]
	v_mfma_f32_16x16x32_bf16 v[44:47], v[156:159], v[188:191], v[44:47]
	v_mfma_f32_16x16x32_bf16 v[36:39], v[148:151], v[210:213], v[36:39]
	v_mfma_f32_16x16x32_bf16 v[28:31], v[156:159], v[210:213], v[28:31]
	v_mfma_f32_16x16x32_bf16 v[20:23], v[148:151], v[218:221], v[20:23]
	v_mfma_f32_16x16x32_bf16 v[12:15], v[156:159], v[218:221], v[12:15]
	v_mfma_f32_16x16x32_bf16 v[48:51], v[160:163], v[176:179], v[48:51]
	v_mfma_f32_16x16x32_bf16 v[40:43], v[168:171], v[176:179], v[40:43]
	v_mfma_f32_16x16x32_bf16 v[32:35], v[160:163], v[184:187], v[32:35]
	v_mfma_f32_16x16x32_bf16 v[24:27], v[168:171], v[184:187], v[24:27]
	v_mfma_f32_16x16x32_bf16 v[16:19], v[160:163], v[206:209], v[16:19]
	v_mfma_f32_16x16x32_bf16 v[8:11], v[168:171], v[206:209], v[8:11]
	v_mfma_f32_16x16x32_bf16 v[4:7], v[160:163], v[214:217], v[4:7]
	v_mfma_f32_16x16x32_bf16 v[0:3], v[168:171], v[214:217], v[0:3]
	v_mfma_f32_16x16x32_bf16 v[48:51], v[164:167], v[180:183], v[48:51]
	v_mfma_f32_16x16x32_bf16 v[40:43], v[172:175], v[180:183], v[40:43]
	v_mfma_f32_16x16x32_bf16 v[32:35], v[164:167], v[188:191], v[32:35]
	v_mfma_f32_16x16x32_bf16 v[24:27], v[172:175], v[188:191], v[24:27]
	v_mfma_f32_16x16x32_bf16 v[16:19], v[164:167], v[210:213], v[16:19]
	v_mfma_f32_16x16x32_bf16 v[8:11], v[172:175], v[210:213], v[8:11]
	v_mfma_f32_16x16x32_bf16 v[4:7], v[164:167], v[218:221], v[4:7]
	v_mfma_f32_16x16x32_bf16 v[0:3], v[172:175], v[218:221], v[0:3]
	s_barrier
	s_setprio 0
	s_add_i32 s37, s37, 2
	s_add_u32 s14, s14, 0x100
	s_addc_u32 s15, s15, 0
	s_add_u32 s35, s35, 0x100
	s_addc_u32 s36, s36, 0
	s_cmp_gt_u32 s37, 29
	s_cbranch_scc0 .LBB0_130
	s_and_b64 vcc, exec, s[4:5]
	s_cbranch_vccz .LBB0_133
	s_barrier

; #define PG8_STAGE(bufoff, gbase, voff) do { _Pragma("unroll") for (int _i = 0; _i < 2; ++_i) \
;         __builtin_amdgcn_global_load_lds((const unsigned*)((const char*)(gbase) + (voff)[_i]), (LAS unsigned*)(lds + (bufoff) + ldsw + _i * 8192), 16, 0, 0); } while (0)
; #define PG8_LDA(dst, b, h) do { _Pragma("unroll") for (int m = 0; m < 4; ++m) _Pragma("unroll") for (int k = 0; k < 2; ++k) dst[m][k] = *(const LAS bf16x8*)(lds + PG8_SA(b, h) + aoff + m * 2048 + k * 1024); } while (0)
; #define PG8_LDB(dst, b, h) do { _Pragma("unroll") for (int n = 0; n < 2; ++n) _Pragma("unroll") for (int k = 0; k < 2; ++k) dst[n][k] = *(const LAS bf16x8*)(lds + PG8_SB(b, h) + boff + n * 2048 + k * 1024); } while (0)
; #define PG8_MMA(ai, bj, At, Bt) do { __builtin_amdgcn_s_setprio(1); _Pragma("unroll") for (int m = 0; m < 4; ++m) _Pragma("unroll") for (int n = 0; n < 2; ++n) _Pragma("unroll") for (int k = 0; k < 2; ++k) \
;         acc[ai][bj][m][n] = __builtin_amdgcn_mfma_f32_16x16x32_bf16(Bt[n][k], At[m][k], acc[ai][bj][m][n], 0, 0, 0); __builtin_amdgcn_s_setprio(0); } while (0)
; template <class Epi, bool PERMA = false, bool DUAL = false, bool ALIGN_EPI = true, bool SP2 = true>
; __device__ __forceinline__ void gemm_phase(LAS unsigned char* lds, const Gemm g, const StaticOrder& S, const Epi& E) {
;     ...
;         const char* nA = has_next ? (const char*)gA_ + (size_t)nxt.pm * tstepA : cA; const char* nB = has_next ? (const char*)gB_ + (size_t)nxt.pn * tstepB : cB;
;         for (int t = 0; t < nt; t += 2) {
;             const bool last = (t == nt - 2);
;             const char* a1 = cA + (size_t)(t + 1) * kstep;
;             const char* a2 = last ? nA : cA + (size_t)(t + 2) * kstep; const char* b2 = last ? nB : cB + (size_t)(t + 2) * kstep;
;             const char* a3 = a2 + kstep; const char* b3 = b2 + kstep;
;             if constexpr (SP2) {
;             PG8_LDB(B0, 0, 0); PG8_LDB(B1, 0, 1); PG8_SCHED; PG8_LDA(At, 0, 0); PG8_STAGE(PG8_SA(1, 1), a1 + hstepA, voffA);
;             PG8_WAIT_V(8); PG8_WAIT_L(0); PG8_BAR; PG8_MMA(0, 0, At, B0); PG8_MMA(0, 1, At, B1); PG8_BAR; PG8_SCHED;
;             PG8_LDA(At, 0, 1); PG8_STAGE(PG8_SB(0, 0), b2, voffB); PG8_STAGE(PG8_SB(0, 1), b2 + hstepB, voffB); PG8_STAGE(PG8_SA(0, 0), a2, voffA);
;             PG8_WAIT_V(8); PG8_WAIT_L(0); PG8_BAR; PG8_MMA(1, 0, At, B0); PG8_MMA(1, 1, At, B1); PG8_BAR; PG8_SCHED;
.LBB0_329:
	s_add_u32 s0, s12, 0x100
	s_addc_u32 s1, s13, 0
	s_add_i32 s38, 0, 0x10000
	s_cmp_eq_u32 s37, 4
	s_cselect_b32 s17, s9, s1
	s_cselect_b32 s16, s8, s0
	s_cselect_b32 s15, s7, s36
	s_cselect_b32 s14, s34, s35
	s_add_i32 s39, 0, 0x14000
	v_add_u32_e32 v140, s38, v193
	v_add_u32_e32 v156, s39, v193
	ds_read_b128 v[128:131], v140
	ds_read_b128 v[132:135], v140 offset:1024
	ds_read_b128 v[136:139], v140 offset:2048
	ds_read_b128 v[140:143], v140 offset:3072
	ds_read_b128 v[144:147], v156
	ds_read_b128 v[148:151], v156 offset:1024
	ds_read_b128 v[152:155], v156 offset:2048
	ds_read_b128 v[156:159], v156 offset:3072
	v_lshl_add_u64 v[220:221], s[12:13], 0, v[216:217]
	s_add_i32 m0, s19, 0xc000
	ds_read_b128 v[160:163], v238
	ds_read_b128 v[164:167], v238 offset:1024
	ds_read_b128 v[168:171], v238 offset:2048
	ds_read_b128 v[172:175], v238 offset:3072
	ds_read_b128 v[176:179], v238 offset:4096
	ds_read_b128 v[180:183], v238 offset:5120
	ds_read_b128 v[184:187], v238 offset:6144
	ds_read_b128 v[188:191], v238 offset:7168
	global_load_lds_dwordx4 v[220:221], off
	v_lshl_add_u64 v[220:221], s[12:13], 0, v[218:219]
	s_add_i32 m0, s19, 0xe000
	s_nop 0
	global_load_lds_dwordx4 v[220:221], off
	s_waitcnt vmcnt(8)
	s_waitcnt lgkmcnt(0)
	s_setprio 1
	s_barrier
	s_waitcnt lgkmcnt(0)
	v_mfma_f32_16x16x32_bf16 v[124:127], v[128:131], v[160:163], v[124:127]
	v_mfma_f32_16x16x32_bf16 v[120:123], v[136:139], v[160:163], v[120:123]
	v_mfma_f32_16x16x32_bf16 v[108:111], v[128:131], v[168:171], v[108:111]
	v_mfma_f32_16x16x32_bf16 v[104:107], v[136:139], v[168:171], v[104:107]
	v_mfma_f32_16x16x32_bf16 v[92:95], v[128:131], v[176:179], v[92:95]
	v_mfma_f32_16x16x32_bf16 v[88:91], v[136:139], v[176:179], v[88:91]
	v_mfma_f32_16x16x32_bf16 v[76:79], v[128:131], v[184:187], v[76:79]
	v_mfma_f32_16x16x32_bf16 v[72:75], v[136:139], v[184:187], v[72:75]
	v_mfma_f32_16x16x32_bf16 v[124:127], v[132:135], v[164:167], v[124:127]
	v_mfma_f32_16x16x32_bf16 v[120:123], v[140:143], v[164:167], v[120:123]
	v_mfma_f32_16x16x32_bf16 v[108:111], v[132:135], v[172:175], v[108:111]
	v_mfma_f32_16x16x32_bf16 v[104:107], v[140:143], v[172:175], v[104:107]
	v_mfma_f32_16x16x32_bf16 v[92:95], v[132:135], v[180:183], v[92:95]
	v_mfma_f32_16x16x32_bf16 v[88:91], v[140:143], v[180:183], v[88:91]
	v_mfma_f32_16x16x32_bf16 v[76:79], v[132:135], v[188:191], v[76:79]
	v_mfma_f32_16x16x32_bf16 v[72:75], v[140:143], v[188:191], v[72:75]
	v_mfma_f32_16x16x32_bf16 v[116:119], v[144:147], v[160:163], v[116:119]
	v_mfma_f32_16x16x32_bf16 v[112:115], v[152:155], v[160:163], v[112:115]
	v_mfma_f32_16x16x32_bf16 v[100:103], v[144:147], v[168:171], v[100:103]
	v_mfma_f32_16x16x32_bf16 v[96:99], v[152:155], v[168:171], v[96:99]
	v_mfma_f32_16x16x32_bf16 v[84:87], v[144:147], v[176:179], v[84:87]
	v_mfma_f32_16x16x32_bf16 v[80:83], v[152:155], v[176:179], v[80:83]
	v_mfma_f32_16x16x32_bf16 v[68:71], v[144:147], v[184:187], v[68:71]
	v_mfma_f32_16x16x32_bf16 v[64:67], v[152:155], v[184:187], v[64:67]
	v_mfma_f32_16x16x32_bf16 v[116:119], v[148:151], v[164:167], v[116:119]
	v_mfma_f32_16x16x32_bf16 v[112:115], v[156:159], v[164:167], v[112:115]
	v_mfma_f32_16x16x32_bf16 v[100:103], v[148:151], v[172:175], v[100:103]
	v_mfma_f32_16x16x32_bf16 v[96:99], v[156:159], v[172:175], v[96:99]
	v_mfma_f32_16x16x32_bf16 v[84:87], v[148:151], v[180:183], v[84:87]
	v_mfma_f32_16x16x32_bf16 v[80:83], v[156:159], v[180:183], v[80:83]
	v_mfma_f32_16x16x32_bf16 v[68:71], v[148:151], v[188:191], v[68:71]
	v_mfma_f32_16x16x32_bf16 v[64:67], v[156:159], v[188:191], v[64:67]
	s_barrier
	s_setprio 0
	s_add_i32 s12, s38, s18
	v_lshl_add_u64 v[220:221], s[14:15], 0, v[210:211]
	s_mov_b32 m0, s12
	ds_read_b128 v[160:163], v238 offset:16384
	ds_read_b128 v[164:167], v238 offset:17408
	ds_read_b128 v[168:171], v238 offset:18432
	ds_read_b128 v[172:175], v238 offset:19456
	ds_read_b128 v[176:179], v238 offset:20480
	ds_read_b128 v[180:183], v238 offset:21504
	ds_read_b128 v[184:187], v238 offset:22528
	ds_read_b128 v[188:191], v238 offset:23552
	global_load_lds_dwordx4 v[220:221], off
	s_add_i32 m0, s12, 0x2000
	s_add_u32 s12, s14, 0x20000
	v_lshl_add_u64 v[222:223], s[14:15], 0, v[206:207]
	s_addc_u32 s13, s15, 0
	s_add_i32 s38, s39, s18
	global_load_lds_dwordx4 v[222:223], off
	v_lshl_add_u64 v[224:225], s[12:13], 0, v[210:211]
	s_mov_b32 m0, s38
	v_lshl_add_u64 v[226:227], s[16:17], 0, v[208:209]
	global_load_lds_dwordx4 v[224:225], off
	v_lshl_add_u64 v[224:225], s[12:13], 0, v[206:207]
	s_add_i32 m0, s38, 0x2000
	s_nop 0
	global_load_lds_dwordx4 v[224:225], off
	v_lshl_add_u64 v[224:225], s[16:17], 0, v[212:213]
	s_mov_b32 m0, s19
	s_nop 0
	global_load_lds_dwordx4 v[224:225], off
	s_mov_b32 m0, s20
	s_nop 0
	global_load_lds_dwordx4 v[226:227], off
	s_waitcnt vmcnt(8)
	s_waitcnt lgkmcnt(0)
	s_setprio 1
	s_barrier
; #define PG8_STAGE(bufoff, gbase, voff) do { _Pragma("unroll") for (int _i = 0; _i < 2; ++_i) \
;         __builtin_amdgcn_global_load_lds((const unsigned*)((const char*)(gbase) + (voff)[_i]), (LAS unsigned*)(lds + (bufoff) + ldsw + _i * 8192), 16, 0, 0); } while (0)
; #define PG8_LDA(dst, b, h) do { _Pragma("unroll") for (int m = 0; m < 4; ++m) _Pragma("unroll") for (int k = 0; k < 2; ++k) dst[m][k] = *(const LAS bf16x8*)(lds + PG8_SA(b, h) + aoff + m * 2048 + k * 1024); } while (0)
; #define PG8_LDB(dst, b, h) do { _Pragma("unroll") for (int n = 0; n < 2; ++n) _Pragma("unroll") for (int k = 0; k < 2; ++k) dst[n][k] = *(const LAS bf16x8*)(lds + PG8_SB(b, h) + boff + n * 2048 + k * 1024); } while (0)
; #define PG8_MMA(ai, bj, At, Bt) do { __builtin_amdgcn_s_setprio(1); _Pragma("unroll") for (int m = 0; m < 4; ++m) _Pragma("unroll") for (int n = 0; n < 2; ++n) _Pragma("unroll") for (int k = 0; k < 2; ++k) \
;         acc[ai][bj][m][n] = __builtin_amdgcn_mfma_f32_16x16x32_bf16(Bt[n][k], At[m][k], acc[ai][bj][m][n], 0, 0, 0); __builtin_amdgcn_s_setprio(0); } while (0)
; #define PG8_WAIT_V(n) asm volatile("s_waitcnt vmcnt(" #n ")" ::: "memory")
; #define PG8_WAIT_L(n) asm volatile("s_waitcnt lgkmcnt(" #n ")" ::: "memory")
; #define PG8_BAR __builtin_amdgcn_s_barrier()
; #define PG8_SCHED __builtin_amdgcn_sched_barrier(0)
; template <class Epi, bool PERMA = false, bool DUAL = false, bool ALIGN_EPI = true, bool SP2 = true>
; __device__ __forceinline__ void gemm_phase(LAS unsigned char* lds, const Gemm g, const StaticOrder& S, const Epi& E) {
;     ...
;             PG8_WAIT_V(8); PG8_WAIT_L(0); PG8_BAR; PG8_MMA(1, 0, At, B0); PG8_MMA(1, 1, At, B1); PG8_BAR; PG8_SCHED;
;             PG8_LDB(B0, 1, 0); PG8_LDB(B1, 1, 1); PG8_SCHED; PG8_LDA(At, 1, 0); PG8_STAGE(PG8_SA(0, 1), a2 + hstepA, voffA);
;             PG8_WAIT_V(8); PG8_WAIT_L(0); PG8_BAR; PG8_MMA(0, 0, At, B0); PG8_MMA(0, 1, At, B1); PG8_BAR; PG8_SCHED;
	s_waitcnt lgkmcnt(0)
	v_mfma_f32_16x16x32_bf16 v[60:63], v[128:131], v[160:163], v[60:63]
	v_mfma_f32_16x16x32_bf16 v[56:59], v[136:139], v[160:163], v[56:59]
	v_mfma_f32_16x16x32_bf16 v[44:47], v[128:131], v[168:171], v[44:47]
	v_mfma_f32_16x16x32_bf16 v[40:43], v[136:139], v[168:171], v[40:43]
	v_mfma_f32_16x16x32_bf16 v[28:31], v[128:131], v[176:179], v[28:31]
	v_mfma_f32_16x16x32_bf16 v[24:27], v[136:139], v[176:179], v[24:27]
	v_mfma_f32_16x16x32_bf16 v[12:15], v[128:131], v[184:187], v[12:15]
	v_mfma_f32_16x16x32_bf16 v[8:11], v[136:139], v[184:187], v[8:11]
	v_mfma_f32_16x16x32_bf16 v[60:63], v[132:135], v[164:167], v[60:63]
	v_mfma_f32_16x16x32_bf16 v[56:59], v[140:143], v[164:167], v[56:59]
	v_mfma_f32_16x16x32_bf16 v[44:47], v[132:135], v[172:175], v[44:47]
	v_mfma_f32_16x16x32_bf16 v[40:43], v[140:143], v[172:175], v[40:43]
	v_mfma_f32_16x16x32_bf16 v[28:31], v[132:135], v[180:183], v[28:31]
	v_mfma_f32_16x16x32_bf16 v[24:27], v[140:143], v[180:183], v[24:27]
	v_mfma_f32_16x16x32_bf16 v[12:15], v[132:135], v[188:191], v[12:15]
	v_mfma_f32_16x16x32_bf16 v[8:11], v[140:143], v[188:191], v[8:11]
	v_mfma_f32_16x16x32_bf16 v[52:55], v[144:147], v[160:163], v[52:55]
	v_mfma_f32_16x16x32_bf16 v[48:51], v[152:155], v[160:163], v[48:51]
	v_mfma_f32_16x16x32_bf16 v[36:39], v[144:147], v[168:171], v[36:39]
	v_mfma_f32_16x16x32_bf16 v[32:35], v[152:155], v[168:171], v[32:35]
	v_mfma_f32_16x16x32_bf16 v[20:23], v[144:147], v[176:179], v[20:23]
	v_mfma_f32_16x16x32_bf16 v[16:19], v[152:155], v[176:179], v[16:19]
	v_mfma_f32_16x16x32_bf16 v[4:7], v[144:147], v[184:187], v[4:7]
	v_mfma_f32_16x16x32_bf16 v[0:3], v[152:155], v[184:187], v[0:3]
	v_mfma_f32_16x16x32_bf16 v[52:55], v[148:151], v[164:167], v[52:55]
	v_mfma_f32_16x16x32_bf16 v[48:51], v[156:159], v[164:167], v[48:51]
	v_mfma_f32_16x16x32_bf16 v[36:39], v[148:151], v[172:175], v[36:39]
	v_mfma_f32_16x16x32_bf16 v[32:35], v[156:159], v[172:175], v[32:35]
	v_mfma_f32_16x16x32_bf16 v[20:23], v[148:151], v[180:183], v[20:23]
	v_mfma_f32_16x16x32_bf16 v[16:19], v[156:159], v[180:183], v[16:19]
	v_mfma_f32_16x16x32_bf16 v[4:7], v[148:151], v[188:191], v[4:7]
	v_mfma_f32_16x16x32_bf16 v[0:3], v[156:159], v[188:191], v[0:3]
	s_barrier
	s_setprio 0
	s_add_i32 s38, 0, 0x18000
	s_add_i32 s39, 0, 0x1c000
	v_add_u32_e32 v140, s38, v193
	v_add_u32_e32 v156, s39, v193
	ds_read_b128 v[128:131], v140
	ds_read_b128 v[132:135], v140 offset:1024
	ds_read_b128 v[136:139], v140 offset:2048
	ds_read_b128 v[140:143], v140 offset:3072
	ds_read_b128 v[144:147], v156
	ds_read_b128 v[148:151], v156 offset:1024
	ds_read_b128 v[152:155], v156 offset:2048
	ds_read_b128 v[156:159], v156 offset:3072
	s_add_u32 s12, s16, 0x180000
	s_addc_u32 s13, s17, 0
	s_mov_b32 m0, s21
	v_lshl_add_u64 v[228:229], s[12:13], 0, v[212:213]
	ds_read_b128 v[160:163], v238 offset:32768
	ds_read_b128 v[164:167], v238 offset:33792
	ds_read_b128 v[168:171], v238 offset:34816
	ds_read_b128 v[172:175], v238 offset:35840
	ds_read_b128 v[176:179], v238 offset:36864
	ds_read_b128 v[180:183], v238 offset:37888
	ds_read_b128 v[184:187], v238 offset:38912
	ds_read_b128 v[188:191], v238 offset:39936
	global_load_lds_dwordx4 v[228:229], off
	v_lshl_add_u64 v[228:229], s[12:13], 0, v[208:209]
	s_mov_b32 m0, s22
	s_nop 0
	global_load_lds_dwordx4 v[228:229], off
	s_waitcnt vmcnt(8)
	s_waitcnt lgkmcnt(0)
	s_setprio 1
	s_barrier
	s_waitcnt lgkmcnt(0)
	v_mfma_f32_16x16x32_bf16 v[124:127], v[128:131], v[160:163], v[124:127]
	v_mfma_f32_16x16x32_bf16 v[120:123], v[136:139], v[160:163], v[120:123]
	v_mfma_f32_16x16x32_bf16 v[108:111], v[128:131], v[168:171], v[108:111]
	v_mfma_f32_16x16x32_bf16 v[104:107], v[136:139], v[168:171], v[104:107]
	v_mfma_f32_16x16x32_bf16 v[92:95], v[128:131], v[176:179], v[92:95]
	v_mfma_f32_16x16x32_bf16 v[88:91], v[136:139], v[176:179], v[88:91]
	v_mfma_f32_16x16x32_bf16 v[76:79], v[128:131], v[184:187], v[76:79]
	v_mfma_f32_16x16x32_bf16 v[72:75], v[136:139], v[184:187], v[72:75]
	v_mfma_f32_16x16x32_bf16 v[124:127], v[132:135], v[164:167], v[124:127]
	v_mfma_f32_16x16x32_bf16 v[120:123], v[140:143], v[164:167], v[120:123]
	v_mfma_f32_16x16x32_bf16 v[108:111], v[132:135], v[172:175], v[108:111]
	v_mfma_f32_16x16x32_bf16 v[104:107], v[140:143], v[172:175], v[104:107]
	v_mfma_f32_16x16x32_bf16 v[92:95], v[132:135], v[180:183], v[92:95]
	v_mfma_f32_16x16x32_bf16 v[88:91], v[140:143], v[180:183], v[88:91]
	v_mfma_f32_16x16x32_bf16 v[76:79], v[132:135], v[188:191], v[76:79]
	v_mfma_f32_16x16x32_bf16 v[72:75], v[140:143], v[188:191], v[72:75]
	v_mfma_f32_16x16x32_bf16 v[116:119], v[144:147], v[160:163], v[116:119]
	v_mfma_f32_16x16x32_bf16 v[112:115], v[152:155], v[160:163], v[112:115]
	v_mfma_f32_16x16x32_bf16 v[100:103], v[144:147], v[168:171], v[100:103]
	v_mfma_f32_16x16x32_bf16 v[96:99], v[152:155], v[168:171], v[96:99]
	v_mfma_f32_16x16x32_bf16 v[84:87], v[144:147], v[176:179], v[84:87]
	v_mfma_f32_16x16x32_bf16 v[80:83], v[152:155], v[176:179], v[80:83]
	v_mfma_f32_16x16x32_bf16 v[68:71], v[144:147], v[184:187], v[68:71]
	v_mfma_f32_16x16x32_bf16 v[64:67], v[152:155], v[184:187], v[64:67]
	v_mfma_f32_16x16x32_bf16 v[116:119], v[148:151], v[164:167], v[116:119]
	v_mfma_f32_16x16x32_bf16 v[112:115], v[156:159], v[164:167], v[112:115]
	v_mfma_f32_16x16x32_bf16 v[100:103], v[148:151], v[172:175], v[100:103]
	v_mfma_f32_16x16x32_bf16 v[96:99], v[156:159], v[172:175], v[96:99]
	v_mfma_f32_16x16x32_bf16 v[84:87], v[148:151], v[180:183], v[84:87]
	v_mfma_f32_16x16x32_bf16 v[80:83], v[156:159], v[180:183], v[80:83]
	v_mfma_f32_16x16x32_bf16 v[68:71], v[148:151], v[188:191], v[68:71]
	v_mfma_f32_16x16x32_bf16 v[64:67], v[156:159], v[188:191], v[64:67]
	s_barrier
; #define PG8_STAGE(bufoff, gbase, voff) do { _Pragma("unroll") for (int _i = 0; _i < 2; ++_i) \
;         __builtin_amdgcn_global_load_lds((const unsigned*)((const char*)(gbase) + (voff)[_i]), (LAS unsigned*)(lds + (bufoff) + ldsw + _i * 8192), 16, 0, 0); } while (0)
; #define PG8_LDA(dst, b, h) do { _Pragma("unroll") for (int m = 0; m < 4; ++m) _Pragma("unroll") for (int k = 0; k < 2; ++k) dst[m][k] = *(const LAS bf16x8*)(lds + PG8_SA(b, h) + aoff + m * 2048 + k * 1024); } while (0)
; #define PG8_MMA(ai, bj, At, Bt) do { __builtin_amdgcn_s_setprio(1); _Pragma("unroll") for (int m = 0; m < 4; ++m) _Pragma("unroll") for (int n = 0; n < 2; ++n) _Pragma("unroll") for (int k = 0; k < 2; ++k) \
;         acc[ai][bj][m][n] = __builtin_amdgcn_mfma_f32_16x16x32_bf16(Bt[n][k], At[m][k], acc[ai][bj][m][n], 0, 0, 0); __builtin_amdgcn_s_setprio(0); } while (0)
; #define PG8_WAIT_V(n) asm volatile("s_waitcnt vmcnt(" #n ")" ::: "memory")
; #define PG8_WAIT_L(n) asm volatile("s_waitcnt lgkmcnt(" #n ")" ::: "memory")
; #define PG8_BAR __builtin_amdgcn_s_barrier()
; #define PG8_SCHED __builtin_amdgcn_sched_barrier(0)
; template <class Epi, bool PERMA = false, bool DUAL = false, bool ALIGN_EPI = true, bool SP2 = true>
; __device__ __forceinline__ void gemm_phase(LAS unsigned char* lds, const Gemm g, const StaticOrder& S, const Epi& E) {
;     ...
;             PG8_LDA(At, 1, 1); PG8_STAGE(PG8_SB(1, 0), b3, voffB); PG8_STAGE(PG8_SB(1, 1), b3 + hstepB, voffB); PG8_STAGE(PG8_SA(1, 0), a3, voffA);
;             PG8_WAIT_V(8); PG8_WAIT_L(0); PG8_BAR; PG8_MMA(1, 0, At, B0); PG8_MMA(1, 1, At, B1); PG8_BAR; PG8_SCHED;
;     ...
;         if constexpr (ALIGN_EPI) { if (wr == 0) PG8_BAR; }
	s_setprio 0
	s_add_i32 s12, s38, s18
	v_lshl_add_u64 v[220:221], v[220:221], 0, s[46:47]
	s_mov_b32 m0, s12
	ds_read_b128 v[160:163], v238 offset:49152
	ds_read_b128 v[164:167], v238 offset:50176
	ds_read_b128 v[168:171], v238 offset:51200
	ds_read_b128 v[172:175], v238 offset:52224
	ds_read_b128 v[176:179], v238 offset:53248
	ds_read_b128 v[180:183], v238 offset:54272
	ds_read_b128 v[184:187], v238 offset:55296
	ds_read_b128 v[188:191], v238 offset:56320
	global_load_lds_dwordx4 v[220:221], off
	s_add_i32 m0, s12, 0x2000
	s_add_u32 s12, s14, 0x20080
	v_lshl_add_u64 v[220:221], v[222:223], 0, s[46:47]
	s_addc_u32 s13, s15, 0
	s_add_i32 s14, s39, s18
	global_load_lds_dwordx4 v[220:221], off
	v_lshl_add_u64 v[220:221], s[12:13], 0, v[210:211]
	s_mov_b32 m0, s14
	s_nop 0
	global_load_lds_dwordx4 v[220:221], off
	v_lshl_add_u64 v[220:221], s[12:13], 0, v[206:207]
	s_add_i32 m0, s14, 0x2000
	s_nop 0
	global_load_lds_dwordx4 v[220:221], off
	v_lshl_add_u64 v[220:221], v[224:225], 0, s[46:47]
	s_mov_b32 m0, s25
	s_nop 0
	global_load_lds_dwordx4 v[220:221], off
	v_lshl_add_u64 v[220:221], v[226:227], 0, s[46:47]
	s_mov_b32 m0, s26
	s_nop 0
	global_load_lds_dwordx4 v[220:221], off
	s_waitcnt vmcnt(8)
	s_waitcnt lgkmcnt(0)
	s_setprio 1
	s_barrier
	s_waitcnt lgkmcnt(0)
	v_mfma_f32_16x16x32_bf16 v[60:63], v[128:131], v[160:163], v[60:63]
	v_mfma_f32_16x16x32_bf16 v[56:59], v[136:139], v[160:163], v[56:59]
	v_mfma_f32_16x16x32_bf16 v[44:47], v[128:131], v[168:171], v[44:47]
	v_mfma_f32_16x16x32_bf16 v[40:43], v[136:139], v[168:171], v[40:43]
	v_mfma_f32_16x16x32_bf16 v[28:31], v[128:131], v[176:179], v[28:31]
	v_mfma_f32_16x16x32_bf16 v[24:27], v[136:139], v[176:179], v[24:27]
	v_mfma_f32_16x16x32_bf16 v[12:15], v[128:131], v[184:187], v[12:15]
	v_mfma_f32_16x16x32_bf16 v[8:11], v[136:139], v[184:187], v[8:11]
	v_mfma_f32_16x16x32_bf16 v[60:63], v[132:135], v[164:167], v[60:63]
	v_mfma_f32_16x16x32_bf16 v[56:59], v[140:143], v[164:167], v[56:59]
	v_mfma_f32_16x16x32_bf16 v[44:47], v[132:135], v[172:175], v[44:47]
	v_mfma_f32_16x16x32_bf16 v[40:43], v[140:143], v[172:175], v[40:43]
	v_mfma_f32_16x16x32_bf16 v[28:31], v[132:135], v[180:183], v[28:31]
	v_mfma_f32_16x16x32_bf16 v[24:27], v[140:143], v[180:183], v[24:27]
	v_mfma_f32_16x16x32_bf16 v[12:15], v[132:135], v[188:191], v[12:15]
	v_mfma_f32_16x16x32_bf16 v[8:11], v[140:143], v[188:191], v[8:11]
	v_mfma_f32_16x16x32_bf16 v[52:55], v[144:147], v[160:163], v[52:55]
	v_mfma_f32_16x16x32_bf16 v[48:51], v[152:155], v[160:163], v[48:51]
	v_mfma_f32_16x16x32_bf16 v[36:39], v[144:147], v[168:171], v[36:39]
	v_mfma_f32_16x16x32_bf16 v[32:35], v[152:155], v[168:171], v[32:35]
	v_mfma_f32_16x16x32_bf16 v[20:23], v[144:147], v[176:179], v[20:23]
	v_mfma_f32_16x16x32_bf16 v[16:19], v[152:155], v[176:179], v[16:19]
	v_mfma_f32_16x16x32_bf16 v[4:7], v[144:147], v[184:187], v[4:7]
	v_mfma_f32_16x16x32_bf16 v[0:3], v[152:155], v[184:187], v[0:3]
	v_mfma_f32_16x16x32_bf16 v[52:55], v[148:151], v[164:167], v[52:55]
	v_mfma_f32_16x16x32_bf16 v[48:51], v[156:159], v[164:167], v[48:51]
	v_mfma_f32_16x16x32_bf16 v[36:39], v[148:151], v[172:175], v[36:39]
	v_mfma_f32_16x16x32_bf16 v[32:35], v[156:159], v[172:175], v[32:35]
	v_mfma_f32_16x16x32_bf16 v[20:23], v[148:151], v[180:183], v[20:23]
	v_mfma_f32_16x16x32_bf16 v[16:19], v[156:159], v[180:183], v[16:19]
	v_mfma_f32_16x16x32_bf16 v[4:7], v[148:151], v[188:191], v[4:7]
	v_mfma_f32_16x16x32_bf16 v[0:3], v[156:159], v[188:191], v[0:3]
	s_barrier
	s_setprio 0
	s_add_i32 s37, s37, 2
	s_add_u32 s35, s35, 0x100
	s_addc_u32 s36, s36, 0
	s_cmp_gt_u32 s37, 5
	s_mov_b64 s[12:13], s[0:1]
	s_cbranch_scc0 .LBB0_329
	s_and_b64 vcc, exec, s[4:5]
	s_cbranch_vccz .LBB0_332
	s_barrier

; #define PG8_STAGE(bufoff, gbase, voff) do { _Pragma("unroll") for (int _i = 0; _i < 2; ++_i) \
;         __builtin_amdgcn_global_load_lds((const unsigned*)((const char*)(gbase) + (voff)[_i]), (LAS unsigned*)(lds + (bufoff) + ldsw + _i * 8192), 16, 0, 0); } while (0)
; #define PG8_LDA(dst, b, h) do { _Pragma("unroll") for (int m = 0; m < 4; ++m) _Pragma("unroll") for (int k = 0; k < 2; ++k) dst[m][k] = *(const LAS bf16x8*)(lds + PG8_SA(b, h) + aoff + m * 2048 + k * 1024); } while (0)
; #define PG8_LDB(dst, b, h) do { _Pragma("unroll") for (int n = 0; n < 2; ++n) _Pragma("unroll") for (int k = 0; k < 2; ++k) dst[n][k] = *(const LAS bf16x8*)(lds + PG8_SB(b, h) + boff + n * 2048 + k * 1024); } while (0)
; #define PG8_MMA(ai, bj, At, Bt) do { __builtin_amdgcn_s_setprio(1); _Pragma("unroll") for (int m = 0; m < 4; ++m) _Pragma("unroll") for (int n = 0; n < 2; ++n) _Pragma("unroll") for (int k = 0; k < 2; ++k) \
;         acc[ai][bj][m][n] = __builtin_amdgcn_mfma_f32_16x16x32_bf16(Bt[n][k], At[m][k], acc[ai][bj][m][n], 0, 0, 0); __builtin_amdgcn_s_setprio(0); } while (0)
; template <class Epi, bool PERMA = false, bool DUAL = false, bool ALIGN_EPI = true, bool SP2 = true>
; __device__ __forceinline__ void gemm_phase(LAS unsigned char* lds, const Gemm g, const StaticOrder& S, const Epi& E) {
;     ...
;         const char* nA = has_next ? (const char*)gA_ + (size_t)nxt.pm * tstepA : cA; const char* nB = has_next ? (const char*)gB_ + (size_t)nxt.pn * tstepB : cB;
;         for (int t = 0; t < nt; t += 2) {
;             const bool last = (t == nt - 2);
;             const char* a1 = cA + (size_t)(t + 1) * kstep;
;             const char* a2 = last ? nA : cA + (size_t)(t + 2) * kstep; const char* b2 = last ? nB : cB + (size_t)(t + 2) * kstep;
;             const char* a3 = a2 + kstep; const char* b3 = b2 + kstep;
;             if constexpr (SP2) {
;             PG8_LDB(B0, 0, 0); PG8_LDB(B1, 0, 1); PG8_SCHED; PG8_LDA(At, 0, 0); PG8_STAGE(PG8_SA(1, 1), a1 + hstepA, voffA);
;             PG8_WAIT_V(8); PG8_WAIT_L(0); PG8_BAR; PG8_MMA(0, 0, At, B0); PG8_MMA(0, 1, At, B1); PG8_BAR; PG8_SCHED;
;             PG8_LDA(At, 0, 1); PG8_STAGE(PG8_SB(0, 0), b2, voffB); PG8_STAGE(PG8_SB(0, 1), b2 + hstepB, voffB); PG8_STAGE(PG8_SA(0, 0), a2, voffA);
;             PG8_WAIT_V(8); PG8_WAIT_L(0); PG8_BAR; PG8_MMA(1, 0, At, B0); PG8_MMA(1, 1, At, B1); PG8_BAR; PG8_SCHED;
.LBB0_405:
	s_add_u32 s16, s14, 0xfff00080
	s_addc_u32 s17, s15, -1
	s_add_i32 s38, 0, 0x10000
	s_cmp_eq_u32 s37, 28
	s_cselect_b32 s19, s9, s17
	s_cselect_b32 s18, s33, s16
	v_add_u32_e32 v142, s38, v144
	s_cselect_b32 s17, s7, s36
	s_cselect_b32 s16, s34, s35
	s_add_i32 s40, 0, 0x14000
	ds_read_b128 v[146:149], v142
	ds_read_b128 v[150:153], v142 offset:1024
	ds_read_b128 v[154:157], v142 offset:2048
	ds_read_b128 v[158:161], v142 offset:3072
	v_add_u32_e32 v142, s40, v144
	ds_read_b128 v[162:165], v142
	ds_read_b128 v[166:169], v142 offset:1024
	ds_read_b128 v[170:173], v142 offset:2048
	ds_read_b128 v[174:177], v142 offset:3072
	v_lshl_add_u64 v[142:143], s[14:15], 0, v[138:139]
	s_add_i32 m0, s21, 0xc000
	ds_read_b128 v[178:181], v145
	ds_read_b128 v[182:185], v145 offset:1024
	ds_read_b128 v[186:189], v145 offset:2048
	ds_read_b128 v[206:209], v145 offset:3072
	ds_read_b128 v[210:213], v145 offset:4096
	ds_read_b128 v[214:217], v145 offset:5120
	ds_read_b128 v[218:221], v145 offset:6144
	ds_read_b128 v[222:225], v145 offset:7168
	global_load_lds_dwordx4 v[142:143], off
	v_lshl_add_u64 v[142:143], s[14:15], 0, v[140:141]
	s_add_i32 m0, s21, 0xe000
	s_nop 0
	global_load_lds_dwordx4 v[142:143], off
	s_waitcnt vmcnt(8)
	s_waitcnt lgkmcnt(0)
	s_setprio 1
	s_barrier
	s_waitcnt lgkmcnt(0)
	v_mfma_f32_16x16x32_bf16 v[124:127], v[146:149], v[178:181], v[124:127]
	v_mfma_f32_16x16x32_bf16 v[120:123], v[154:157], v[178:181], v[120:123]
	v_mfma_f32_16x16x32_bf16 v[116:119], v[146:149], v[186:189], v[116:119]
	v_mfma_f32_16x16x32_bf16 v[108:111], v[154:157], v[186:189], v[108:111]
	v_mfma_f32_16x16x32_bf16 v[100:103], v[146:149], v[210:213], v[100:103]
	v_mfma_f32_16x16x32_bf16 v[92:95], v[154:157], v[210:213], v[92:95]
	v_mfma_f32_16x16x32_bf16 v[84:87], v[146:149], v[218:221], v[84:87]
	v_mfma_f32_16x16x32_bf16 v[76:79], v[154:157], v[218:221], v[76:79]
	v_mfma_f32_16x16x32_bf16 v[124:127], v[150:153], v[182:185], v[124:127]
	v_mfma_f32_16x16x32_bf16 v[120:123], v[158:161], v[182:185], v[120:123]
	v_mfma_f32_16x16x32_bf16 v[116:119], v[150:153], v[206:209], v[116:119]
	v_mfma_f32_16x16x32_bf16 v[108:111], v[158:161], v[206:209], v[108:111]
	v_mfma_f32_16x16x32_bf16 v[100:103], v[150:153], v[214:217], v[100:103]
	v_mfma_f32_16x16x32_bf16 v[92:95], v[158:161], v[214:217], v[92:95]
	v_mfma_f32_16x16x32_bf16 v[84:87], v[150:153], v[222:225], v[84:87]
	v_mfma_f32_16x16x32_bf16 v[76:79], v[158:161], v[222:225], v[76:79]
	v_mfma_f32_16x16x32_bf16 v[112:115], v[162:165], v[178:181], v[112:115]
	v_mfma_f32_16x16x32_bf16 v[104:107], v[170:173], v[178:181], v[104:107]
	v_mfma_f32_16x16x32_bf16 v[96:99], v[162:165], v[186:189], v[96:99]
	v_mfma_f32_16x16x32_bf16 v[88:91], v[170:173], v[186:189], v[88:91]
	v_mfma_f32_16x16x32_bf16 v[80:83], v[162:165], v[210:213], v[80:83]
	v_mfma_f32_16x16x32_bf16 v[72:75], v[170:173], v[210:213], v[72:75]
	v_mfma_f32_16x16x32_bf16 v[68:71], v[162:165], v[218:221], v[68:71]
	v_mfma_f32_16x16x32_bf16 v[64:67], v[170:173], v[218:221], v[64:67]
	v_mfma_f32_16x16x32_bf16 v[112:115], v[166:169], v[182:185], v[112:115]
	v_mfma_f32_16x16x32_bf16 v[104:107], v[174:177], v[182:185], v[104:107]
	v_mfma_f32_16x16x32_bf16 v[96:99], v[166:169], v[206:209], v[96:99]
	v_mfma_f32_16x16x32_bf16 v[88:91], v[174:177], v[206:209], v[88:91]
	v_mfma_f32_16x16x32_bf16 v[80:83], v[166:169], v[214:217], v[80:83]
	v_mfma_f32_16x16x32_bf16 v[72:75], v[174:177], v[214:217], v[72:75]
	v_mfma_f32_16x16x32_bf16 v[68:71], v[166:169], v[222:225], v[68:71]
	v_mfma_f32_16x16x32_bf16 v[64:67], v[174:177], v[222:225], v[64:67]
	s_barrier
	s_setprio 0
	s_add_i32 s38, s38, s20
	v_lshl_add_u64 v[142:143], s[16:17], 0, v[132:133]
	s_mov_b32 m0, s38
	ds_read_b128 v[178:181], v145 offset:16384
	ds_read_b128 v[182:185], v145 offset:17408
	ds_read_b128 v[186:189], v145 offset:18432
	ds_read_b128 v[206:209], v145 offset:19456
	ds_read_b128 v[210:213], v145 offset:20480
	ds_read_b128 v[214:217], v145 offset:21504
	ds_read_b128 v[218:221], v145 offset:22528
	ds_read_b128 v[222:225], v145 offset:23552
	global_load_lds_dwordx4 v[142:143], off
	s_add_i32 m0, s38, 0x2000
	s_add_u32 s38, s16, 0x80000
	v_lshl_add_u64 v[190:191], s[16:17], 0, v[128:129]
	s_addc_u32 s39, s17, 0
	s_add_i32 s40, s40, s20
	global_load_lds_dwordx4 v[190:191], off
	v_lshl_add_u64 v[226:227], s[38:39], 0, v[132:133]
	s_mov_b32 m0, s40
	v_lshl_add_u64 v[228:229], s[18:19], 0, v[130:131]
	global_load_lds_dwordx4 v[226:227], off
	v_lshl_add_u64 v[226:227], s[38:39], 0, v[128:129]
	s_add_i32 m0, s40, 0x2000
	s_nop 0
	global_load_lds_dwordx4 v[226:227], off
	v_lshl_add_u64 v[226:227], s[18:19], 0, v[134:135]
	s_mov_b32 m0, s21
	s_nop 0
	global_load_lds_dwordx4 v[226:227], off
	s_mov_b32 m0, s22
	s_nop 0
	global_load_lds_dwordx4 v[228:229], off
	s_waitcnt vmcnt(8)
	s_waitcnt lgkmcnt(0)
	s_setprio 1
	s_barrier
; #define PG8_STAGE(bufoff, gbase, voff) do { _Pragma("unroll") for (int _i = 0; _i < 2; ++_i) \
;         __builtin_amdgcn_global_load_lds((const unsigned*)((const char*)(gbase) + (voff)[_i]), (LAS unsigned*)(lds + (bufoff) + ldsw + _i * 8192), 16, 0, 0); } while (0)
; #define PG8_LDA(dst, b, h) do { _Pragma("unroll") for (int m = 0; m < 4; ++m) _Pragma("unroll") for (int k = 0; k < 2; ++k) dst[m][k] = *(const LAS bf16x8*)(lds + PG8_SA(b, h) + aoff + m * 2048 + k * 1024); } while (0)
; #define PG8_LDB(dst, b, h) do { _Pragma("unroll") for (int n = 0; n < 2; ++n) _Pragma("unroll") for (int k = 0; k < 2; ++k) dst[n][k] = *(const LAS bf16x8*)(lds + PG8_SB(b, h) + boff + n * 2048 + k * 1024); } while (0)
; #define PG8_MMA(ai, bj, At, Bt) do { __builtin_amdgcn_s_setprio(1); _Pragma("unroll") for (int m = 0; m < 4; ++m) _Pragma("unroll") for (int n = 0; n < 2; ++n) _Pragma("unroll") for (int k = 0; k < 2; ++k) \
;         acc[ai][bj][m][n] = __builtin_amdgcn_mfma_f32_16x16x32_bf16(Bt[n][k], At[m][k], acc[ai][bj][m][n], 0, 0, 0); __builtin_amdgcn_s_setprio(0); } while (0)
; #define PG8_WAIT_V(n) asm volatile("s_waitcnt vmcnt(" #n ")" ::: "memory")
; #define PG8_WAIT_L(n) asm volatile("s_waitcnt lgkmcnt(" #n ")" ::: "memory")
; #define PG8_BAR __builtin_amdgcn_s_barrier()
; #define PG8_SCHED __builtin_amdgcn_sched_barrier(0)
; template <class Epi, bool PERMA = false, bool DUAL = false, bool ALIGN_EPI = true, bool SP2 = true>
; __device__ __forceinline__ void gemm_phase(LAS unsigned char* lds, const Gemm g, const StaticOrder& S, const Epi& E) {
;     ...
;             PG8_WAIT_V(8); PG8_WAIT_L(0); PG8_BAR; PG8_MMA(1, 0, At, B0); PG8_MMA(1, 1, At, B1); PG8_BAR; PG8_SCHED;
;             PG8_LDB(B0, 1, 0); PG8_LDB(B1, 1, 1); PG8_SCHED; PG8_LDA(At, 1, 0); PG8_STAGE(PG8_SA(0, 1), a2 + hstepA, voffA);
;             PG8_WAIT_V(8); PG8_WAIT_L(0); PG8_BAR; PG8_MMA(0, 0, At, B0); PG8_MMA(0, 1, At, B1); PG8_BAR; PG8_SCHED;
	s_waitcnt lgkmcnt(0)
	v_mfma_f32_16x16x32_bf16 v[60:63], v[146:149], v[178:181], v[60:63]
	v_mfma_f32_16x16x32_bf16 v[56:59], v[154:157], v[178:181], v[56:59]
	v_mfma_f32_16x16x32_bf16 v[52:55], v[146:149], v[186:189], v[52:55]
	v_mfma_f32_16x16x32_bf16 v[44:47], v[154:157], v[186:189], v[44:47]
	v_mfma_f32_16x16x32_bf16 v[36:39], v[146:149], v[210:213], v[36:39]
	v_mfma_f32_16x16x32_bf16 v[28:31], v[154:157], v[210:213], v[28:31]
	v_mfma_f32_16x16x32_bf16 v[20:23], v[146:149], v[218:221], v[20:23]
	v_mfma_f32_16x16x32_bf16 v[12:15], v[154:157], v[218:221], v[12:15]
	v_mfma_f32_16x16x32_bf16 v[60:63], v[150:153], v[182:185], v[60:63]
	v_mfma_f32_16x16x32_bf16 v[56:59], v[158:161], v[182:185], v[56:59]
	v_mfma_f32_16x16x32_bf16 v[52:55], v[150:153], v[206:209], v[52:55]
	v_mfma_f32_16x16x32_bf16 v[44:47], v[158:161], v[206:209], v[44:47]
	v_mfma_f32_16x16x32_bf16 v[36:39], v[150:153], v[214:217], v[36:39]
	v_mfma_f32_16x16x32_bf16 v[28:31], v[158:161], v[214:217], v[28:31]
	v_mfma_f32_16x16x32_bf16 v[20:23], v[150:153], v[222:225], v[20:23]
	v_mfma_f32_16x16x32_bf16 v[12:15], v[158:161], v[222:225], v[12:15]
	v_mfma_f32_16x16x32_bf16 v[48:51], v[162:165], v[178:181], v[48:51]
	v_mfma_f32_16x16x32_bf16 v[40:43], v[170:173], v[178:181], v[40:43]
	v_mfma_f32_16x16x32_bf16 v[32:35], v[162:165], v[186:189], v[32:35]
	v_mfma_f32_16x16x32_bf16 v[24:27], v[170:173], v[186:189], v[24:27]
	v_mfma_f32_16x16x32_bf16 v[16:19], v[162:165], v[210:213], v[16:19]
	v_mfma_f32_16x16x32_bf16 v[8:11], v[170:173], v[210:213], v[8:11]
	v_mfma_f32_16x16x32_bf16 v[4:7], v[162:165], v[218:221], v[4:7]
	v_mfma_f32_16x16x32_bf16 v[0:3], v[170:173], v[218:221], v[0:3]
	v_mfma_f32_16x16x32_bf16 v[48:51], v[166:169], v[182:185], v[48:51]
	v_mfma_f32_16x16x32_bf16 v[40:43], v[174:177], v[182:185], v[40:43]
	v_mfma_f32_16x16x32_bf16 v[32:35], v[166:169], v[206:209], v[32:35]
	v_mfma_f32_16x16x32_bf16 v[24:27], v[174:177], v[206:209], v[24:27]
	v_mfma_f32_16x16x32_bf16 v[16:19], v[166:169], v[214:217], v[16:19]
	v_mfma_f32_16x16x32_bf16 v[8:11], v[174:177], v[214:217], v[8:11]
	v_mfma_f32_16x16x32_bf16 v[4:7], v[166:169], v[222:225], v[4:7]
	v_mfma_f32_16x16x32_bf16 v[0:3], v[174:177], v[222:225], v[0:3]
	s_barrier
	s_setprio 0
	s_add_i32 s38, 0, 0x18000
	s_add_i32 s39, 0, 0x1c000
	v_add_u32_e32 v158, s38, v144
	v_add_u32_e32 v174, s39, v144
	ds_read_b128 v[146:149], v158
	ds_read_b128 v[150:153], v158 offset:1024
	ds_read_b128 v[154:157], v158 offset:2048
	ds_read_b128 v[158:161], v158 offset:3072
	ds_read_b128 v[162:165], v174
	ds_read_b128 v[166:169], v174 offset:1024
	ds_read_b128 v[170:173], v174 offset:2048
	ds_read_b128 v[174:177], v174 offset:3072
	s_add_u32 s18, s18, 0x100000
	s_addc_u32 s19, s19, 0
	s_mov_b32 m0, s23
	v_lshl_add_u64 v[238:239], s[18:19], 0, v[134:135]
	ds_read_b128 v[178:181], v145 offset:32768
	ds_read_b128 v[182:185], v145 offset:33792
	ds_read_b128 v[186:189], v145 offset:34816
	ds_read_b128 v[206:209], v145 offset:35840
	ds_read_b128 v[210:213], v145 offset:36864
	ds_read_b128 v[214:217], v145 offset:37888
	ds_read_b128 v[218:221], v145 offset:38912
	ds_read_b128 v[222:225], v145 offset:39936
	global_load_lds_dwordx4 v[238:239], off
	v_lshl_add_u64 v[238:239], s[18:19], 0, v[130:131]
	s_mov_b32 m0, s24
	s_nop 0
	global_load_lds_dwordx4 v[238:239], off
	s_waitcnt vmcnt(8)
	s_waitcnt lgkmcnt(0)
	s_setprio 1
	s_barrier
	s_waitcnt lgkmcnt(0)
	v_mfma_f32_16x16x32_bf16 v[124:127], v[146:149], v[178:181], v[124:127]
	v_mfma_f32_16x16x32_bf16 v[120:123], v[154:157], v[178:181], v[120:123]
	v_mfma_f32_16x16x32_bf16 v[116:119], v[146:149], v[186:189], v[116:119]
	v_mfma_f32_16x16x32_bf16 v[108:111], v[154:157], v[186:189], v[108:111]
	v_mfma_f32_16x16x32_bf16 v[100:103], v[146:149], v[210:213], v[100:103]
	v_mfma_f32_16x16x32_bf16 v[92:95], v[154:157], v[210:213], v[92:95]
	v_mfma_f32_16x16x32_bf16 v[84:87], v[146:149], v[218:221], v[84:87]
	v_mfma_f32_16x16x32_bf16 v[76:79], v[154:157], v[218:221], v[76:79]
	v_mfma_f32_16x16x32_bf16 v[124:127], v[150:153], v[182:185], v[124:127]
	v_mfma_f32_16x16x32_bf16 v[120:123], v[158:161], v[182:185], v[120:123]
	v_mfma_f32_16x16x32_bf16 v[116:119], v[150:153], v[206:209], v[116:119]
	v_mfma_f32_16x16x32_bf16 v[108:111], v[158:161], v[206:209], v[108:111]
	v_mfma_f32_16x16x32_bf16 v[100:103], v[150:153], v[214:217], v[100:103]
	v_mfma_f32_16x16x32_bf16 v[92:95], v[158:161], v[214:217], v[92:95]
	v_mfma_f32_16x16x32_bf16 v[84:87], v[150:153], v[222:225], v[84:87]
	v_mfma_f32_16x16x32_bf16 v[76:79], v[158:161], v[222:225], v[76:79]
	v_mfma_f32_16x16x32_bf16 v[112:115], v[162:165], v[178:181], v[112:115]
	v_mfma_f32_16x16x32_bf16 v[104:107], v[170:173], v[178:181], v[104:107]
	v_mfma_f32_16x16x32_bf16 v[96:99], v[162:165], v[186:189], v[96:99]
	v_mfma_f32_16x16x32_bf16 v[88:91], v[170:173], v[186:189], v[88:91]
	v_mfma_f32_16x16x32_bf16 v[80:83], v[162:165], v[210:213], v[80:83]
	v_mfma_f32_16x16x32_bf16 v[72:75], v[170:173], v[210:213], v[72:75]
	v_mfma_f32_16x16x32_bf16 v[68:71], v[162:165], v[218:221], v[68:71]
	v_mfma_f32_16x16x32_bf16 v[64:67], v[170:173], v[218:221], v[64:67]
	v_mfma_f32_16x16x32_bf16 v[112:115], v[166:169], v[182:185], v[112:115]
	v_mfma_f32_16x16x32_bf16 v[104:107], v[174:177], v[182:185], v[104:107]
	v_mfma_f32_16x16x32_bf16 v[96:99], v[166:169], v[206:209], v[96:99]
	v_mfma_f32_16x16x32_bf16 v[88:91], v[174:177], v[206:209], v[88:91]
	v_mfma_f32_16x16x32_bf16 v[80:83], v[166:169], v[214:217], v[80:83]
	v_mfma_f32_16x16x32_bf16 v[72:75], v[174:177], v[214:217], v[72:75]
	v_mfma_f32_16x16x32_bf16 v[68:71], v[166:169], v[222:225], v[68:71]
	v_mfma_f32_16x16x32_bf16 v[64:67], v[174:177], v[222:225], v[64:67]
	s_barrier
; #define PG8_STAGE(bufoff, gbase, voff) do { _Pragma("unroll") for (int _i = 0; _i < 2; ++_i) \
;         __builtin_amdgcn_global_load_lds((const unsigned*)((const char*)(gbase) + (voff)[_i]), (LAS unsigned*)(lds + (bufoff) + ldsw + _i * 8192), 16, 0, 0); } while (0)
; #define PG8_LDA(dst, b, h) do { _Pragma("unroll") for (int m = 0; m < 4; ++m) _Pragma("unroll") for (int k = 0; k < 2; ++k) dst[m][k] = *(const LAS bf16x8*)(lds + PG8_SA(b, h) + aoff + m * 2048 + k * 1024); } while (0)
; #define PG8_MMA(ai, bj, At, Bt) do { __builtin_amdgcn_s_setprio(1); _Pragma("unroll") for (int m = 0; m < 4; ++m) _Pragma("unroll") for (int n = 0; n < 2; ++n) _Pragma("unroll") for (int k = 0; k < 2; ++k) \
;         acc[ai][bj][m][n] = __builtin_amdgcn_mfma_f32_16x16x32_bf16(Bt[n][k], At[m][k], acc[ai][bj][m][n], 0, 0, 0); __builtin_amdgcn_s_setprio(0); } while (0)
; #define PG8_WAIT_V(n) asm volatile("s_waitcnt vmcnt(" #n ")" ::: "memory")
; #define PG8_WAIT_L(n) asm volatile("s_waitcnt lgkmcnt(" #n ")" ::: "memory")
; #define PG8_BAR __builtin_amdgcn_s_barrier()
; #define PG8_SCHED __builtin_amdgcn_sched_barrier(0)
; template <class Epi, bool PERMA = false, bool DUAL = false, bool ALIGN_EPI = true, bool SP2 = true>
; __device__ __forceinline__ void gemm_phase(LAS unsigned char* lds, const Gemm g, const StaticOrder& S, const Epi& E) {
;     ...
;             PG8_LDA(At, 1, 1); PG8_STAGE(PG8_SB(1, 0), b3, voffB); PG8_STAGE(PG8_SB(1, 1), b3 + hstepB, voffB); PG8_STAGE(PG8_SA(1, 0), a3, voffA);
;             PG8_WAIT_V(8); PG8_WAIT_L(0); PG8_BAR; PG8_MMA(1, 0, At, B0); PG8_MMA(1, 1, At, B1); PG8_BAR; PG8_SCHED;
;     ...
;         if constexpr (ALIGN_EPI) { if (wr == 0) PG8_BAR; }
	s_setprio 0
	s_add_i32 s18, s38, s20
	v_lshl_add_u64 v[142:143], v[142:143], 0, s[46:47]
	s_mov_b32 m0, s18
	ds_read_b128 v[178:181], v145 offset:49152
	ds_read_b128 v[182:185], v145 offset:50176
	ds_read_b128 v[186:189], v145 offset:51200
	ds_read_b128 v[206:209], v145 offset:52224
	ds_read_b128 v[210:213], v145 offset:53248
	ds_read_b128 v[214:217], v145 offset:54272
	ds_read_b128 v[218:221], v145 offset:55296
	ds_read_b128 v[222:225], v145 offset:56320
	global_load_lds_dwordx4 v[142:143], off
	s_add_i32 m0, s18, 0x2000
	s_add_u32 s16, s16, 0x80080
	v_lshl_add_u64 v[142:143], v[190:191], 0, s[46:47]
	s_addc_u32 s17, s17, 0
	s_add_i32 s18, s39, s20
	global_load_lds_dwordx4 v[142:143], off
	v_lshl_add_u64 v[142:143], s[16:17], 0, v[132:133]
	s_mov_b32 m0, s18
	s_nop 0
	global_load_lds_dwordx4 v[142:143], off
	v_lshl_add_u64 v[142:143], s[16:17], 0, v[128:129]
	s_add_i32 m0, s18, 0x2000
	s_nop 0
	global_load_lds_dwordx4 v[142:143], off
	v_lshl_add_u64 v[142:143], v[226:227], 0, s[46:47]
	s_mov_b32 m0, s27
	s_nop 0
	global_load_lds_dwordx4 v[142:143], off
	v_lshl_add_u64 v[142:143], v[228:229], 0, s[46:47]
	s_mov_b32 m0, s28
	s_nop 0
	global_load_lds_dwordx4 v[142:143], off
	s_waitcnt vmcnt(8)
	s_waitcnt lgkmcnt(0)
	s_setprio 1
	s_barrier
	s_waitcnt lgkmcnt(0)
	v_mfma_f32_16x16x32_bf16 v[60:63], v[146:149], v[178:181], v[60:63]
	v_mfma_f32_16x16x32_bf16 v[56:59], v[154:157], v[178:181], v[56:59]
	v_mfma_f32_16x16x32_bf16 v[52:55], v[146:149], v[186:189], v[52:55]
	v_mfma_f32_16x16x32_bf16 v[44:47], v[154:157], v[186:189], v[44:47]
	v_mfma_f32_16x16x32_bf16 v[36:39], v[146:149], v[210:213], v[36:39]
	v_mfma_f32_16x16x32_bf16 v[28:31], v[154:157], v[210:213], v[28:31]
	v_mfma_f32_16x16x32_bf16 v[20:23], v[146:149], v[218:221], v[20:23]
	v_mfma_f32_16x16x32_bf16 v[12:15], v[154:157], v[218:221], v[12:15]
	v_mfma_f32_16x16x32_bf16 v[60:63], v[150:153], v[182:185], v[60:63]
	v_mfma_f32_16x16x32_bf16 v[56:59], v[158:161], v[182:185], v[56:59]
	v_mfma_f32_16x16x32_bf16 v[52:55], v[150:153], v[206:209], v[52:55]
	v_mfma_f32_16x16x32_bf16 v[44:47], v[158:161], v[206:209], v[44:47]
	v_mfma_f32_16x16x32_bf16 v[36:39], v[150:153], v[214:217], v[36:39]
	v_mfma_f32_16x16x32_bf16 v[28:31], v[158:161], v[214:217], v[28:31]
	v_mfma_f32_16x16x32_bf16 v[20:23], v[150:153], v[222:225], v[20:23]
	v_mfma_f32_16x16x32_bf16 v[12:15], v[158:161], v[222:225], v[12:15]
	v_mfma_f32_16x16x32_bf16 v[48:51], v[162:165], v[178:181], v[48:51]
	v_mfma_f32_16x16x32_bf16 v[40:43], v[170:173], v[178:181], v[40:43]
	v_mfma_f32_16x16x32_bf16 v[32:35], v[162:165], v[186:189], v[32:35]
	v_mfma_f32_16x16x32_bf16 v[24:27], v[170:173], v[186:189], v[24:27]
	v_mfma_f32_16x16x32_bf16 v[16:19], v[162:165], v[210:213], v[16:19]
	v_mfma_f32_16x16x32_bf16 v[8:11], v[170:173], v[210:213], v[8:11]
	v_mfma_f32_16x16x32_bf16 v[4:7], v[162:165], v[218:221], v[4:7]
	v_mfma_f32_16x16x32_bf16 v[0:3], v[170:173], v[218:221], v[0:3]
	v_mfma_f32_16x16x32_bf16 v[48:51], v[166:169], v[182:185], v[48:51]
	v_mfma_f32_16x16x32_bf16 v[40:43], v[174:177], v[182:185], v[40:43]
	v_mfma_f32_16x16x32_bf16 v[32:35], v[166:169], v[206:209], v[32:35]
	v_mfma_f32_16x16x32_bf16 v[24:27], v[174:177], v[206:209], v[24:27]
	v_mfma_f32_16x16x32_bf16 v[16:19], v[166:169], v[214:217], v[16:19]
	v_mfma_f32_16x16x32_bf16 v[8:11], v[174:177], v[214:217], v[8:11]
	v_mfma_f32_16x16x32_bf16 v[4:7], v[166:169], v[222:225], v[4:7]
	v_mfma_f32_16x16x32_bf16 v[0:3], v[174:177], v[222:225], v[0:3]
	s_barrier
	s_setprio 0
	s_add_i32 s37, s37, 2
	s_add_u32 s14, s14, 0x100
	s_addc_u32 s15, s15, 0
	s_add_u32 s35, s35, 0x100
	s_addc_u32 s36, s36, 0
	s_cmp_gt_u32 s37, 29
	s_cbranch_scc0 .LBB0_405
	s_and_b64 vcc, exec, s[4:5]
	s_cbranch_vccz .LBB0_408
	s_barrier

; #define PG8_STAGE(bufoff, gbase, voff) do { _Pragma("unroll") for (int _i = 0; _i < 2; ++_i) \
;         __builtin_amdgcn_global_load_lds((const unsigned*)((const char*)(gbase) + (voff)[_i]), (LAS unsigned*)(lds + (bufoff) + ldsw + _i * 8192), 16, 0, 0); } while (0)
; #define PG8_LDA(dst, b, h) do { _Pragma("unroll") for (int m = 0; m < 4; ++m) _Pragma("unroll") for (int k = 0; k < 2; ++k) dst[m][k] = *(const LAS bf16x8*)(lds + PG8_SA(b, h) + aoff + m * 2048 + k * 1024); } while (0)
; #define PG8_LDB(dst, b, h) do { _Pragma("unroll") for (int n = 0; n < 2; ++n) _Pragma("unroll") for (int k = 0; k < 2; ++k) dst[n][k] = *(const LAS bf16x8*)(lds + PG8_SB(b, h) + boff + n * 2048 + k * 1024); } while (0)
; #define PG8_MMA(ai, bj, At, Bt) do { __builtin_amdgcn_s_setprio(1); _Pragma("unroll") for (int m = 0; m < 4; ++m) _Pragma("unroll") for (int n = 0; n < 2; ++n) _Pragma("unroll") for (int k = 0; k < 2; ++k) \
;         acc[ai][bj][m][n] = __builtin_amdgcn_mfma_f32_16x16x32_bf16(Bt[n][k], At[m][k], acc[ai][bj][m][n], 0, 0, 0); __builtin_amdgcn_s_setprio(0); } while (0)
; template <class Epi, bool PERMA = false, bool DUAL = false, bool ALIGN_EPI = true, bool SP2 = true>
; __device__ __forceinline__ void gemm_phase(LAS unsigned char* lds, const Gemm g, const StaticOrder& S, const Epi& E) {
;     ...
;         const char* nA = has_next ? (const char*)gA_ + (size_t)nxt.pm * tstepA : cA; const char* nB = has_next ? (const char*)gB_ + (size_t)nxt.pn * tstepB : cB;
;         for (int t = 0; t < nt; t += 2) {
;             const bool last = (t == nt - 2);
;             const char* a1 = cA + (size_t)(t + 1) * kstep;
;             const char* a2 = last ? nA : cA + (size_t)(t + 2) * kstep; const char* b2 = last ? nB : cB + (size_t)(t + 2) * kstep;
;             const char* a3 = a2 + kstep; const char* b3 = b2 + kstep;
;             if constexpr (SP2) {
;             PG8_LDB(B0, 0, 0); PG8_LDB(B1, 0, 1); PG8_SCHED; PG8_LDA(At, 0, 0); PG8_STAGE(PG8_SA(1, 1), a1 + hstepA, voffA);
;             PG8_WAIT_V(8); PG8_WAIT_L(0); PG8_BAR; PG8_MMA(0, 0, At, B0); PG8_MMA(0, 1, At, B1); PG8_BAR; PG8_SCHED;
;             PG8_LDA(At, 0, 1); PG8_STAGE(PG8_SB(0, 0), b2, voffB); PG8_STAGE(PG8_SB(0, 1), b2 + hstepB, voffB); PG8_STAGE(PG8_SA(0, 0), a2, voffA);
;             PG8_WAIT_V(8); PG8_WAIT_L(0); PG8_BAR; PG8_MMA(1, 0, At, B0); PG8_MMA(1, 1, At, B1); PG8_BAR; PG8_SCHED;
.LBB0_528:
	s_add_u32 s22, s20, 0x100
	s_addc_u32 s23, s21, 0
	s_add_i32 s52, 0, 0x10000
	s_cmp_eq_u32 s51, 28
	s_cselect_b32 s27, s15, s23
	s_cselect_b32 s26, s39, s22
	s_cselect_b32 s25, s13, s50
	s_cselect_b32 s24, s48, s49
	s_add_i32 s53, 0, 0x14000
	v_add_u32_e32 v108, s52, v193
	v_add_u32_e32 v124, s53, v193
	ds_read_b128 v[96:99], v108
	ds_read_b128 v[100:103], v108 offset:1024
	ds_read_b128 v[104:107], v108 offset:2048
	ds_read_b128 v[108:111], v108 offset:3072
	ds_read_b128 v[112:115], v124
	ds_read_b128 v[116:119], v124 offset:1024
	ds_read_b128 v[120:123], v124 offset:2048
	ds_read_b128 v[124:127], v124 offset:3072
	v_lshl_add_u64 v[220:221], s[20:21], 0, v[216:217]
	s_add_i32 m0, s29, 0xc000
	ds_read_b128 v[128:131], v224
	ds_read_b128 v[132:135], v224 offset:1024
	ds_read_b128 v[136:139], v224 offset:2048
	ds_read_b128 v[144:147], v224 offset:3072
	ds_read_b128 v[152:155], v224 offset:4096
	ds_read_b128 v[160:163], v224 offset:5120
	ds_read_b128 v[168:171], v224 offset:6144
	ds_read_b128 v[188:191], v224 offset:7168
	global_load_lds_dwordx4 v[220:221], off
	v_lshl_add_u64 v[220:221], s[20:21], 0, v[218:219]
	s_add_i32 m0, s29, 0xe000
	s_nop 0
	global_load_lds_dwordx4 v[220:221], off
	s_waitcnt vmcnt(8)
	s_waitcnt lgkmcnt(0)
	s_setprio 1
	s_barrier
	s_waitcnt lgkmcnt(0)
	v_mfma_f32_16x16x32_bf16 v[184:187], v[96:99], v[128:131], v[184:187]
	v_mfma_f32_16x16x32_bf16 v[92:95], v[104:107], v[128:131], v[92:95]
	v_mfma_f32_16x16x32_bf16 v[180:183], v[96:99], v[136:139], v[180:183]
	v_mfma_f32_16x16x32_bf16 v[88:91], v[104:107], v[136:139], v[88:91]
	v_mfma_f32_16x16x32_bf16 v[176:179], v[96:99], v[152:155], v[176:179]
	v_mfma_f32_16x16x32_bf16 v[84:87], v[104:107], v[152:155], v[84:87]
	v_mfma_f32_16x16x32_bf16 v[172:175], v[96:99], v[168:171], v[172:175]
	v_mfma_f32_16x16x32_bf16 v[80:83], v[104:107], v[168:171], v[80:83]
	v_mfma_f32_16x16x32_bf16 v[184:187], v[100:103], v[132:135], v[184:187]
	v_mfma_f32_16x16x32_bf16 v[92:95], v[108:111], v[132:135], v[92:95]
	v_mfma_f32_16x16x32_bf16 v[180:183], v[100:103], v[144:147], v[180:183]
	v_mfma_f32_16x16x32_bf16 v[88:91], v[108:111], v[144:147], v[88:91]
	v_mfma_f32_16x16x32_bf16 v[176:179], v[100:103], v[160:163], v[176:179]
	v_mfma_f32_16x16x32_bf16 v[84:87], v[108:111], v[160:163], v[84:87]
	v_mfma_f32_16x16x32_bf16 v[172:175], v[100:103], v[188:191], v[172:175]
	v_mfma_f32_16x16x32_bf16 v[80:83], v[108:111], v[188:191], v[80:83]
	v_mfma_f32_16x16x32_bf16 v[164:167], v[112:115], v[128:131], v[164:167]
	v_mfma_f32_16x16x32_bf16 v[76:79], v[120:123], v[128:131], v[76:79]
	v_mfma_f32_16x16x32_bf16 v[72:75], v[120:123], v[136:139], v[72:75]
	v_mfma_f32_16x16x32_bf16 v[68:71], v[120:123], v[152:155], v[68:71]
	v_mfma_f32_16x16x32_bf16 v[64:67], v[120:123], v[168:171], v[64:67]
	v_mfma_f32_16x16x32_bf16 v[164:167], v[116:119], v[132:135], v[164:167]
	v_mfma_f32_16x16x32_bf16 v[76:79], v[124:127], v[132:135], v[76:79]
	v_mfma_f32_16x16x32_bf16 v[128:131], v[112:115], v[136:139], v[156:159]
	v_mfma_f32_16x16x32_bf16 v[72:75], v[124:127], v[144:147], v[72:75]
	v_mfma_f32_16x16x32_bf16 v[132:135], v[112:115], v[152:155], v[148:151]
	v_mfma_f32_16x16x32_bf16 v[68:71], v[124:127], v[160:163], v[68:71]
	v_mfma_f32_16x16x32_bf16 v[136:139], v[112:115], v[168:171], v[140:143]
	v_mfma_f32_16x16x32_bf16 v[64:67], v[124:127], v[188:191], v[64:67]
	v_mfma_f32_16x16x32_bf16 v[128:131], v[116:119], v[144:147], v[128:131]
	v_mfma_f32_16x16x32_bf16 v[132:135], v[116:119], v[160:163], v[132:135]
	v_mfma_f32_16x16x32_bf16 v[136:139], v[116:119], v[188:191], v[136:139]
	s_barrier
	s_setprio 0
	s_add_i32 s20, s52, s28
	v_lshl_add_u64 v[220:221], s[24:25], 0, v[210:211]
	s_mov_b32 m0, s20
	ds_read_b128 v[140:143], v224 offset:16384
	ds_read_b128 v[144:147], v224 offset:17408
	ds_read_b128 v[148:151], v224 offset:18432
	ds_read_b128 v[152:155], v224 offset:19456
	ds_read_b128 v[156:159], v224 offset:20480
	ds_read_b128 v[160:163], v224 offset:21504
	ds_read_b128 v[168:171], v224 offset:22528
	ds_read_b128 v[188:191], v224 offset:23552
	global_load_lds_dwordx4 v[220:221], off
	s_add_i32 m0, s20, 0x2000
	s_add_u32 s20, s24, 0x80000
	v_lshl_add_u64 v[238:239], s[24:25], 0, v[206:207]
	s_addc_u32 s21, s25, 0
	s_add_i32 s52, s53, s28
	global_load_lds_dwordx4 v[238:239], off
	v_lshl_add_u64 v[226:227], s[20:21], 0, v[210:211]
	s_mov_b32 m0, s52
	v_lshl_add_u64 v[240:241], s[26:27], 0, v[212:213]
	global_load_lds_dwordx4 v[226:227], off
	v_lshl_add_u64 v[226:227], s[20:21], 0, v[206:207]
	s_add_i32 m0, s52, 0x2000
	v_lshl_add_u64 v[242:243], s[26:27], 0, v[208:209]
	global_load_lds_dwordx4 v[226:227], off
	s_mov_b32 m0, s29
	s_nop 0
	global_load_lds_dwordx4 v[240:241], off
	s_mov_b32 m0, s30
	s_nop 0
	global_load_lds_dwordx4 v[242:243], off
	s_waitcnt vmcnt(8)
	s_waitcnt lgkmcnt(0)
	s_setprio 1
	s_barrier
; #define PG8_STAGE(bufoff, gbase, voff) do { _Pragma("unroll") for (int _i = 0; _i < 2; ++_i) \
;         __builtin_amdgcn_global_load_lds((const unsigned*)((const char*)(gbase) + (voff)[_i]), (LAS unsigned*)(lds + (bufoff) + ldsw + _i * 8192), 16, 0, 0); } while (0)
; #define PG8_LDA(dst, b, h) do { _Pragma("unroll") for (int m = 0; m < 4; ++m) _Pragma("unroll") for (int k = 0; k < 2; ++k) dst[m][k] = *(const LAS bf16x8*)(lds + PG8_SA(b, h) + aoff + m * 2048 + k * 1024); } while (0)
; #define PG8_LDB(dst, b, h) do { _Pragma("unroll") for (int n = 0; n < 2; ++n) _Pragma("unroll") for (int k = 0; k < 2; ++k) dst[n][k] = *(const LAS bf16x8*)(lds + PG8_SB(b, h) + boff + n * 2048 + k * 1024); } while (0)
; #define PG8_MMA(ai, bj, At, Bt) do { __builtin_amdgcn_s_setprio(1); _Pragma("unroll") for (int m = 0; m < 4; ++m) _Pragma("unroll") for (int n = 0; n < 2; ++n) _Pragma("unroll") for (int k = 0; k < 2; ++k) \
;         acc[ai][bj][m][n] = __builtin_amdgcn_mfma_f32_16x16x32_bf16(Bt[n][k], At[m][k], acc[ai][bj][m][n], 0, 0, 0); __builtin_amdgcn_s_setprio(0); } while (0)
; #define PG8_WAIT_V(n) asm volatile("s_waitcnt vmcnt(" #n ")" ::: "memory")
; #define PG8_WAIT_L(n) asm volatile("s_waitcnt lgkmcnt(" #n ")" ::: "memory")
; #define PG8_BAR __builtin_amdgcn_s_barrier()
; #define PG8_SCHED __builtin_amdgcn_sched_barrier(0)
; template <class Epi, bool PERMA = false, bool DUAL = false, bool ALIGN_EPI = true, bool SP2 = true>
; __device__ __forceinline__ void gemm_phase(LAS unsigned char* lds, const Gemm g, const StaticOrder& S, const Epi& E) {
;     ...
;             PG8_WAIT_V(8); PG8_WAIT_L(0); PG8_BAR; PG8_MMA(1, 0, At, B0); PG8_MMA(1, 1, At, B1); PG8_BAR; PG8_SCHED;
;             PG8_LDB(B0, 1, 0); PG8_LDB(B1, 1, 1); PG8_SCHED; PG8_LDA(At, 1, 0); PG8_STAGE(PG8_SA(0, 1), a2 + hstepA, voffA);
;             PG8_WAIT_V(8); PG8_WAIT_L(0); PG8_BAR; PG8_MMA(0, 0, At, B0); PG8_MMA(0, 1, At, B1); PG8_BAR; PG8_SCHED;
	s_waitcnt lgkmcnt(0)
	v_mfma_f32_16x16x32_bf16 v[60:63], v[96:99], v[140:143], v[60:63]
	v_mfma_f32_16x16x32_bf16 v[28:31], v[104:107], v[140:143], v[28:31]
	v_mfma_f32_16x16x32_bf16 v[56:59], v[96:99], v[148:151], v[56:59]
	v_mfma_f32_16x16x32_bf16 v[24:27], v[104:107], v[148:151], v[24:27]
	v_mfma_f32_16x16x32_bf16 v[52:55], v[96:99], v[156:159], v[52:55]
	v_mfma_f32_16x16x32_bf16 v[20:23], v[104:107], v[156:159], v[20:23]
	v_mfma_f32_16x16x32_bf16 v[48:51], v[96:99], v[168:171], v[48:51]
	v_mfma_f32_16x16x32_bf16 v[16:19], v[104:107], v[168:171], v[16:19]
	v_mfma_f32_16x16x32_bf16 v[60:63], v[100:103], v[144:147], v[60:63]
	v_mfma_f32_16x16x32_bf16 v[28:31], v[108:111], v[144:147], v[28:31]
	v_mfma_f32_16x16x32_bf16 v[56:59], v[100:103], v[152:155], v[56:59]
	v_mfma_f32_16x16x32_bf16 v[24:27], v[108:111], v[152:155], v[24:27]
	v_mfma_f32_16x16x32_bf16 v[52:55], v[100:103], v[160:163], v[52:55]
	v_mfma_f32_16x16x32_bf16 v[20:23], v[108:111], v[160:163], v[20:23]
	v_mfma_f32_16x16x32_bf16 v[48:51], v[100:103], v[188:191], v[48:51]
	v_mfma_f32_16x16x32_bf16 v[16:19], v[108:111], v[188:191], v[16:19]
	v_mfma_f32_16x16x32_bf16 v[44:47], v[112:115], v[140:143], v[44:47]
	v_mfma_f32_16x16x32_bf16 v[12:15], v[120:123], v[140:143], v[12:15]
	v_mfma_f32_16x16x32_bf16 v[40:43], v[112:115], v[148:151], v[40:43]
	v_mfma_f32_16x16x32_bf16 v[8:11], v[120:123], v[148:151], v[8:11]
	v_mfma_f32_16x16x32_bf16 v[36:39], v[112:115], v[156:159], v[36:39]
	v_mfma_f32_16x16x32_bf16 v[4:7], v[120:123], v[156:159], v[4:7]
	v_mfma_f32_16x16x32_bf16 v[32:35], v[112:115], v[168:171], v[32:35]
	v_mfma_f32_16x16x32_bf16 v[0:3], v[120:123], v[168:171], v[0:3]
	v_mfma_f32_16x16x32_bf16 v[44:47], v[116:119], v[144:147], v[44:47]
	v_mfma_f32_16x16x32_bf16 v[12:15], v[124:127], v[144:147], v[12:15]
	v_mfma_f32_16x16x32_bf16 v[40:43], v[116:119], v[152:155], v[40:43]
	v_mfma_f32_16x16x32_bf16 v[8:11], v[124:127], v[152:155], v[8:11]
	v_mfma_f32_16x16x32_bf16 v[36:39], v[116:119], v[160:163], v[36:39]
	v_mfma_f32_16x16x32_bf16 v[4:7], v[124:127], v[160:163], v[4:7]
	v_mfma_f32_16x16x32_bf16 v[32:35], v[116:119], v[188:191], v[32:35]
	v_mfma_f32_16x16x32_bf16 v[0:3], v[124:127], v[188:191], v[0:3]
	s_barrier
	s_setprio 0
	s_add_i32 s52, 0, 0x18000
	s_add_i32 s53, 0, 0x1c000
	v_add_u32_e32 v108, s52, v193
	v_add_u32_e32 v124, s53, v193
	ds_read_b128 v[96:99], v108
	ds_read_b128 v[100:103], v108 offset:1024
	ds_read_b128 v[104:107], v108 offset:2048
	ds_read_b128 v[108:111], v108 offset:3072
	ds_read_b128 v[112:115], v124
	ds_read_b128 v[116:119], v124 offset:1024
	ds_read_b128 v[120:123], v124 offset:2048
	ds_read_b128 v[124:127], v124 offset:3072
	s_add_u32 s20, s26, 0x80000
	s_addc_u32 s21, s27, 0
	s_mov_b32 m0, s31
	v_lshl_add_u64 v[156:157], s[20:21], 0, v[212:213]
	ds_read_b128 v[140:143], v224 offset:32768
	ds_read_b128 v[144:147], v224 offset:33792
	ds_read_b128 v[148:151], v224 offset:34816
	ds_read_b128 v[152:155], v224 offset:35840
	ds_read_b128 v[160:163], v224 offset:36864
	ds_read_b128 v[168:171], v224 offset:37888
	ds_read_b128 v[188:191], v224 offset:38912
	ds_read_b128 v[226:229], v224 offset:39936
	global_load_lds_dwordx4 v[156:157], off
	v_lshl_add_u64 v[156:157], s[20:21], 0, v[208:209]
	s_mov_b32 m0, s34
	s_nop 0
	global_load_lds_dwordx4 v[156:157], off
	s_waitcnt vmcnt(8)
	s_waitcnt lgkmcnt(0)
	s_setprio 1
	s_barrier
	s_waitcnt lgkmcnt(0)
	v_mfma_f32_16x16x32_bf16 v[156:159], v[96:99], v[140:143], v[184:187]
	v_mfma_f32_16x16x32_bf16 v[184:187], v[100:103], v[144:147], v[156:159]
	v_mfma_f32_16x16x32_bf16 v[156:159], v[96:99], v[148:151], v[180:183]
	v_mfma_f32_16x16x32_bf16 v[180:183], v[100:103], v[152:155], v[156:159]
	v_mfma_f32_16x16x32_bf16 v[156:159], v[96:99], v[160:163], v[176:179]
	v_mfma_f32_16x16x32_bf16 v[92:95], v[104:107], v[140:143], v[92:95]
	v_mfma_f32_16x16x32_bf16 v[88:91], v[104:107], v[148:151], v[88:91]
	v_mfma_f32_16x16x32_bf16 v[176:179], v[100:103], v[168:171], v[156:159]
	v_mfma_f32_16x16x32_bf16 v[84:87], v[104:107], v[160:163], v[84:87]
	v_mfma_f32_16x16x32_bf16 v[156:159], v[96:99], v[188:191], v[172:175]
	v_mfma_f32_16x16x32_bf16 v[80:83], v[104:107], v[188:191], v[80:83]
	v_mfma_f32_16x16x32_bf16 v[92:95], v[108:111], v[144:147], v[92:95]
	v_mfma_f32_16x16x32_bf16 v[88:91], v[108:111], v[152:155], v[88:91]
	v_mfma_f32_16x16x32_bf16 v[84:87], v[108:111], v[168:171], v[84:87]
	v_mfma_f32_16x16x32_bf16 v[172:175], v[100:103], v[226:229], v[156:159]
	v_mfma_f32_16x16x32_bf16 v[80:83], v[108:111], v[226:229], v[80:83]
	v_mfma_f32_16x16x32_bf16 v[156:159], v[112:115], v[140:143], v[164:167]
	v_mfma_f32_16x16x32_bf16 v[128:131], v[112:115], v[148:151], v[128:131]
	v_mfma_f32_16x16x32_bf16 v[164:167], v[116:119], v[144:147], v[156:159]
	v_mfma_f32_16x16x32_bf16 v[156:159], v[116:119], v[152:155], v[128:131]
	v_mfma_f32_16x16x32_bf16 v[128:131], v[112:115], v[160:163], v[132:135]
	v_mfma_f32_16x16x32_bf16 v[76:79], v[120:123], v[140:143], v[76:79]
	v_mfma_f32_16x16x32_bf16 v[72:75], v[120:123], v[148:151], v[72:75]
	v_mfma_f32_16x16x32_bf16 v[148:151], v[116:119], v[168:171], v[128:131]
	v_mfma_f32_16x16x32_bf16 v[68:71], v[120:123], v[160:163], v[68:71]
	v_mfma_f32_16x16x32_bf16 v[128:131], v[112:115], v[188:191], v[136:139]
	v_mfma_f32_16x16x32_bf16 v[64:67], v[120:123], v[188:191], v[64:67]
	v_mfma_f32_16x16x32_bf16 v[76:79], v[124:127], v[144:147], v[76:79]
	v_mfma_f32_16x16x32_bf16 v[72:75], v[124:127], v[152:155], v[72:75]
	v_mfma_f32_16x16x32_bf16 v[68:71], v[124:127], v[168:171], v[68:71]
	v_mfma_f32_16x16x32_bf16 v[140:143], v[116:119], v[226:229], v[128:131]
	v_mfma_f32_16x16x32_bf16 v[64:67], v[124:127], v[226:229], v[64:67]
	s_barrier
; #define PG8_STAGE(bufoff, gbase, voff) do { _Pragma("unroll") for (int _i = 0; _i < 2; ++_i) \
;         __builtin_amdgcn_global_load_lds((const unsigned*)((const char*)(gbase) + (voff)[_i]), (LAS unsigned*)(lds + (bufoff) + ldsw + _i * 8192), 16, 0, 0); } while (0)
; #define PG8_LDA(dst, b, h) do { _Pragma("unroll") for (int m = 0; m < 4; ++m) _Pragma("unroll") for (int k = 0; k < 2; ++k) dst[m][k] = *(const LAS bf16x8*)(lds + PG8_SA(b, h) + aoff + m * 2048 + k * 1024); } while (0)
; #define PG8_MMA(ai, bj, At, Bt) do { __builtin_amdgcn_s_setprio(1); _Pragma("unroll") for (int m = 0; m < 4; ++m) _Pragma("unroll") for (int n = 0; n < 2; ++n) _Pragma("unroll") for (int k = 0; k < 2; ++k) \
;         acc[ai][bj][m][n] = __builtin_amdgcn_mfma_f32_16x16x32_bf16(Bt[n][k], At[m][k], acc[ai][bj][m][n], 0, 0, 0); __builtin_amdgcn_s_setprio(0); } while (0)
; #define PG8_WAIT_V(n) asm volatile("s_waitcnt vmcnt(" #n ")" ::: "memory")
; #define PG8_WAIT_L(n) asm volatile("s_waitcnt lgkmcnt(" #n ")" ::: "memory")
; #define PG8_BAR __builtin_amdgcn_s_barrier()
; #define PG8_SCHED __builtin_amdgcn_sched_barrier(0)
; template <class Epi, bool PERMA = false, bool DUAL = false, bool ALIGN_EPI = true, bool SP2 = true>
; __device__ __forceinline__ void gemm_phase(LAS unsigned char* lds, const Gemm g, const StaticOrder& S, const Epi& E) {
;     ...
;             PG8_LDA(At, 1, 1); PG8_STAGE(PG8_SB(1, 0), b3, voffB); PG8_STAGE(PG8_SB(1, 1), b3 + hstepB, voffB); PG8_STAGE(PG8_SA(1, 0), a3, voffA);
;             PG8_WAIT_V(8); PG8_WAIT_L(0); PG8_BAR; PG8_MMA(1, 0, At, B0); PG8_MMA(1, 1, At, B1); PG8_BAR; PG8_SCHED;
;     __device__ __forceinline__ void operator()(const f32x4 (&acc)[2][2][4][2], const Unit& u, int wr, int wc, int fr, int fq) const {
;     ...
;         const int ch0 = u.pn * HALF + wc * 32 + 8 * fq;
;         const int tok0 = u.pm * BM + wr * 64 + 4 * fr;
;         f32x4 wgt[2][8];
; #pragma unroll
;         for (int n = 0; n < 2; ++n) { const float* wp = cw + ch0 + 4 * n;
;             wgt[n][0] = *(const f32x4*)wp; wgt[n][1] = *(const f32x4*)(wp + 2 * DFF); wgt[n][2] = *(const f32x4*)(wp + 4 * DFF); wgt[n][3] = *(const f32x4*)(cb + ch0 + 4 * n);
;             wgt[n][4] = *(const f32x4*)(wp + DFF); wgt[n][5] = *(const f32x4*)(wp + 3 * DFF); wgt[n][6] = *(const f32x4*)(wp + 5 * DFF); wgt[n][7] = *(const f32x4*)(cb + DFF + ch0 + 4 * n); }
	s_setprio 0
	s_add_i32 s20, s52, s28
	v_lshl_add_u64 v[220:221], v[220:221], 0, s[56:57]
	s_mov_b32 m0, s20
	ds_read_b128 v[128:131], v224 offset:49152
	ds_read_b128 v[132:135], v224 offset:50176
	ds_read_b128 v[136:139], v224 offset:51200
	ds_read_b128 v[144:147], v224 offset:52224
	ds_read_b128 v[152:155], v224 offset:53248
	ds_read_b128 v[160:163], v224 offset:54272
	ds_read_b128 v[168:171], v224 offset:55296
	ds_read_b128 v[188:191], v224 offset:56320
	global_load_lds_dwordx4 v[220:221], off
	s_add_i32 m0, s20, 0x2000
	s_add_u32 s20, s24, 0x80080
	v_lshl_add_u64 v[220:221], v[238:239], 0, s[56:57]
	s_addc_u32 s21, s25, 0
	s_add_i32 s24, s53, s28
	global_load_lds_dwordx4 v[220:221], off
	v_lshl_add_u64 v[220:221], s[20:21], 0, v[210:211]
	s_mov_b32 m0, s24
	s_nop 0
	global_load_lds_dwordx4 v[220:221], off
	v_lshl_add_u64 v[220:221], s[20:21], 0, v[206:207]
	s_add_i32 m0, s24, 0x2000
	s_nop 0
	global_load_lds_dwordx4 v[220:221], off
	v_lshl_add_u64 v[220:221], v[240:241], 0, s[56:57]
	s_mov_b32 m0, s35
	s_nop 0
	global_load_lds_dwordx4 v[220:221], off
	v_lshl_add_u64 v[220:221], v[242:243], 0, s[56:57]
	s_mov_b32 m0, s36
	s_nop 0
	global_load_lds_dwordx4 v[220:221], off
	s_waitcnt vmcnt(8)
	s_waitcnt lgkmcnt(0)
	s_setprio 1
	s_barrier
	s_waitcnt lgkmcnt(0)
	v_mfma_f32_16x16x32_bf16 v[60:63], v[96:99], v[128:131], v[60:63]
	v_mfma_f32_16x16x32_bf16 v[28:31], v[104:107], v[128:131], v[28:31]
	v_mfma_f32_16x16x32_bf16 v[56:59], v[96:99], v[136:139], v[56:59]
	v_mfma_f32_16x16x32_bf16 v[24:27], v[104:107], v[136:139], v[24:27]
	v_mfma_f32_16x16x32_bf16 v[52:55], v[96:99], v[152:155], v[52:55]
	v_mfma_f32_16x16x32_bf16 v[20:23], v[104:107], v[152:155], v[20:23]
	v_mfma_f32_16x16x32_bf16 v[48:51], v[96:99], v[168:171], v[48:51]
	v_mfma_f32_16x16x32_bf16 v[16:19], v[104:107], v[168:171], v[16:19]
	v_mfma_f32_16x16x32_bf16 v[60:63], v[100:103], v[132:135], v[60:63]
	v_mfma_f32_16x16x32_bf16 v[28:31], v[108:111], v[132:135], v[28:31]
	v_mfma_f32_16x16x32_bf16 v[56:59], v[100:103], v[144:147], v[56:59]
	v_mfma_f32_16x16x32_bf16 v[24:27], v[108:111], v[144:147], v[24:27]
	v_mfma_f32_16x16x32_bf16 v[52:55], v[100:103], v[160:163], v[52:55]
	v_mfma_f32_16x16x32_bf16 v[20:23], v[108:111], v[160:163], v[20:23]
	v_mfma_f32_16x16x32_bf16 v[48:51], v[100:103], v[188:191], v[48:51]
	v_mfma_f32_16x16x32_bf16 v[16:19], v[108:111], v[188:191], v[16:19]
	v_mfma_f32_16x16x32_bf16 v[44:47], v[112:115], v[128:131], v[44:47]
	v_mfma_f32_16x16x32_bf16 v[12:15], v[120:123], v[128:131], v[12:15]
	v_mfma_f32_16x16x32_bf16 v[40:43], v[112:115], v[136:139], v[40:43]
	v_mfma_f32_16x16x32_bf16 v[8:11], v[120:123], v[136:139], v[8:11]
	v_mfma_f32_16x16x32_bf16 v[36:39], v[112:115], v[152:155], v[36:39]
	v_mfma_f32_16x16x32_bf16 v[4:7], v[120:123], v[152:155], v[4:7]
	v_mfma_f32_16x16x32_bf16 v[32:35], v[112:115], v[168:171], v[32:35]
	v_mfma_f32_16x16x32_bf16 v[0:3], v[120:123], v[168:171], v[0:3]
	v_mfma_f32_16x16x32_bf16 v[44:47], v[116:119], v[132:135], v[44:47]
	v_mfma_f32_16x16x32_bf16 v[12:15], v[124:127], v[132:135], v[12:15]
	v_mfma_f32_16x16x32_bf16 v[40:43], v[116:119], v[144:147], v[40:43]
	v_mfma_f32_16x16x32_bf16 v[8:11], v[124:127], v[144:147], v[8:11]
	v_mfma_f32_16x16x32_bf16 v[36:39], v[116:119], v[160:163], v[36:39]
	v_mfma_f32_16x16x32_bf16 v[4:7], v[124:127], v[160:163], v[4:7]
	v_mfma_f32_16x16x32_bf16 v[32:35], v[116:119], v[188:191], v[32:35]
	v_mfma_f32_16x16x32_bf16 v[0:3], v[124:127], v[188:191], v[0:3]
	s_barrier
	s_setprio 0
	s_add_i32 s51, s51, 2
	s_add_u32 s49, s49, 0x100
	s_addc_u32 s50, s50, 0
	s_cmp_gt_u32 s51, 29
	s_mov_b64 s[20:21], s[22:23]
	s_cbranch_scc0 .LBB0_528
	v_lshl_or_b32 v220, s38, 7, v214
	v_ashrrev_i32_e32 v221, 31, v220
	v_lshlrev_b64 v[96:97], 2, v[220:221]
	v_lshl_add_u64 v[112:113], s[2:3], 0, v[96:97]
	v_add_co_u32_e32 v102, vcc, s72, v112
	s_mov_b64 s[20:21], 0xb000
	s_nop 0
	v_addc_co_u32_e32 v103, vcc, 0, v113, vcc
	s_mov_b32 s13, 0x16000
	v_lshl_add_u64 v[100:101], v[112:113], 0, s[20:21]
	s_mov_b64 s[20:21], 0x16000
	v_add_co_u32_e32 v106, vcc, s13, v112
	s_nop 0
	v_lshl_add_u64 v[104:105], v[112:113], 0, s[20:21]
	v_addc_co_u32_e32 v107, vcc, 0, v113, vcc
	v_lshl_add_u64 v[114:115], s[6:7], 0, v[96:97]
	v_lshl_add_u64 v[188:189], s[10:11], 0, v[96:97]
	global_load_dwordx4 v[96:99], v[112:113], off offset:16
	global_load_dwordx4 v[128:131], v[112:113], off
	global_load_dwordx4 v[132:135], v[102:103], off
	s_nop 0
	global_load_dwordx4 v[100:103], v[100:101], off offset:16
	s_nop 0
	global_load_dwordx4 v[136:139], v[106:107], off
	s_nop 0
	global_load_dwordx4 v[104:107], v[104:105], off offset:16
	s_nop 0
	global_load_dwordx4 v[108:111], v[114:115], off offset:16
	global_load_dwordx4 v[144:147], v[114:115], off
	s_movk_i32 s13, 0x5000
	v_add_co_u32_e32 v116, vcc, s13, v112
	s_mov_b64 s[20:21], 0x5800
	s_nop 0
	v_addc_co_u32_e32 v117, vcc, 0, v113, vcc
	s_mov_b32 s13, 0x10000
	v_lshl_add_u64 v[114:115], v[112:113], 0, s[20:21]
	s_mov_b64 s[20:21], 0x10800
	v_add_co_u32_e32 v120, vcc, s13, v112
	global_load_dwordx4 v[160:163], v[116:117], off offset:2048
	s_nop 0
	global_load_dwordx4 v[116:119], v[114:115], off offset:16
	v_lshl_add_u64 v[114:115], v[112:113], 0, s[20:21]
	v_addc_co_u32_e32 v121, vcc, 0, v113, vcc
	s_mov_b64 s[20:21], 0x1b800
	s_mov_b32 s13, 0x1b000
	global_load_dwordx4 v[168:171], v[120:121], off offset:2048
	s_nop 0
	global_load_dwordx4 v[120:123], v[114:115], off offset:16
	v_lshl_add_u64 v[114:115], v[112:113], 0, s[20:21]
	v_add_co_u32_e32 v112, vcc, s13, v112
	s_nop 0
	v_addc_co_u32_e32 v113, vcc, 0, v113, vcc
	global_load_dwordx4 v[152:155], v[112:113], off offset:2048
	s_nop 0
	global_load_dwordx4 v[112:115], v[114:115], off offset:16
	s_nop 0
	global_load_dwordx4 v[124:127], v[188:189], off offset:16
	s_nop 0
	global_load_dwordx4 v[188:191], v[188:189], off
	s_and_b64 vcc, exec, s[4:5]
	s_cbranch_vccz .LBB0_531
	s_barrier

; #define PG8_STAGE(bufoff, gbase, voff) do { _Pragma("unroll") for (int _i = 0; _i < 2; ++_i) \
;         __builtin_amdgcn_global_load_lds((const unsigned*)((const char*)(gbase) + (voff)[_i]), (LAS unsigned*)(lds + (bufoff) + ldsw + _i * 8192), 16, 0, 0); } while (0)
; #define PG8_LDA(dst, b, h) do { _Pragma("unroll") for (int m = 0; m < 4; ++m) _Pragma("unroll") for (int k = 0; k < 2; ++k) dst[m][k] = *(const LAS bf16x8*)(lds + PG8_SA(b, h) + aoff + m * 2048 + k * 1024); } while (0)
; #define PG8_LDB(dst, b, h) do { _Pragma("unroll") for (int n = 0; n < 2; ++n) _Pragma("unroll") for (int k = 0; k < 2; ++k) dst[n][k] = *(const LAS bf16x8*)(lds + PG8_SB(b, h) + boff + n * 2048 + k * 1024); } while (0)
; #define PG8_MMA(ai, bj, At, Bt) do { __builtin_amdgcn_s_setprio(1); _Pragma("unroll") for (int m = 0; m < 4; ++m) _Pragma("unroll") for (int n = 0; n < 2; ++n) _Pragma("unroll") for (int k = 0; k < 2; ++k) \
;         acc[ai][bj][m][n] = __builtin_amdgcn_mfma_f32_16x16x32_bf16(Bt[n][k], At[m][k], acc[ai][bj][m][n], 0, 0, 0); __builtin_amdgcn_s_setprio(0); } while (0)
; template <class Epi, bool PERMA = false, bool DUAL = false, bool ALIGN_EPI = true, bool SP2 = true>
; __device__ __forceinline__ void gemm_phase(LAS unsigned char* lds, const Gemm g, const StaticOrder& S, const Epi& E) {
;     ...
;         const char* nA = has_next ? (const char*)gA_ + (size_t)nxt.pm * tstepA : cA; const char* nB = has_next ? (const char*)gB_ + (size_t)nxt.pn * tstepB : cB;
;         for (int t = 0; t < nt; t += 2) {
;             const bool last = (t == nt - 2);
;             const char* a1 = cA + (size_t)(t + 1) * kstep;
;             const char* a2 = last ? nA : cA + (size_t)(t + 2) * kstep; const char* b2 = last ? nB : cB + (size_t)(t + 2) * kstep;
;             const char* a3 = a2 + kstep; const char* b3 = b2 + kstep;
;             if constexpr (SP2) {
;             PG8_LDB(B0, 0, 0); PG8_LDB(B1, 0, 1); PG8_SCHED; PG8_LDA(At, 0, 0); PG8_STAGE(PG8_SA(1, 1), a1 + hstepA, voffA);
;             PG8_WAIT_V(8); PG8_WAIT_L(0); PG8_BAR; PG8_MMA(0, 0, At, B0); PG8_MMA(0, 1, At, B1); PG8_BAR; PG8_SCHED;
;             PG8_LDA(At, 0, 1); PG8_STAGE(PG8_SB(0, 0), b2, voffB); PG8_STAGE(PG8_SB(0, 1), b2 + hstepB, voffB); PG8_STAGE(PG8_SA(0, 0), a2, voffA);
;             PG8_WAIT_V(8); PG8_WAIT_L(0); PG8_BAR; PG8_MMA(1, 0, At, B0); PG8_MMA(1, 1, At, B1); PG8_BAR; PG8_SCHED;
.LBB0_675:
	s_add_u32 s14, s12, 0x100
	s_addc_u32 s15, s13, 0
	s_add_i32 s36, 0, 0x10000
	s_cmpk_eq_i32 s33, 0x54
	s_cselect_b32 s19, s1, s15
	s_cselect_b32 s18, s0, s14
	s_cselect_b32 s17, s7, s11
	s_cselect_b32 s16, s6, s9
	s_add_i32 s37, 0, 0x14000
	v_add_u32_e32 v116, s36, v193
	v_add_u32_e32 v156, s37, v193
	ds_read_b128 v[104:107], v116
	ds_read_b128 v[108:111], v116 offset:1024
	ds_read_b128 v[112:115], v116 offset:2048
	ds_read_b128 v[116:119], v116 offset:3072
	ds_read_b128 v[144:147], v156
	ds_read_b128 v[148:151], v156 offset:1024
	ds_read_b128 v[152:155], v156 offset:2048
	ds_read_b128 v[156:159], v156 offset:3072
	v_lshl_add_u64 v[206:207], s[12:13], 0, v[180:181]
	s_add_i32 m0, s21, 0xc000
	ds_read_b128 v[184:187], v212
	ds_read_b128 v[188:191], v212 offset:1024
	ds_read_b128 v[214:217], v212 offset:2048
	ds_read_b128 v[218:221], v212 offset:3072
	ds_read_b128 v[222:225], v212 offset:4096
	ds_read_b128 v[226:229], v212 offset:5120
	ds_read_b128 v[238:241], v212 offset:6144
	ds_read_b128 v[242:245], v212 offset:7168
	global_load_lds_dwordx4 v[206:207], off
	v_lshl_add_u64 v[206:207], s[12:13], 0, v[182:183]
	s_add_i32 m0, s21, 0xe000
	s_nop 0
	global_load_lds_dwordx4 v[206:207], off
	s_waitcnt vmcnt(8)
	s_waitcnt lgkmcnt(0)
	s_setprio 1
	s_barrier
	s_waitcnt lgkmcnt(0)
	v_mfma_f32_16x16x32_bf16 v[140:143], v[104:107], v[184:187], v[140:143]
	v_mfma_f32_16x16x32_bf16 v[136:139], v[112:115], v[184:187], v[136:139]
	v_mfma_f32_16x16x32_bf16 v[124:127], v[104:107], v[214:217], v[124:127]
	v_mfma_f32_16x16x32_bf16 v[120:123], v[112:115], v[214:217], v[120:123]
	v_mfma_f32_16x16x32_bf16 v[92:95], v[104:107], v[222:225], v[92:95]
	v_mfma_f32_16x16x32_bf16 v[88:91], v[112:115], v[222:225], v[88:91]
	v_mfma_f32_16x16x32_bf16 v[76:79], v[104:107], v[238:241], v[76:79]
	v_mfma_f32_16x16x32_bf16 v[72:75], v[112:115], v[238:241], v[72:75]
	v_mfma_f32_16x16x32_bf16 v[140:143], v[108:111], v[188:191], v[140:143]
	v_mfma_f32_16x16x32_bf16 v[136:139], v[116:119], v[188:191], v[136:139]
	v_mfma_f32_16x16x32_bf16 v[124:127], v[108:111], v[218:221], v[124:127]
	v_mfma_f32_16x16x32_bf16 v[120:123], v[116:119], v[218:221], v[120:123]
	v_mfma_f32_16x16x32_bf16 v[92:95], v[108:111], v[226:229], v[92:95]
	v_mfma_f32_16x16x32_bf16 v[88:91], v[116:119], v[226:229], v[88:91]
	v_mfma_f32_16x16x32_bf16 v[76:79], v[108:111], v[242:245], v[76:79]
	v_mfma_f32_16x16x32_bf16 v[72:75], v[116:119], v[242:245], v[72:75]
	v_mfma_f32_16x16x32_bf16 v[132:135], v[144:147], v[184:187], v[132:135]
	v_mfma_f32_16x16x32_bf16 v[128:131], v[152:155], v[184:187], v[128:131]
	v_mfma_f32_16x16x32_bf16 v[100:103], v[144:147], v[214:217], v[100:103]
	v_mfma_f32_16x16x32_bf16 v[96:99], v[152:155], v[214:217], v[96:99]
	v_mfma_f32_16x16x32_bf16 v[84:87], v[144:147], v[222:225], v[84:87]
	v_mfma_f32_16x16x32_bf16 v[80:83], v[152:155], v[222:225], v[80:83]
	v_mfma_f32_16x16x32_bf16 v[68:71], v[144:147], v[238:241], v[68:71]
	v_mfma_f32_16x16x32_bf16 v[64:67], v[152:155], v[238:241], v[64:67]
	v_mfma_f32_16x16x32_bf16 v[132:135], v[148:151], v[188:191], v[132:135]
	v_mfma_f32_16x16x32_bf16 v[128:131], v[156:159], v[188:191], v[128:131]
	v_mfma_f32_16x16x32_bf16 v[100:103], v[148:151], v[218:221], v[100:103]
	v_mfma_f32_16x16x32_bf16 v[96:99], v[156:159], v[218:221], v[96:99]
	v_mfma_f32_16x16x32_bf16 v[84:87], v[148:151], v[226:229], v[84:87]
	v_mfma_f32_16x16x32_bf16 v[80:83], v[156:159], v[226:229], v[80:83]
	v_mfma_f32_16x16x32_bf16 v[68:71], v[148:151], v[242:245], v[68:71]
	v_mfma_f32_16x16x32_bf16 v[64:67], v[156:159], v[242:245], v[64:67]
	s_barrier
	s_setprio 0
	s_add_i32 s12, s36, s20
	v_lshl_add_u64 v[206:207], s[16:17], 0, v[164:165]
	s_mov_b32 m0, s12
	ds_read_b128 v[184:187], v212 offset:16384
	ds_read_b128 v[188:191], v212 offset:17408
	ds_read_b128 v[214:217], v212 offset:18432
	ds_read_b128 v[218:221], v212 offset:19456
	ds_read_b128 v[222:225], v212 offset:20480
	ds_read_b128 v[226:229], v212 offset:21504
	ds_read_b128 v[238:241], v212 offset:22528
	ds_read_b128 v[242:245], v212 offset:23552
	global_load_lds_dwordx4 v[206:207], off
	s_add_i32 m0, s12, 0x2000
	s_add_u32 s12, s16, 0x160000
	v_lshl_add_u64 v[246:247], s[16:17], 0, v[160:161]
	s_addc_u32 s13, s17, 0
	s_add_i32 s36, s37, s20
	global_load_lds_dwordx4 v[246:247], off
	v_lshl_add_u64 v[248:249], s[12:13], 0, v[164:165]
	s_mov_b32 m0, s36
	v_lshl_add_u64 v[194:195], s[18:19], 0, v[162:163]
	global_load_lds_dwordx4 v[248:249], off
	v_lshl_add_u64 v[248:249], s[12:13], 0, v[160:161]
	s_add_i32 m0, s36, 0x2000
	s_nop 0
	global_load_lds_dwordx4 v[248:249], off
	v_lshl_add_u64 v[248:249], s[18:19], 0, v[166:167]
	s_mov_b32 m0, s21
	s_nop 0
	global_load_lds_dwordx4 v[248:249], off
	s_mov_b32 m0, s22
	s_nop 0
	global_load_lds_dwordx4 v[194:195], off
	s_waitcnt vmcnt(8)
	s_waitcnt lgkmcnt(0)
	s_setprio 1
	s_barrier
; #define PG8_STAGE(bufoff, gbase, voff) do { _Pragma("unroll") for (int _i = 0; _i < 2; ++_i) \
;         __builtin_amdgcn_global_load_lds((const unsigned*)((const char*)(gbase) + (voff)[_i]), (LAS unsigned*)(lds + (bufoff) + ldsw + _i * 8192), 16, 0, 0); } while (0)
; #define PG8_LDA(dst, b, h) do { _Pragma("unroll") for (int m = 0; m < 4; ++m) _Pragma("unroll") for (int k = 0; k < 2; ++k) dst[m][k] = *(const LAS bf16x8*)(lds + PG8_SA(b, h) + aoff + m * 2048 + k * 1024); } while (0)
; #define PG8_LDB(dst, b, h) do { _Pragma("unroll") for (int n = 0; n < 2; ++n) _Pragma("unroll") for (int k = 0; k < 2; ++k) dst[n][k] = *(const LAS bf16x8*)(lds + PG8_SB(b, h) + boff + n * 2048 + k * 1024); } while (0)
; #define PG8_MMA(ai, bj, At, Bt) do { __builtin_amdgcn_s_setprio(1); _Pragma("unroll") for (int m = 0; m < 4; ++m) _Pragma("unroll") for (int n = 0; n < 2; ++n) _Pragma("unroll") for (int k = 0; k < 2; ++k) \
;         acc[ai][bj][m][n] = __builtin_amdgcn_mfma_f32_16x16x32_bf16(Bt[n][k], At[m][k], acc[ai][bj][m][n], 0, 0, 0); __builtin_amdgcn_s_setprio(0); } while (0)
; #define PG8_WAIT_V(n) asm volatile("s_waitcnt vmcnt(" #n ")" ::: "memory")
; #define PG8_WAIT_L(n) asm volatile("s_waitcnt lgkmcnt(" #n ")" ::: "memory")
; #define PG8_BAR __builtin_amdgcn_s_barrier()
; #define PG8_SCHED __builtin_amdgcn_sched_barrier(0)
; template <class Epi, bool PERMA = false, bool DUAL = false, bool ALIGN_EPI = true, bool SP2 = true>
; __device__ __forceinline__ void gemm_phase(LAS unsigned char* lds, const Gemm g, const StaticOrder& S, const Epi& E) {
;     ...
;             PG8_WAIT_V(8); PG8_WAIT_L(0); PG8_BAR; PG8_MMA(1, 0, At, B0); PG8_MMA(1, 1, At, B1); PG8_BAR; PG8_SCHED;
;             PG8_LDB(B0, 1, 0); PG8_LDB(B1, 1, 1); PG8_SCHED; PG8_LDA(At, 1, 0); PG8_STAGE(PG8_SA(0, 1), a2 + hstepA, voffA);
;             PG8_WAIT_V(8); PG8_WAIT_L(0); PG8_BAR; PG8_MMA(0, 0, At, B0); PG8_MMA(0, 1, At, B1); PG8_BAR; PG8_SCHED;
	s_waitcnt lgkmcnt(0)
	v_mfma_f32_16x16x32_bf16 v[60:63], v[104:107], v[184:187], v[60:63]
	v_mfma_f32_16x16x32_bf16 v[56:59], v[112:115], v[184:187], v[56:59]
	v_mfma_f32_16x16x32_bf16 v[44:47], v[104:107], v[214:217], v[44:47]
	v_mfma_f32_16x16x32_bf16 v[40:43], v[112:115], v[214:217], v[40:43]
	v_mfma_f32_16x16x32_bf16 v[28:31], v[104:107], v[222:225], v[28:31]
	v_mfma_f32_16x16x32_bf16 v[24:27], v[112:115], v[222:225], v[24:27]
	v_mfma_f32_16x16x32_bf16 v[12:15], v[104:107], v[238:241], v[12:15]
	v_mfma_f32_16x16x32_bf16 v[8:11], v[112:115], v[238:241], v[8:11]
	v_mfma_f32_16x16x32_bf16 v[60:63], v[108:111], v[188:191], v[60:63]
	v_mfma_f32_16x16x32_bf16 v[56:59], v[116:119], v[188:191], v[56:59]
	v_mfma_f32_16x16x32_bf16 v[44:47], v[108:111], v[218:221], v[44:47]
	v_mfma_f32_16x16x32_bf16 v[40:43], v[116:119], v[218:221], v[40:43]
	v_mfma_f32_16x16x32_bf16 v[28:31], v[108:111], v[226:229], v[28:31]
	v_mfma_f32_16x16x32_bf16 v[24:27], v[116:119], v[226:229], v[24:27]
	v_mfma_f32_16x16x32_bf16 v[12:15], v[108:111], v[242:245], v[12:15]
	v_mfma_f32_16x16x32_bf16 v[8:11], v[116:119], v[242:245], v[8:11]
	v_mfma_f32_16x16x32_bf16 v[52:55], v[144:147], v[184:187], v[52:55]
	v_mfma_f32_16x16x32_bf16 v[48:51], v[152:155], v[184:187], v[48:51]
	v_mfma_f32_16x16x32_bf16 v[36:39], v[144:147], v[214:217], v[36:39]
	v_mfma_f32_16x16x32_bf16 v[32:35], v[152:155], v[214:217], v[32:35]
	v_mfma_f32_16x16x32_bf16 v[20:23], v[144:147], v[222:225], v[20:23]
	v_mfma_f32_16x16x32_bf16 v[16:19], v[152:155], v[222:225], v[16:19]
	v_mfma_f32_16x16x32_bf16 v[4:7], v[144:147], v[238:241], v[4:7]
	v_mfma_f32_16x16x32_bf16 v[0:3], v[152:155], v[238:241], v[0:3]
	v_mfma_f32_16x16x32_bf16 v[52:55], v[148:151], v[188:191], v[52:55]
	v_mfma_f32_16x16x32_bf16 v[48:51], v[156:159], v[188:191], v[48:51]
	v_mfma_f32_16x16x32_bf16 v[36:39], v[148:151], v[218:221], v[36:39]
	v_mfma_f32_16x16x32_bf16 v[32:35], v[156:159], v[218:221], v[32:35]
	v_mfma_f32_16x16x32_bf16 v[20:23], v[148:151], v[226:229], v[20:23]
	v_mfma_f32_16x16x32_bf16 v[16:19], v[156:159], v[226:229], v[16:19]
	v_mfma_f32_16x16x32_bf16 v[4:7], v[148:151], v[242:245], v[4:7]
	v_mfma_f32_16x16x32_bf16 v[0:3], v[156:159], v[242:245], v[0:3]
	s_barrier
	s_setprio 0
	s_add_i32 s36, 0, 0x18000
	s_add_i32 s37, 0, 0x1c000
	v_add_u32_e32 v116, s36, v193
	v_add_u32_e32 v156, s37, v193
	ds_read_b128 v[104:107], v116
	ds_read_b128 v[108:111], v116 offset:1024
	ds_read_b128 v[112:115], v116 offset:2048
	ds_read_b128 v[116:119], v116 offset:3072
	ds_read_b128 v[144:147], v156
	ds_read_b128 v[148:151], v156 offset:1024
	ds_read_b128 v[152:155], v156 offset:2048
	ds_read_b128 v[156:159], v156 offset:3072
	s_add_u32 s12, s18, 0x160000
	s_addc_u32 s13, s19, 0
	s_mov_b32 m0, s23
	v_lshl_add_u64 v[196:197], s[12:13], 0, v[166:167]
	ds_read_b128 v[184:187], v212 offset:32768
	ds_read_b128 v[188:191], v212 offset:33792
	ds_read_b128 v[214:217], v212 offset:34816
	ds_read_b128 v[218:221], v212 offset:35840
	ds_read_b128 v[222:225], v212 offset:36864
	ds_read_b128 v[226:229], v212 offset:37888
	ds_read_b128 v[238:241], v212 offset:38912
	ds_read_b128 v[242:245], v212 offset:39936
	global_load_lds_dwordx4 v[196:197], off
	v_lshl_add_u64 v[196:197], s[12:13], 0, v[162:163]
	s_mov_b32 m0, s24
	s_nop 0
	global_load_lds_dwordx4 v[196:197], off
	s_waitcnt vmcnt(8)
	s_waitcnt lgkmcnt(0)
	s_setprio 1
	s_barrier
	s_waitcnt lgkmcnt(0)
	v_mfma_f32_16x16x32_bf16 v[140:143], v[104:107], v[184:187], v[140:143]
	v_mfma_f32_16x16x32_bf16 v[136:139], v[112:115], v[184:187], v[136:139]
	v_mfma_f32_16x16x32_bf16 v[124:127], v[104:107], v[214:217], v[124:127]
	v_mfma_f32_16x16x32_bf16 v[120:123], v[112:115], v[214:217], v[120:123]
	v_mfma_f32_16x16x32_bf16 v[92:95], v[104:107], v[222:225], v[92:95]
	v_mfma_f32_16x16x32_bf16 v[88:91], v[112:115], v[222:225], v[88:91]
	v_mfma_f32_16x16x32_bf16 v[76:79], v[104:107], v[238:241], v[76:79]
	v_mfma_f32_16x16x32_bf16 v[72:75], v[112:115], v[238:241], v[72:75]
	v_mfma_f32_16x16x32_bf16 v[140:143], v[108:111], v[188:191], v[140:143]
	v_mfma_f32_16x16x32_bf16 v[136:139], v[116:119], v[188:191], v[136:139]
	v_mfma_f32_16x16x32_bf16 v[124:127], v[108:111], v[218:221], v[124:127]
	v_mfma_f32_16x16x32_bf16 v[120:123], v[116:119], v[218:221], v[120:123]
	v_mfma_f32_16x16x32_bf16 v[92:95], v[108:111], v[226:229], v[92:95]
	v_mfma_f32_16x16x32_bf16 v[88:91], v[116:119], v[226:229], v[88:91]
	v_mfma_f32_16x16x32_bf16 v[76:79], v[108:111], v[242:245], v[76:79]
	v_mfma_f32_16x16x32_bf16 v[72:75], v[116:119], v[242:245], v[72:75]
	v_mfma_f32_16x16x32_bf16 v[132:135], v[144:147], v[184:187], v[132:135]
	v_mfma_f32_16x16x32_bf16 v[128:131], v[152:155], v[184:187], v[128:131]
	v_mfma_f32_16x16x32_bf16 v[100:103], v[144:147], v[214:217], v[100:103]
	v_mfma_f32_16x16x32_bf16 v[96:99], v[152:155], v[214:217], v[96:99]
	v_mfma_f32_16x16x32_bf16 v[84:87], v[144:147], v[222:225], v[84:87]
	v_mfma_f32_16x16x32_bf16 v[80:83], v[152:155], v[222:225], v[80:83]
	v_mfma_f32_16x16x32_bf16 v[68:71], v[144:147], v[238:241], v[68:71]
	v_mfma_f32_16x16x32_bf16 v[64:67], v[152:155], v[238:241], v[64:67]
	v_mfma_f32_16x16x32_bf16 v[132:135], v[148:151], v[188:191], v[132:135]
	v_mfma_f32_16x16x32_bf16 v[128:131], v[156:159], v[188:191], v[128:131]
	v_mfma_f32_16x16x32_bf16 v[100:103], v[148:151], v[218:221], v[100:103]
	v_mfma_f32_16x16x32_bf16 v[96:99], v[156:159], v[218:221], v[96:99]
	v_mfma_f32_16x16x32_bf16 v[84:87], v[148:151], v[226:229], v[84:87]
	v_mfma_f32_16x16x32_bf16 v[80:83], v[156:159], v[226:229], v[80:83]
	v_mfma_f32_16x16x32_bf16 v[68:71], v[148:151], v[242:245], v[68:71]
	v_mfma_f32_16x16x32_bf16 v[64:67], v[156:159], v[242:245], v[64:67]
	s_barrier
; #define PG8_STAGE(bufoff, gbase, voff) do { _Pragma("unroll") for (int _i = 0; _i < 2; ++_i) \
;         __builtin_amdgcn_global_load_lds((const unsigned*)((const char*)(gbase) + (voff)[_i]), (LAS unsigned*)(lds + (bufoff) + ldsw + _i * 8192), 16, 0, 0); } while (0)
; #define PG8_LDA(dst, b, h) do { _Pragma("unroll") for (int m = 0; m < 4; ++m) _Pragma("unroll") for (int k = 0; k < 2; ++k) dst[m][k] = *(const LAS bf16x8*)(lds + PG8_SA(b, h) + aoff + m * 2048 + k * 1024); } while (0)
; #define PG8_MMA(ai, bj, At, Bt) do { __builtin_amdgcn_s_setprio(1); _Pragma("unroll") for (int m = 0; m < 4; ++m) _Pragma("unroll") for (int n = 0; n < 2; ++n) _Pragma("unroll") for (int k = 0; k < 2; ++k) \
;         acc[ai][bj][m][n] = __builtin_amdgcn_mfma_f32_16x16x32_bf16(Bt[n][k], At[m][k], acc[ai][bj][m][n], 0, 0, 0); __builtin_amdgcn_s_setprio(0); } while (0)
; #define PG8_WAIT_V(n) asm volatile("s_waitcnt vmcnt(" #n ")" ::: "memory")
; #define PG8_WAIT_L(n) asm volatile("s_waitcnt lgkmcnt(" #n ")" ::: "memory")
; #define PG8_BAR __builtin_amdgcn_s_barrier()
; #define PG8_SCHED __builtin_amdgcn_sched_barrier(0)
; template <class Epi, bool PERMA = false, bool DUAL = false, bool ALIGN_EPI = true, bool SP2 = true>
; __device__ __forceinline__ void gemm_phase(LAS unsigned char* lds, const Gemm g, const StaticOrder& S, const Epi& E) {
;     ...
;             PG8_LDA(At, 1, 1); PG8_STAGE(PG8_SB(1, 0), b3, voffB); PG8_STAGE(PG8_SB(1, 1), b3 + hstepB, voffB); PG8_STAGE(PG8_SA(1, 0), a3, voffA);
;             PG8_WAIT_V(8); PG8_WAIT_L(0); PG8_BAR; PG8_MMA(1, 0, At, B0); PG8_MMA(1, 1, At, B1); PG8_BAR; PG8_SCHED;
;     ...
;         if constexpr (ALIGN_EPI) { if (wr == 0) PG8_BAR; }
	s_setprio 0
	s_add_i32 s12, s36, s20
	v_lshl_add_u64 v[196:197], v[206:207], 0, s[38:39]
	s_mov_b32 m0, s12
	ds_read_b128 v[184:187], v212 offset:49152
	ds_read_b128 v[188:191], v212 offset:50176
	ds_read_b128 v[214:217], v212 offset:51200
	ds_read_b128 v[218:221], v212 offset:52224
	ds_read_b128 v[222:225], v212 offset:53248
	ds_read_b128 v[226:229], v212 offset:54272
	ds_read_b128 v[238:241], v212 offset:55296
	ds_read_b128 v[242:245], v212 offset:56320
	global_load_lds_dwordx4 v[196:197], off
	s_add_i32 m0, s12, 0x2000
	s_add_u32 s12, s16, 0x160080
	v_lshl_add_u64 v[196:197], v[246:247], 0, s[38:39]
	s_addc_u32 s13, s17, 0
	s_add_i32 s16, s37, s20
	global_load_lds_dwordx4 v[196:197], off
	v_lshl_add_u64 v[196:197], s[12:13], 0, v[164:165]
	s_mov_b32 m0, s16
	v_lshl_add_u64 v[194:195], v[194:195], 0, s[38:39]
	global_load_lds_dwordx4 v[196:197], off
	v_lshl_add_u64 v[196:197], s[12:13], 0, v[160:161]
	s_add_i32 m0, s16, 0x2000
	s_nop 0
	global_load_lds_dwordx4 v[196:197], off
	v_lshl_add_u64 v[196:197], v[248:249], 0, s[38:39]
	s_mov_b32 m0, s29
	s_nop 0
	global_load_lds_dwordx4 v[196:197], off
	s_mov_b32 m0, s30
	s_nop 0
	global_load_lds_dwordx4 v[194:195], off
	s_waitcnt vmcnt(8)
	s_waitcnt lgkmcnt(0)
	s_setprio 1
	s_barrier
	s_waitcnt lgkmcnt(0)
	v_mfma_f32_16x16x32_bf16 v[60:63], v[104:107], v[184:187], v[60:63]
	v_mfma_f32_16x16x32_bf16 v[56:59], v[112:115], v[184:187], v[56:59]
	v_mfma_f32_16x16x32_bf16 v[44:47], v[104:107], v[214:217], v[44:47]
	v_mfma_f32_16x16x32_bf16 v[40:43], v[112:115], v[214:217], v[40:43]
	v_mfma_f32_16x16x32_bf16 v[28:31], v[104:107], v[222:225], v[28:31]
	v_mfma_f32_16x16x32_bf16 v[24:27], v[112:115], v[222:225], v[24:27]
	v_mfma_f32_16x16x32_bf16 v[12:15], v[104:107], v[238:241], v[12:15]
	v_mfma_f32_16x16x32_bf16 v[8:11], v[112:115], v[238:241], v[8:11]
	v_mfma_f32_16x16x32_bf16 v[60:63], v[108:111], v[188:191], v[60:63]
	v_mfma_f32_16x16x32_bf16 v[56:59], v[116:119], v[188:191], v[56:59]
	v_mfma_f32_16x16x32_bf16 v[44:47], v[108:111], v[218:221], v[44:47]
	v_mfma_f32_16x16x32_bf16 v[40:43], v[116:119], v[218:221], v[40:43]
	v_mfma_f32_16x16x32_bf16 v[28:31], v[108:111], v[226:229], v[28:31]
	v_mfma_f32_16x16x32_bf16 v[24:27], v[116:119], v[226:229], v[24:27]
	v_mfma_f32_16x16x32_bf16 v[12:15], v[108:111], v[242:245], v[12:15]
	v_mfma_f32_16x16x32_bf16 v[8:11], v[116:119], v[242:245], v[8:11]
	v_mfma_f32_16x16x32_bf16 v[52:55], v[144:147], v[184:187], v[52:55]
	v_mfma_f32_16x16x32_bf16 v[48:51], v[152:155], v[184:187], v[48:51]
	v_mfma_f32_16x16x32_bf16 v[36:39], v[144:147], v[214:217], v[36:39]
	v_mfma_f32_16x16x32_bf16 v[32:35], v[152:155], v[214:217], v[32:35]
	v_mfma_f32_16x16x32_bf16 v[20:23], v[144:147], v[222:225], v[20:23]
	v_mfma_f32_16x16x32_bf16 v[16:19], v[152:155], v[222:225], v[16:19]
	v_mfma_f32_16x16x32_bf16 v[4:7], v[144:147], v[238:241], v[4:7]
	v_mfma_f32_16x16x32_bf16 v[0:3], v[152:155], v[238:241], v[0:3]
	v_mfma_f32_16x16x32_bf16 v[52:55], v[148:151], v[188:191], v[52:55]
	v_mfma_f32_16x16x32_bf16 v[48:51], v[156:159], v[188:191], v[48:51]
	v_mfma_f32_16x16x32_bf16 v[36:39], v[148:151], v[218:221], v[36:39]
	v_mfma_f32_16x16x32_bf16 v[32:35], v[156:159], v[218:221], v[32:35]
	v_mfma_f32_16x16x32_bf16 v[20:23], v[148:151], v[226:229], v[20:23]
	v_mfma_f32_16x16x32_bf16 v[16:19], v[156:159], v[226:229], v[16:19]
	v_mfma_f32_16x16x32_bf16 v[4:7], v[148:151], v[242:245], v[4:7]
	v_mfma_f32_16x16x32_bf16 v[0:3], v[156:159], v[242:245], v[0:3]
	s_barrier
	s_setprio 0
	s_add_i32 s33, s33, 2
	s_add_u32 s9, s9, 0x100
	s_addc_u32 s11, s11, 0
	s_cmpk_gt_u32 s33, 0x55
	s_mov_b64 s[12:13], s[14:15]
	s_cbranch_scc0 .LBB0_675
	s_and_b64 vcc, exec, s[4:5]
	s_cbranch_vccz .LBB0_678
	s_barrier

; #define PG8_STAGE(bufoff, gbase, voff) do { _Pragma("unroll") for (int _i = 0; _i < 2; ++_i) \
;         __builtin_amdgcn_global_load_lds((const unsigned*)((const char*)(gbase) + (voff)[_i]), (LAS unsigned*)(lds + (bufoff) + ldsw + _i * 8192), 16, 0, 0); } while (0)
; #define PG8_LDA(dst, b, h) do { _Pragma("unroll") for (int m = 0; m < 4; ++m) _Pragma("unroll") for (int k = 0; k < 2; ++k) dst[m][k] = *(const LAS bf16x8*)(lds + PG8_SA(b, h) + aoff + m * 2048 + k * 1024); } while (0)
; #define PG8_LDB(dst, b, h) do { _Pragma("unroll") for (int n = 0; n < 2; ++n) _Pragma("unroll") for (int k = 0; k < 2; ++k) dst[n][k] = *(const LAS bf16x8*)(lds + PG8_SB(b, h) + boff + n * 2048 + k * 1024); } while (0)
; #define PG8_MMA(ai, bj, At, Bt) do { __builtin_amdgcn_s_setprio(1); _Pragma("unroll") for (int m = 0; m < 4; ++m) _Pragma("unroll") for (int n = 0; n < 2; ++n) _Pragma("unroll") for (int k = 0; k < 2; ++k) \
;         acc[ai][bj][m][n] = __builtin_amdgcn_mfma_f32_16x16x32_bf16(Bt[n][k], At[m][k], acc[ai][bj][m][n], 0, 0, 0); __builtin_amdgcn_s_setprio(0); } while (0)
; template <class Epi, bool PERMA = false, bool DUAL = false, bool ALIGN_EPI = true, bool SP2 = true>
; __device__ __forceinline__ void gemm_phase(LAS unsigned char* lds, const Gemm g, const StaticOrder& S, const Epi& E) {
;     ...
;         const char* nA = has_next ? (const char*)gA_ + (size_t)nxt.pm * tstepA : cA; const char* nB = has_next ? (const char*)gB_ + (size_t)nxt.pn * tstepB : cB;
;         for (int t = 0; t < nt; t += 2) {
;             const bool last = (t == nt - 2);
;             const char* a1 = cA + (size_t)(t + 1) * kstep;
;             const char* a2 = last ? nA : cA + (size_t)(t + 2) * kstep; const char* b2 = last ? nB : cB + (size_t)(t + 2) * kstep;
;             const char* a3 = a2 + kstep; const char* b3 = b2 + kstep;
;             if constexpr (SP2) {
;             PG8_LDB(B0, 0, 0); PG8_LDB(B1, 0, 1); PG8_SCHED; PG8_LDA(At, 0, 0); PG8_STAGE(PG8_SA(1, 1), a1 + hstepA, voffA);
;             PG8_WAIT_V(8); PG8_WAIT_L(0); PG8_BAR; PG8_MMA(0, 0, At, B0); PG8_MMA(0, 1, At, B1); PG8_BAR; PG8_SCHED;
;             PG8_LDA(At, 0, 1); PG8_STAGE(PG8_SB(0, 0), b2, voffB); PG8_STAGE(PG8_SB(0, 1), b2 + hstepB, voffB); PG8_STAGE(PG8_SA(0, 0), a2, voffA);
;             PG8_WAIT_V(8); PG8_WAIT_L(0); PG8_BAR; PG8_MMA(1, 0, At, B0); PG8_MMA(1, 1, At, B1); PG8_BAR; PG8_SCHED;
.LBB0_770:
	s_add_u32 s23, s14, s22
	s_addc_u32 s28, s15, 0
	s_add_u32 s26, s23, 0x100
	s_addc_u32 s27, s28, 0
	s_and_b64 s[24:25], s[20:21], exec
	s_cselect_b32 s25, s9, s27
	s_cselect_b32 s24, s47, s26
	s_add_u32 s22, s16, s22
	s_addc_u32 s26, s17, 0
	s_add_u32 s22, s22, 0x100
	s_addc_u32 s26, s26, 0
	s_add_i32 s57, 0, 0x10000
	s_and_b64 s[20:21], s[20:21], exec
	s_cselect_b32 s27, s7, s26
	s_cselect_b32 s26, s48, s22
	s_add_i32 s21, 0, 0x14000
	s_add_u32 s30, s23, 0x10080
	s_addc_u32 s31, s28, 0
	s_add_i32 s56, s57, s35
	s_add_i32 m0, s36, 0xc000
	s_add_i32 s59, s36, 0xe000
	s_add_i32 s53, s56, 0x2000
	v_add_u32_e32 v138, s57, v140
	s_add_u32 s28, s26, 0x10000
	ds_read_b128 v[142:145], v138
	ds_read_b128 v[146:149], v138 offset:1024
	ds_read_b128 v[150:153], v138 offset:2048
	ds_read_b128 v[154:157], v138 offset:3072
	v_add_u32_e32 v138, s21, v140
	s_addc_u32 s29, s27, 0
	s_add_i32 s55, s21, s35
	ds_read_b128 v[158:161], v138
	ds_read_b128 v[162:165], v138 offset:1024
	ds_read_b128 v[166:169], v138 offset:2048
	ds_read_b128 v[170:173], v138 offset:3072
	s_add_i32 s54, s55, 0x2000
	s_add_i32 s52, 0, 0x18000
	s_add_i32 s51, 0, 0x1c000
	s_add_u32 s22, s24, 0x10000
	s_addc_u32 s23, s25, 0
	s_add_i32 s50, s52, s35
	s_add_i32 s49, s50, 0x2000
	s_add_u32 s20, s26, 0x10080
	s_addc_u32 s21, s27, 0
	s_add_i32 s58, s51, s35
	s_add_i32 s57, s58, 0x2000
	v_lshl_add_u64 v[138:139], s[30:31], 0, v[134:135]
	ds_read_b128 v[174:177], v141
	ds_read_b128 v[178:181], v141 offset:1024
	ds_read_b128 v[182:185], v141 offset:2048
	ds_read_b128 v[186:189], v141 offset:3072
	ds_read_b128 v[206:209], v141 offset:4096
	ds_read_b128 v[210:213], v141 offset:5120
	ds_read_b128 v[214:217], v141 offset:6144
	ds_read_b128 v[218:221], v141 offset:7168
	global_load_lds_dwordx4 v[138:139], off
	v_lshl_add_u64 v[138:139], s[30:31], 0, v[130:131]
	s_mov_b32 m0, s59
	s_nop 0
	global_load_lds_dwordx4 v[138:139], off
	s_waitcnt vmcnt(8)
	s_waitcnt lgkmcnt(0)
	s_setprio 1
	s_barrier
	s_waitcnt lgkmcnt(0)
	v_mfma_f32_16x16x32_bf16 v[124:127], v[142:145], v[174:177], v[124:127]
	v_mfma_f32_16x16x32_bf16 v[120:123], v[150:153], v[174:177], v[120:123]
	v_mfma_f32_16x16x32_bf16 v[116:119], v[142:145], v[182:185], v[116:119]
	v_mfma_f32_16x16x32_bf16 v[108:111], v[150:153], v[182:185], v[108:111]
	v_mfma_f32_16x16x32_bf16 v[100:103], v[142:145], v[206:209], v[100:103]
	v_mfma_f32_16x16x32_bf16 v[92:95], v[150:153], v[206:209], v[92:95]
	v_mfma_f32_16x16x32_bf16 v[84:87], v[142:145], v[214:217], v[84:87]
	v_mfma_f32_16x16x32_bf16 v[76:79], v[150:153], v[214:217], v[76:79]
	v_mfma_f32_16x16x32_bf16 v[124:127], v[146:149], v[178:181], v[124:127]
	v_mfma_f32_16x16x32_bf16 v[120:123], v[154:157], v[178:181], v[120:123]
	v_mfma_f32_16x16x32_bf16 v[116:119], v[146:149], v[186:189], v[116:119]
	v_mfma_f32_16x16x32_bf16 v[108:111], v[154:157], v[186:189], v[108:111]
	v_mfma_f32_16x16x32_bf16 v[100:103], v[146:149], v[210:213], v[100:103]
	v_mfma_f32_16x16x32_bf16 v[92:95], v[154:157], v[210:213], v[92:95]
	v_mfma_f32_16x16x32_bf16 v[84:87], v[146:149], v[218:221], v[84:87]
	v_mfma_f32_16x16x32_bf16 v[76:79], v[154:157], v[218:221], v[76:79]
	v_mfma_f32_16x16x32_bf16 v[112:115], v[158:161], v[174:177], v[112:115]
	v_mfma_f32_16x16x32_bf16 v[104:107], v[166:169], v[174:177], v[104:107]
	v_mfma_f32_16x16x32_bf16 v[96:99], v[158:161], v[182:185], v[96:99]
	v_mfma_f32_16x16x32_bf16 v[88:91], v[166:169], v[182:185], v[88:91]
	v_mfma_f32_16x16x32_bf16 v[80:83], v[158:161], v[206:209], v[80:83]
	v_mfma_f32_16x16x32_bf16 v[72:75], v[166:169], v[206:209], v[72:75]
	v_mfma_f32_16x16x32_bf16 v[68:71], v[158:161], v[214:217], v[68:71]
	v_mfma_f32_16x16x32_bf16 v[64:67], v[166:169], v[214:217], v[64:67]
	v_mfma_f32_16x16x32_bf16 v[112:115], v[162:165], v[178:181], v[112:115]
	v_mfma_f32_16x16x32_bf16 v[104:107], v[170:173], v[178:181], v[104:107]
	v_mfma_f32_16x16x32_bf16 v[96:99], v[162:165], v[186:189], v[96:99]
	v_mfma_f32_16x16x32_bf16 v[88:91], v[170:173], v[186:189], v[88:91]
	v_mfma_f32_16x16x32_bf16 v[80:83], v[162:165], v[210:213], v[80:83]
	v_mfma_f32_16x16x32_bf16 v[72:75], v[170:173], v[210:213], v[72:75]
	v_mfma_f32_16x16x32_bf16 v[68:71], v[162:165], v[218:221], v[68:71]
	v_mfma_f32_16x16x32_bf16 v[64:67], v[170:173], v[218:221], v[64:67]
	s_barrier
	s_setprio 0
	s_mov_b32 m0, s56
	v_lshl_add_u64 v[138:139], s[26:27], 0, v[132:133]
	ds_read_b128 v[174:177], v141 offset:16384
	ds_read_b128 v[178:181], v141 offset:17408
	ds_read_b128 v[182:185], v141 offset:18432
	ds_read_b128 v[186:189], v141 offset:19456
	ds_read_b128 v[206:209], v141 offset:20480
	ds_read_b128 v[210:213], v141 offset:21504
	ds_read_b128 v[214:217], v141 offset:22528
	ds_read_b128 v[218:221], v141 offset:23552
	global_load_lds_dwordx4 v[138:139], off
	v_lshl_add_u64 v[190:191], s[26:27], 0, v[128:129]
	s_mov_b32 m0, s53
	v_lshl_add_u64 v[194:195], s[28:29], 0, v[132:133]
	global_load_lds_dwordx4 v[190:191], off
	s_mov_b32 m0, s55
	v_lshl_add_u64 v[196:197], s[24:25], 0, v[130:131]
	global_load_lds_dwordx4 v[194:195], off
	v_lshl_add_u64 v[194:195], s[28:29], 0, v[128:129]
	s_mov_b32 m0, s54
	s_nop 0
	global_load_lds_dwordx4 v[194:195], off
	v_lshl_add_u64 v[194:195], s[24:25], 0, v[134:135]
	s_mov_b32 m0, s36
	s_nop 0
	global_load_lds_dwordx4 v[194:195], off
	s_mov_b32 m0, s37
	s_nop 0
	global_load_lds_dwordx4 v[196:197], off
	s_waitcnt vmcnt(8)
	s_waitcnt lgkmcnt(0)
	s_setprio 1
	s_barrier
; #define PG8_STAGE(bufoff, gbase, voff) do { _Pragma("unroll") for (int _i = 0; _i < 2; ++_i) \
;         __builtin_amdgcn_global_load_lds((const unsigned*)((const char*)(gbase) + (voff)[_i]), (LAS unsigned*)(lds + (bufoff) + ldsw + _i * 8192), 16, 0, 0); } while (0)
; #define PG8_LDA(dst, b, h) do { _Pragma("unroll") for (int m = 0; m < 4; ++m) _Pragma("unroll") for (int k = 0; k < 2; ++k) dst[m][k] = *(const LAS bf16x8*)(lds + PG8_SA(b, h) + aoff + m * 2048 + k * 1024); } while (0)
; #define PG8_LDB(dst, b, h) do { _Pragma("unroll") for (int n = 0; n < 2; ++n) _Pragma("unroll") for (int k = 0; k < 2; ++k) dst[n][k] = *(const LAS bf16x8*)(lds + PG8_SB(b, h) + boff + n * 2048 + k * 1024); } while (0)
; #define PG8_MMA(ai, bj, At, Bt) do { __builtin_amdgcn_s_setprio(1); _Pragma("unroll") for (int m = 0; m < 4; ++m) _Pragma("unroll") for (int n = 0; n < 2; ++n) _Pragma("unroll") for (int k = 0; k < 2; ++k) \
;         acc[ai][bj][m][n] = __builtin_amdgcn_mfma_f32_16x16x32_bf16(Bt[n][k], At[m][k], acc[ai][bj][m][n], 0, 0, 0); __builtin_amdgcn_s_setprio(0); } while (0)
; #define PG8_WAIT_V(n) asm volatile("s_waitcnt vmcnt(" #n ")" ::: "memory")
; #define PG8_WAIT_L(n) asm volatile("s_waitcnt lgkmcnt(" #n ")" ::: "memory")
; #define PG8_BAR __builtin_amdgcn_s_barrier()
; #define PG8_SCHED __builtin_amdgcn_sched_barrier(0)
; template <class Epi, bool PERMA = false, bool DUAL = false, bool ALIGN_EPI = true, bool SP2 = true>
; __device__ __forceinline__ void gemm_phase(LAS unsigned char* lds, const Gemm g, const StaticOrder& S, const Epi& E) {
;     ...
;             PG8_WAIT_V(8); PG8_WAIT_L(0); PG8_BAR; PG8_MMA(1, 0, At, B0); PG8_MMA(1, 1, At, B1); PG8_BAR; PG8_SCHED;
;             PG8_LDB(B0, 1, 0); PG8_LDB(B1, 1, 1); PG8_SCHED; PG8_LDA(At, 1, 0); PG8_STAGE(PG8_SA(0, 1), a2 + hstepA, voffA);
;             PG8_WAIT_V(8); PG8_WAIT_L(0); PG8_BAR; PG8_MMA(0, 0, At, B0); PG8_MMA(0, 1, At, B1); PG8_BAR; PG8_SCHED;
	s_waitcnt lgkmcnt(0)
	v_mfma_f32_16x16x32_bf16 v[60:63], v[142:145], v[174:177], v[60:63]
	v_mfma_f32_16x16x32_bf16 v[56:59], v[150:153], v[174:177], v[56:59]
	v_mfma_f32_16x16x32_bf16 v[52:55], v[142:145], v[182:185], v[52:55]
	v_mfma_f32_16x16x32_bf16 v[44:47], v[150:153], v[182:185], v[44:47]
	v_mfma_f32_16x16x32_bf16 v[36:39], v[142:145], v[206:209], v[36:39]
	v_mfma_f32_16x16x32_bf16 v[28:31], v[150:153], v[206:209], v[28:31]
	v_mfma_f32_16x16x32_bf16 v[20:23], v[142:145], v[214:217], v[20:23]
	v_mfma_f32_16x16x32_bf16 v[12:15], v[150:153], v[214:217], v[12:15]
	v_mfma_f32_16x16x32_bf16 v[60:63], v[146:149], v[178:181], v[60:63]
	v_mfma_f32_16x16x32_bf16 v[56:59], v[154:157], v[178:181], v[56:59]
	v_mfma_f32_16x16x32_bf16 v[52:55], v[146:149], v[186:189], v[52:55]
	v_mfma_f32_16x16x32_bf16 v[44:47], v[154:157], v[186:189], v[44:47]
	v_mfma_f32_16x16x32_bf16 v[36:39], v[146:149], v[210:213], v[36:39]
	v_mfma_f32_16x16x32_bf16 v[28:31], v[154:157], v[210:213], v[28:31]
	v_mfma_f32_16x16x32_bf16 v[20:23], v[146:149], v[218:221], v[20:23]
	v_mfma_f32_16x16x32_bf16 v[12:15], v[154:157], v[218:221], v[12:15]
	v_mfma_f32_16x16x32_bf16 v[48:51], v[158:161], v[174:177], v[48:51]
	v_mfma_f32_16x16x32_bf16 v[40:43], v[166:169], v[174:177], v[40:43]
	v_mfma_f32_16x16x32_bf16 v[32:35], v[158:161], v[182:185], v[32:35]
	v_mfma_f32_16x16x32_bf16 v[24:27], v[166:169], v[182:185], v[24:27]
	v_mfma_f32_16x16x32_bf16 v[16:19], v[158:161], v[206:209], v[16:19]
	v_mfma_f32_16x16x32_bf16 v[8:11], v[166:169], v[206:209], v[8:11]
	v_mfma_f32_16x16x32_bf16 v[4:7], v[158:161], v[214:217], v[4:7]
	v_mfma_f32_16x16x32_bf16 v[0:3], v[166:169], v[214:217], v[0:3]
	v_mfma_f32_16x16x32_bf16 v[48:51], v[162:165], v[178:181], v[48:51]
	v_mfma_f32_16x16x32_bf16 v[40:43], v[170:173], v[178:181], v[40:43]
	v_mfma_f32_16x16x32_bf16 v[32:35], v[162:165], v[186:189], v[32:35]
	v_mfma_f32_16x16x32_bf16 v[24:27], v[170:173], v[186:189], v[24:27]
	v_mfma_f32_16x16x32_bf16 v[16:19], v[162:165], v[210:213], v[16:19]
	v_mfma_f32_16x16x32_bf16 v[8:11], v[170:173], v[210:213], v[8:11]
	v_mfma_f32_16x16x32_bf16 v[4:7], v[162:165], v[218:221], v[4:7]
	v_mfma_f32_16x16x32_bf16 v[0:3], v[170:173], v[218:221], v[0:3]
	s_barrier
	s_setprio 0
	v_add_u32_e32 v154, s52, v140
	v_add_u32_e32 v170, s51, v140
	ds_read_b128 v[142:145], v154
	ds_read_b128 v[146:149], v154 offset:1024
	ds_read_b128 v[150:153], v154 offset:2048
	ds_read_b128 v[154:157], v154 offset:3072
	ds_read_b128 v[158:161], v170
	ds_read_b128 v[162:165], v170 offset:1024
	ds_read_b128 v[166:169], v170 offset:2048
	ds_read_b128 v[170:173], v170 offset:3072
	s_mov_b32 m0, s38
	v_lshl_add_u64 v[222:223], s[22:23], 0, v[134:135]
	ds_read_b128 v[174:177], v141 offset:32768
	ds_read_b128 v[178:181], v141 offset:33792
	ds_read_b128 v[182:185], v141 offset:34816
	ds_read_b128 v[186:189], v141 offset:35840
	ds_read_b128 v[206:209], v141 offset:36864
	ds_read_b128 v[210:213], v141 offset:37888
	ds_read_b128 v[214:217], v141 offset:38912
	ds_read_b128 v[218:221], v141 offset:39936
	global_load_lds_dwordx4 v[222:223], off
	v_lshl_add_u64 v[222:223], s[22:23], 0, v[130:131]
	s_mov_b32 m0, s39
	s_nop 0
	global_load_lds_dwordx4 v[222:223], off
	s_waitcnt vmcnt(8)
	s_waitcnt lgkmcnt(0)
	s_setprio 1
	s_barrier
	s_waitcnt lgkmcnt(0)
	v_mfma_f32_16x16x32_bf16 v[124:127], v[142:145], v[174:177], v[124:127]
	v_mfma_f32_16x16x32_bf16 v[120:123], v[150:153], v[174:177], v[120:123]
	v_mfma_f32_16x16x32_bf16 v[116:119], v[142:145], v[182:185], v[116:119]
	v_mfma_f32_16x16x32_bf16 v[108:111], v[150:153], v[182:185], v[108:111]
	v_mfma_f32_16x16x32_bf16 v[100:103], v[142:145], v[206:209], v[100:103]
	v_mfma_f32_16x16x32_bf16 v[92:95], v[150:153], v[206:209], v[92:95]
	v_mfma_f32_16x16x32_bf16 v[84:87], v[142:145], v[214:217], v[84:87]
	v_mfma_f32_16x16x32_bf16 v[76:79], v[150:153], v[214:217], v[76:79]
	v_mfma_f32_16x16x32_bf16 v[124:127], v[146:149], v[178:181], v[124:127]
	v_mfma_f32_16x16x32_bf16 v[120:123], v[154:157], v[178:181], v[120:123]
	v_mfma_f32_16x16x32_bf16 v[116:119], v[146:149], v[186:189], v[116:119]
	v_mfma_f32_16x16x32_bf16 v[108:111], v[154:157], v[186:189], v[108:111]
	v_mfma_f32_16x16x32_bf16 v[100:103], v[146:149], v[210:213], v[100:103]
	v_mfma_f32_16x16x32_bf16 v[92:95], v[154:157], v[210:213], v[92:95]
	v_mfma_f32_16x16x32_bf16 v[84:87], v[146:149], v[218:221], v[84:87]
	v_mfma_f32_16x16x32_bf16 v[76:79], v[154:157], v[218:221], v[76:79]
	v_mfma_f32_16x16x32_bf16 v[112:115], v[158:161], v[174:177], v[112:115]
	v_mfma_f32_16x16x32_bf16 v[104:107], v[166:169], v[174:177], v[104:107]
	v_mfma_f32_16x16x32_bf16 v[96:99], v[158:161], v[182:185], v[96:99]
	v_mfma_f32_16x16x32_bf16 v[88:91], v[166:169], v[182:185], v[88:91]
	v_mfma_f32_16x16x32_bf16 v[80:83], v[158:161], v[206:209], v[80:83]
	v_mfma_f32_16x16x32_bf16 v[72:75], v[166:169], v[206:209], v[72:75]
	v_mfma_f32_16x16x32_bf16 v[68:71], v[158:161], v[214:217], v[68:71]
	v_mfma_f32_16x16x32_bf16 v[64:67], v[166:169], v[214:217], v[64:67]
	v_mfma_f32_16x16x32_bf16 v[112:115], v[162:165], v[178:181], v[112:115]
	v_mfma_f32_16x16x32_bf16 v[104:107], v[170:173], v[178:181], v[104:107]
	v_mfma_f32_16x16x32_bf16 v[96:99], v[162:165], v[186:189], v[96:99]
	v_mfma_f32_16x16x32_bf16 v[88:91], v[170:173], v[186:189], v[88:91]
	v_mfma_f32_16x16x32_bf16 v[80:83], v[162:165], v[210:213], v[80:83]
	v_mfma_f32_16x16x32_bf16 v[72:75], v[170:173], v[210:213], v[72:75]
	v_mfma_f32_16x16x32_bf16 v[68:71], v[162:165], v[218:221], v[68:71]
	v_mfma_f32_16x16x32_bf16 v[64:67], v[170:173], v[218:221], v[64:67]
	s_barrier
; #define PG8_STAGE(bufoff, gbase, voff) do { _Pragma("unroll") for (int _i = 0; _i < 2; ++_i) \
;         __builtin_amdgcn_global_load_lds((const unsigned*)((const char*)(gbase) + (voff)[_i]), (LAS unsigned*)(lds + (bufoff) + ldsw + _i * 8192), 16, 0, 0); } while (0)
; #define PG8_LDA(dst, b, h) do { _Pragma("unroll") for (int m = 0; m < 4; ++m) _Pragma("unroll") for (int k = 0; k < 2; ++k) dst[m][k] = *(const LAS bf16x8*)(lds + PG8_SA(b, h) + aoff + m * 2048 + k * 1024); } while (0)
; #define PG8_MMA(ai, bj, At, Bt) do { __builtin_amdgcn_s_setprio(1); _Pragma("unroll") for (int m = 0; m < 4; ++m) _Pragma("unroll") for (int n = 0; n < 2; ++n) _Pragma("unroll") for (int k = 0; k < 2; ++k) \
;         acc[ai][bj][m][n] = __builtin_amdgcn_mfma_f32_16x16x32_bf16(Bt[n][k], At[m][k], acc[ai][bj][m][n], 0, 0, 0); __builtin_amdgcn_s_setprio(0); } while (0)
; #define PG8_WAIT_V(n) asm volatile("s_waitcnt vmcnt(" #n ")" ::: "memory")
; #define PG8_WAIT_L(n) asm volatile("s_waitcnt lgkmcnt(" #n ")" ::: "memory")
; #define PG8_BAR __builtin_amdgcn_s_barrier()
; #define PG8_SCHED __builtin_amdgcn_sched_barrier(0)
; template <class Epi, bool PERMA = false, bool DUAL = false, bool ALIGN_EPI = true, bool SP2 = true>
; __device__ __forceinline__ void gemm_phase(LAS unsigned char* lds, const Gemm g, const StaticOrder& S, const Epi& E) {
;     ...
;             PG8_LDA(At, 1, 1); PG8_STAGE(PG8_SB(1, 0), b3, voffB); PG8_STAGE(PG8_SB(1, 1), b3 + hstepB, voffB); PG8_STAGE(PG8_SA(1, 0), a3, voffA);
;             PG8_WAIT_V(8); PG8_WAIT_L(0); PG8_BAR; PG8_MMA(1, 0, At, B0); PG8_MMA(1, 1, At, B1); PG8_BAR; PG8_SCHED;
;     ...
;         if constexpr (ALIGN_EPI) { if (wr == 0) PG8_BAR; }
	s_setprio 0
	s_mov_b32 m0, s50
	v_lshl_add_u64 v[138:139], v[138:139], 0, s[68:69]
	ds_read_b128 v[174:177], v141 offset:49152
	ds_read_b128 v[178:181], v141 offset:50176
	ds_read_b128 v[182:185], v141 offset:51200
	ds_read_b128 v[186:189], v141 offset:52224
	ds_read_b128 v[206:209], v141 offset:53248
	ds_read_b128 v[210:213], v141 offset:54272
	ds_read_b128 v[214:217], v141 offset:55296
	ds_read_b128 v[218:221], v141 offset:56320
	global_load_lds_dwordx4 v[138:139], off
	v_lshl_add_u64 v[138:139], v[190:191], 0, s[68:69]
	s_mov_b32 m0, s49
	s_nop 0
	global_load_lds_dwordx4 v[138:139], off
	v_lshl_add_u64 v[138:139], s[20:21], 0, v[132:133]
	s_mov_b32 m0, s58
	s_nop 0
	global_load_lds_dwordx4 v[138:139], off
	v_lshl_add_u64 v[138:139], s[20:21], 0, v[128:129]
	s_mov_b32 m0, s57
	s_nop 0
	global_load_lds_dwordx4 v[138:139], off
	v_lshl_add_u64 v[138:139], v[194:195], 0, s[68:69]
	s_mov_b32 m0, s42
	s_nop 0
	global_load_lds_dwordx4 v[138:139], off
	v_lshl_add_u64 v[138:139], v[196:197], 0, s[68:69]
	s_mov_b32 m0, s43
	s_nop 0
	global_load_lds_dwordx4 v[138:139], off
	s_waitcnt vmcnt(8)
	s_waitcnt lgkmcnt(0)
	s_setprio 1
	s_barrier
	s_waitcnt lgkmcnt(0)
	v_mfma_f32_16x16x32_bf16 v[60:63], v[142:145], v[174:177], v[60:63]
	v_mfma_f32_16x16x32_bf16 v[56:59], v[150:153], v[174:177], v[56:59]
	v_mfma_f32_16x16x32_bf16 v[52:55], v[142:145], v[182:185], v[52:55]
	v_mfma_f32_16x16x32_bf16 v[44:47], v[150:153], v[182:185], v[44:47]
	v_mfma_f32_16x16x32_bf16 v[36:39], v[142:145], v[206:209], v[36:39]
	v_mfma_f32_16x16x32_bf16 v[28:31], v[150:153], v[206:209], v[28:31]
	v_mfma_f32_16x16x32_bf16 v[20:23], v[142:145], v[214:217], v[20:23]
	v_mfma_f32_16x16x32_bf16 v[12:15], v[150:153], v[214:217], v[12:15]
	v_mfma_f32_16x16x32_bf16 v[60:63], v[146:149], v[178:181], v[60:63]
	v_mfma_f32_16x16x32_bf16 v[56:59], v[154:157], v[178:181], v[56:59]
	v_mfma_f32_16x16x32_bf16 v[52:55], v[146:149], v[186:189], v[52:55]
	v_mfma_f32_16x16x32_bf16 v[44:47], v[154:157], v[186:189], v[44:47]
	v_mfma_f32_16x16x32_bf16 v[36:39], v[146:149], v[210:213], v[36:39]
	v_mfma_f32_16x16x32_bf16 v[28:31], v[154:157], v[210:213], v[28:31]
	v_mfma_f32_16x16x32_bf16 v[20:23], v[146:149], v[218:221], v[20:23]
	v_mfma_f32_16x16x32_bf16 v[12:15], v[154:157], v[218:221], v[12:15]
	v_mfma_f32_16x16x32_bf16 v[48:51], v[158:161], v[174:177], v[48:51]
	v_mfma_f32_16x16x32_bf16 v[40:43], v[166:169], v[174:177], v[40:43]
	v_mfma_f32_16x16x32_bf16 v[32:35], v[158:161], v[182:185], v[32:35]
	v_mfma_f32_16x16x32_bf16 v[24:27], v[166:169], v[182:185], v[24:27]
	v_mfma_f32_16x16x32_bf16 v[16:19], v[158:161], v[206:209], v[16:19]
	v_mfma_f32_16x16x32_bf16 v[8:11], v[166:169], v[206:209], v[8:11]
	v_mfma_f32_16x16x32_bf16 v[4:7], v[158:161], v[214:217], v[4:7]
	v_mfma_f32_16x16x32_bf16 v[0:3], v[166:169], v[214:217], v[0:3]
	v_mfma_f32_16x16x32_bf16 v[48:51], v[162:165], v[178:181], v[48:51]
	v_mfma_f32_16x16x32_bf16 v[40:43], v[170:173], v[178:181], v[40:43]
	v_mfma_f32_16x16x32_bf16 v[32:35], v[162:165], v[186:189], v[32:35]
	v_mfma_f32_16x16x32_bf16 v[24:27], v[170:173], v[186:189], v[24:27]
	v_mfma_f32_16x16x32_bf16 v[16:19], v[162:165], v[210:213], v[16:19]
	v_mfma_f32_16x16x32_bf16 v[8:11], v[170:173], v[210:213], v[8:11]
	v_mfma_f32_16x16x32_bf16 v[4:7], v[162:165], v[218:221], v[4:7]
	v_mfma_f32_16x16x32_bf16 v[0:3], v[170:173], v[218:221], v[0:3]
	s_barrier
	s_setprio 0
	s_movk_i32 s22, 0x100
	s_andn2_b64 vcc, exec, s[18:19]
	s_mov_b64 s[20:21], -1
	s_mov_b64 s[18:19], 0
	s_cbranch_vccz .LBB0_770
	s_and_b64 vcc, exec, s[4:5]
	s_cbranch_vccz .LBB0_773
	s_barrier

; #define PG8_STAGE(bufoff, gbase, voff) do { _Pragma("unroll") for (int _i = 0; _i < 2; ++_i) \
;         __builtin_amdgcn_global_load_lds((const unsigned*)((const char*)(gbase) + (voff)[_i]), (LAS unsigned*)(lds + (bufoff) + ldsw + _i * 8192), 16, 0, 0); } while (0)
; #define PG8_LDA(dst, b, h) do { _Pragma("unroll") for (int m = 0; m < 4; ++m) _Pragma("unroll") for (int k = 0; k < 2; ++k) dst[m][k] = *(const LAS bf16x8*)(lds + PG8_SA(b, h) + aoff + m * 2048 + k * 1024); } while (0)
; #define PG8_LDB(dst, b, h) do { _Pragma("unroll") for (int n = 0; n < 2; ++n) _Pragma("unroll") for (int k = 0; k < 2; ++k) dst[n][k] = *(const LAS bf16x8*)(lds + PG8_SB(b, h) + boff + n * 2048 + k * 1024); } while (0)
; #define PG8_MMA(ai, bj, At, Bt) do { __builtin_amdgcn_s_setprio(1); _Pragma("unroll") for (int m = 0; m < 4; ++m) _Pragma("unroll") for (int n = 0; n < 2; ++n) _Pragma("unroll") for (int k = 0; k < 2; ++k) \
;         acc[ai][bj][m][n] = __builtin_amdgcn_mfma_f32_16x16x32_bf16(Bt[n][k], At[m][k], acc[ai][bj][m][n], 0, 0, 0); __builtin_amdgcn_s_setprio(0); } while (0)
; template <class Epi, bool PERMA = false, bool DUAL = false, bool ALIGN_EPI = true, bool SP2 = true>
; __device__ __forceinline__ void gemm_phase(LAS unsigned char* lds, const Gemm g, const StaticOrder& S, const Epi& E) {
;     ...
;         const char* nA = has_next ? (const char*)gA_ + (size_t)nxt.pm * tstepA : cA; const char* nB = has_next ? (const char*)gB_ + (size_t)nxt.pn * tstepB : cB;
;         for (int t = 0; t < nt; t += 2) {
;             const bool last = (t == nt - 2);
;             const char* a1 = cA + (size_t)(t + 1) * kstep;
;             const char* a2 = last ? nA : cA + (size_t)(t + 2) * kstep; const char* b2 = last ? nB : cB + (size_t)(t + 2) * kstep;
;             const char* a3 = a2 + kstep; const char* b3 = b2 + kstep;
;             if constexpr (SP2) {
;             PG8_LDB(B0, 0, 0); PG8_LDB(B1, 0, 1); PG8_SCHED; PG8_LDA(At, 0, 0); PG8_STAGE(PG8_SA(1, 1), a1 + hstepA, voffA);
;             PG8_WAIT_V(8); PG8_WAIT_L(0); PG8_BAR; PG8_MMA(0, 0, At, B0); PG8_MMA(0, 1, At, B1); PG8_BAR; PG8_SCHED;
;             PG8_LDA(At, 0, 1); PG8_STAGE(PG8_SB(0, 0), b2, voffB); PG8_STAGE(PG8_SB(0, 1), b2 + hstepB, voffB); PG8_STAGE(PG8_SA(0, 0), a2, voffA);
;             PG8_WAIT_V(8); PG8_WAIT_L(0); PG8_BAR; PG8_MMA(1, 0, At, B0); PG8_MMA(1, 1, At, B1); PG8_BAR; PG8_SCHED;
.LBB0_790:
	s_add_u32 s14, s12, 0xfff80080
	s_addc_u32 s15, s13, -1
	s_add_i32 s36, 0, 0x10000
	s_cmp_eq_u32 s35, 28
	s_cselect_b32 s17, s7, s15
	s_cselect_b32 s16, s30, s14
	s_cselect_b32 s15, s5, s34
	s_cselect_b32 s14, s31, s33
	s_add_i32 s40, 0, 0x14000
	v_add_u32_e32 v140, s36, v190
	v_add_u32_e32 v156, s40, v190
	ds_read_b128 v[120:123], v140
	ds_read_b128 v[128:131], v140 offset:1024
	ds_read_b128 v[132:135], v140 offset:2048
	ds_read_b128 v[140:143], v140 offset:3072
	ds_read_b128 v[144:147], v156
	ds_read_b128 v[148:151], v156 offset:1024
	ds_read_b128 v[152:155], v156 offset:2048
	ds_read_b128 v[156:159], v156 offset:3072
	v_lshl_add_u64 v[194:195], s[12:13], 0, v[174:175]
	s_add_i32 m0, s19, 0xc000
	ds_read_b128 v[178:181], v191
	ds_read_b128 v[182:185], v191 offset:1024
	ds_read_b128 v[186:189], v191 offset:2048
	ds_read_b128 v[206:209], v191 offset:3072
	ds_read_b128 v[210:213], v191 offset:4096
	ds_read_b128 v[214:217], v191 offset:5120
	ds_read_b128 v[218:221], v191 offset:6144
	ds_read_b128 v[222:225], v191 offset:7168
	global_load_lds_dwordx4 v[194:195], off
	v_lshl_add_u64 v[194:195], s[12:13], 0, v[176:177]
	s_add_i32 m0, s19, 0xe000
	s_nop 0
	global_load_lds_dwordx4 v[194:195], off
	s_waitcnt vmcnt(8)
	s_waitcnt lgkmcnt(0)
	s_setprio 1
	s_barrier
	s_waitcnt lgkmcnt(0)
	v_mfma_f32_16x16x32_bf16 v[136:139], v[120:123], v[178:181], v[136:139]
	v_mfma_f32_16x16x32_bf16 v[124:127], v[132:135], v[178:181], v[124:127]
	v_mfma_f32_16x16x32_bf16 v[108:111], v[120:123], v[186:189], v[108:111]
	v_mfma_f32_16x16x32_bf16 v[104:107], v[132:135], v[186:189], v[104:107]
	v_mfma_f32_16x16x32_bf16 v[92:95], v[120:123], v[210:213], v[92:95]
	v_mfma_f32_16x16x32_bf16 v[88:91], v[132:135], v[210:213], v[88:91]
	v_mfma_f32_16x16x32_bf16 v[76:79], v[120:123], v[218:221], v[76:79]
	v_mfma_f32_16x16x32_bf16 v[72:75], v[132:135], v[218:221], v[72:75]
	v_mfma_f32_16x16x32_bf16 v[136:139], v[128:131], v[182:185], v[136:139]
	v_mfma_f32_16x16x32_bf16 v[124:127], v[140:143], v[182:185], v[124:127]
	v_mfma_f32_16x16x32_bf16 v[108:111], v[128:131], v[206:209], v[108:111]
	v_mfma_f32_16x16x32_bf16 v[104:107], v[140:143], v[206:209], v[104:107]
	v_mfma_f32_16x16x32_bf16 v[92:95], v[128:131], v[214:217], v[92:95]
	v_mfma_f32_16x16x32_bf16 v[88:91], v[140:143], v[214:217], v[88:91]
	v_mfma_f32_16x16x32_bf16 v[76:79], v[128:131], v[222:225], v[76:79]
	v_mfma_f32_16x16x32_bf16 v[72:75], v[140:143], v[222:225], v[72:75]
	v_mfma_f32_16x16x32_bf16 v[116:119], v[144:147], v[178:181], v[116:119]
	v_mfma_f32_16x16x32_bf16 v[112:115], v[152:155], v[178:181], v[112:115]
	v_mfma_f32_16x16x32_bf16 v[100:103], v[144:147], v[186:189], v[100:103]
	v_mfma_f32_16x16x32_bf16 v[96:99], v[152:155], v[186:189], v[96:99]
	v_mfma_f32_16x16x32_bf16 v[84:87], v[144:147], v[210:213], v[84:87]
	v_mfma_f32_16x16x32_bf16 v[80:83], v[152:155], v[210:213], v[80:83]
	v_mfma_f32_16x16x32_bf16 v[68:71], v[144:147], v[218:221], v[68:71]
	v_mfma_f32_16x16x32_bf16 v[64:67], v[152:155], v[218:221], v[64:67]
	v_mfma_f32_16x16x32_bf16 v[116:119], v[148:151], v[182:185], v[116:119]
	v_mfma_f32_16x16x32_bf16 v[112:115], v[156:159], v[182:185], v[112:115]
	v_mfma_f32_16x16x32_bf16 v[100:103], v[148:151], v[206:209], v[100:103]
	v_mfma_f32_16x16x32_bf16 v[96:99], v[156:159], v[206:209], v[96:99]
	v_mfma_f32_16x16x32_bf16 v[84:87], v[148:151], v[214:217], v[84:87]
	v_mfma_f32_16x16x32_bf16 v[80:83], v[156:159], v[214:217], v[80:83]
	v_mfma_f32_16x16x32_bf16 v[68:71], v[148:151], v[222:225], v[68:71]
	v_mfma_f32_16x16x32_bf16 v[64:67], v[156:159], v[222:225], v[64:67]
	s_barrier
	s_setprio 0
	s_add_i32 s36, s36, s18
	v_lshl_add_u64 v[194:195], s[14:15], 0, v[164:165]
	s_mov_b32 m0, s36
	ds_read_b128 v[178:181], v191 offset:16384
	ds_read_b128 v[182:185], v191 offset:17408
	ds_read_b128 v[186:189], v191 offset:18432
	ds_read_b128 v[206:209], v191 offset:19456
	ds_read_b128 v[210:213], v191 offset:20480
	ds_read_b128 v[214:217], v191 offset:21504
	ds_read_b128 v[218:221], v191 offset:22528
	ds_read_b128 v[222:225], v191 offset:23552
	global_load_lds_dwordx4 v[194:195], off
	s_add_i32 m0, s36, 0x2000
	s_add_u32 s36, s14, 0x80000
	v_lshl_add_u64 v[196:197], s[14:15], 0, v[160:161]
	s_addc_u32 s37, s15, 0
	s_add_i32 s40, s40, s18
	global_load_lds_dwordx4 v[196:197], off
	v_lshl_add_u64 v[226:227], s[36:37], 0, v[164:165]
	s_mov_b32 m0, s40
	v_lshl_add_u64 v[228:229], s[16:17], 0, v[162:163]
	global_load_lds_dwordx4 v[226:227], off
	v_lshl_add_u64 v[226:227], s[36:37], 0, v[160:161]
	s_add_i32 m0, s40, 0x2000
	s_nop 0
	global_load_lds_dwordx4 v[226:227], off
	v_lshl_add_u64 v[226:227], s[16:17], 0, v[166:167]
	s_mov_b32 m0, s19
	s_nop 0
	global_load_lds_dwordx4 v[226:227], off
	s_mov_b32 m0, s20
	s_nop 0
	global_load_lds_dwordx4 v[228:229], off
	s_waitcnt vmcnt(8)
	s_waitcnt lgkmcnt(0)
	s_setprio 1
	s_barrier
; #define PG8_STAGE(bufoff, gbase, voff) do { _Pragma("unroll") for (int _i = 0; _i < 2; ++_i) \
;         __builtin_amdgcn_global_load_lds((const unsigned*)((const char*)(gbase) + (voff)[_i]), (LAS unsigned*)(lds + (bufoff) + ldsw + _i * 8192), 16, 0, 0); } while (0)
; #define PG8_LDA(dst, b, h) do { _Pragma("unroll") for (int m = 0; m < 4; ++m) _Pragma("unroll") for (int k = 0; k < 2; ++k) dst[m][k] = *(const LAS bf16x8*)(lds + PG8_SA(b, h) + aoff + m * 2048 + k * 1024); } while (0)
; #define PG8_LDB(dst, b, h) do { _Pragma("unroll") for (int n = 0; n < 2; ++n) _Pragma("unroll") for (int k = 0; k < 2; ++k) dst[n][k] = *(const LAS bf16x8*)(lds + PG8_SB(b, h) + boff + n * 2048 + k * 1024); } while (0)
; #define PG8_MMA(ai, bj, At, Bt) do { __builtin_amdgcn_s_setprio(1); _Pragma("unroll") for (int m = 0; m < 4; ++m) _Pragma("unroll") for (int n = 0; n < 2; ++n) _Pragma("unroll") for (int k = 0; k < 2; ++k) \
;         acc[ai][bj][m][n] = __builtin_amdgcn_mfma_f32_16x16x32_bf16(Bt[n][k], At[m][k], acc[ai][bj][m][n], 0, 0, 0); __builtin_amdgcn_s_setprio(0); } while (0)
; #define PG8_WAIT_V(n) asm volatile("s_waitcnt vmcnt(" #n ")" ::: "memory")
; #define PG8_WAIT_L(n) asm volatile("s_waitcnt lgkmcnt(" #n ")" ::: "memory")
; #define PG8_BAR __builtin_amdgcn_s_barrier()
; #define PG8_SCHED __builtin_amdgcn_sched_barrier(0)
; template <class Epi, bool PERMA = false, bool DUAL = false, bool ALIGN_EPI = true, bool SP2 = true>
; __device__ __forceinline__ void gemm_phase(LAS unsigned char* lds, const Gemm g, const StaticOrder& S, const Epi& E) {
;     ...
;             PG8_WAIT_V(8); PG8_WAIT_L(0); PG8_BAR; PG8_MMA(1, 0, At, B0); PG8_MMA(1, 1, At, B1); PG8_BAR; PG8_SCHED;
;             PG8_LDB(B0, 1, 0); PG8_LDB(B1, 1, 1); PG8_SCHED; PG8_LDA(At, 1, 0); PG8_STAGE(PG8_SA(0, 1), a2 + hstepA, voffA);
;             PG8_WAIT_V(8); PG8_WAIT_L(0); PG8_BAR; PG8_MMA(0, 0, At, B0); PG8_MMA(0, 1, At, B1); PG8_BAR; PG8_SCHED;
	s_waitcnt lgkmcnt(0)
	v_mfma_f32_16x16x32_bf16 v[60:63], v[120:123], v[178:181], v[60:63]
	v_mfma_f32_16x16x32_bf16 v[56:59], v[132:135], v[178:181], v[56:59]
	v_mfma_f32_16x16x32_bf16 v[44:47], v[120:123], v[186:189], v[44:47]
	v_mfma_f32_16x16x32_bf16 v[40:43], v[132:135], v[186:189], v[40:43]
	v_mfma_f32_16x16x32_bf16 v[28:31], v[120:123], v[210:213], v[28:31]
	v_mfma_f32_16x16x32_bf16 v[24:27], v[132:135], v[210:213], v[24:27]
	v_mfma_f32_16x16x32_bf16 v[12:15], v[120:123], v[218:221], v[12:15]
	v_mfma_f32_16x16x32_bf16 v[8:11], v[132:135], v[218:221], v[8:11]
	v_mfma_f32_16x16x32_bf16 v[60:63], v[128:131], v[182:185], v[60:63]
	v_mfma_f32_16x16x32_bf16 v[56:59], v[140:143], v[182:185], v[56:59]
	v_mfma_f32_16x16x32_bf16 v[44:47], v[128:131], v[206:209], v[44:47]
	v_mfma_f32_16x16x32_bf16 v[40:43], v[140:143], v[206:209], v[40:43]
	v_mfma_f32_16x16x32_bf16 v[28:31], v[128:131], v[214:217], v[28:31]
	v_mfma_f32_16x16x32_bf16 v[24:27], v[140:143], v[214:217], v[24:27]
	v_mfma_f32_16x16x32_bf16 v[12:15], v[128:131], v[222:225], v[12:15]
	v_mfma_f32_16x16x32_bf16 v[8:11], v[140:143], v[222:225], v[8:11]
	v_mfma_f32_16x16x32_bf16 v[52:55], v[144:147], v[178:181], v[52:55]
	v_mfma_f32_16x16x32_bf16 v[48:51], v[152:155], v[178:181], v[48:51]
	v_mfma_f32_16x16x32_bf16 v[36:39], v[144:147], v[186:189], v[36:39]
	v_mfma_f32_16x16x32_bf16 v[32:35], v[152:155], v[186:189], v[32:35]
	v_mfma_f32_16x16x32_bf16 v[20:23], v[144:147], v[210:213], v[20:23]
	v_mfma_f32_16x16x32_bf16 v[16:19], v[152:155], v[210:213], v[16:19]
	v_mfma_f32_16x16x32_bf16 v[0:3], v[144:147], v[218:221], v[0:3]
	v_mfma_f32_16x16x32_bf16 v[4:7], v[152:155], v[218:221], v[4:7]
	v_mfma_f32_16x16x32_bf16 v[52:55], v[148:151], v[182:185], v[52:55]
	v_mfma_f32_16x16x32_bf16 v[48:51], v[156:159], v[182:185], v[48:51]
	v_mfma_f32_16x16x32_bf16 v[36:39], v[148:151], v[206:209], v[36:39]
	v_mfma_f32_16x16x32_bf16 v[32:35], v[156:159], v[206:209], v[32:35]
	v_mfma_f32_16x16x32_bf16 v[20:23], v[148:151], v[214:217], v[20:23]
	v_mfma_f32_16x16x32_bf16 v[16:19], v[156:159], v[214:217], v[16:19]
	v_mfma_f32_16x16x32_bf16 v[0:3], v[148:151], v[222:225], v[0:3]
	v_mfma_f32_16x16x32_bf16 v[4:7], v[156:159], v[222:225], v[4:7]
	s_barrier
	s_setprio 0
	s_add_i32 s36, 0, 0x18000
	s_add_i32 s37, 0, 0x1c000
	v_add_u32_e32 v140, s36, v190
	v_add_u32_e32 v156, s37, v190
	ds_read_b128 v[120:123], v140
	ds_read_b128 v[128:131], v140 offset:1024
	ds_read_b128 v[132:135], v140 offset:2048
	ds_read_b128 v[140:143], v140 offset:3072
	ds_read_b128 v[144:147], v156
	ds_read_b128 v[148:151], v156 offset:1024
	ds_read_b128 v[152:155], v156 offset:2048
	ds_read_b128 v[156:159], v156 offset:3072
	s_add_u32 s16, s16, 0x80000
	s_addc_u32 s17, s17, 0
	s_mov_b32 m0, s21
	v_lshl_add_u64 v[238:239], s[16:17], 0, v[166:167]
	ds_read_b128 v[178:181], v191 offset:32768
	ds_read_b128 v[182:185], v191 offset:33792
	ds_read_b128 v[186:189], v191 offset:34816
	ds_read_b128 v[206:209], v191 offset:35840
	ds_read_b128 v[210:213], v191 offset:36864
	ds_read_b128 v[214:217], v191 offset:37888
	ds_read_b128 v[218:221], v191 offset:38912
	ds_read_b128 v[222:225], v191 offset:39936
	global_load_lds_dwordx4 v[238:239], off
	v_lshl_add_u64 v[238:239], s[16:17], 0, v[162:163]
	s_mov_b32 m0, s22
	s_nop 0
	global_load_lds_dwordx4 v[238:239], off
	s_waitcnt vmcnt(8)
	s_waitcnt lgkmcnt(0)
	s_setprio 1
	s_barrier
	s_waitcnt lgkmcnt(0)
	v_mfma_f32_16x16x32_bf16 v[136:139], v[120:123], v[178:181], v[136:139]
	v_mfma_f32_16x16x32_bf16 v[124:127], v[132:135], v[178:181], v[124:127]
	v_mfma_f32_16x16x32_bf16 v[108:111], v[120:123], v[186:189], v[108:111]
	v_mfma_f32_16x16x32_bf16 v[104:107], v[132:135], v[186:189], v[104:107]
	v_mfma_f32_16x16x32_bf16 v[92:95], v[120:123], v[210:213], v[92:95]
	v_mfma_f32_16x16x32_bf16 v[88:91], v[132:135], v[210:213], v[88:91]
	v_mfma_f32_16x16x32_bf16 v[76:79], v[120:123], v[218:221], v[76:79]
	v_mfma_f32_16x16x32_bf16 v[72:75], v[132:135], v[218:221], v[72:75]
	v_mfma_f32_16x16x32_bf16 v[136:139], v[128:131], v[182:185], v[136:139]
	v_mfma_f32_16x16x32_bf16 v[124:127], v[140:143], v[182:185], v[124:127]
	v_mfma_f32_16x16x32_bf16 v[108:111], v[128:131], v[206:209], v[108:111]
	v_mfma_f32_16x16x32_bf16 v[104:107], v[140:143], v[206:209], v[104:107]
	v_mfma_f32_16x16x32_bf16 v[92:95], v[128:131], v[214:217], v[92:95]
	v_mfma_f32_16x16x32_bf16 v[88:91], v[140:143], v[214:217], v[88:91]
	v_mfma_f32_16x16x32_bf16 v[76:79], v[128:131], v[222:225], v[76:79]
	v_mfma_f32_16x16x32_bf16 v[72:75], v[140:143], v[222:225], v[72:75]
	v_mfma_f32_16x16x32_bf16 v[116:119], v[144:147], v[178:181], v[116:119]
	v_mfma_f32_16x16x32_bf16 v[112:115], v[152:155], v[178:181], v[112:115]
	v_mfma_f32_16x16x32_bf16 v[100:103], v[144:147], v[186:189], v[100:103]
	v_mfma_f32_16x16x32_bf16 v[96:99], v[152:155], v[186:189], v[96:99]
	v_mfma_f32_16x16x32_bf16 v[84:87], v[144:147], v[210:213], v[84:87]
	v_mfma_f32_16x16x32_bf16 v[80:83], v[152:155], v[210:213], v[80:83]
	v_mfma_f32_16x16x32_bf16 v[68:71], v[144:147], v[218:221], v[68:71]
	v_mfma_f32_16x16x32_bf16 v[64:67], v[152:155], v[218:221], v[64:67]
	v_mfma_f32_16x16x32_bf16 v[116:119], v[148:151], v[182:185], v[116:119]
	v_mfma_f32_16x16x32_bf16 v[112:115], v[156:159], v[182:185], v[112:115]
	v_mfma_f32_16x16x32_bf16 v[100:103], v[148:151], v[206:209], v[100:103]
	v_mfma_f32_16x16x32_bf16 v[96:99], v[156:159], v[206:209], v[96:99]
	v_mfma_f32_16x16x32_bf16 v[84:87], v[148:151], v[214:217], v[84:87]
	v_mfma_f32_16x16x32_bf16 v[80:83], v[156:159], v[214:217], v[80:83]
	v_mfma_f32_16x16x32_bf16 v[68:71], v[148:151], v[222:225], v[68:71]
	v_mfma_f32_16x16x32_bf16 v[64:67], v[156:159], v[222:225], v[64:67]
	s_barrier
; #define PG8_STAGE(bufoff, gbase, voff) do { _Pragma("unroll") for (int _i = 0; _i < 2; ++_i) \
;         __builtin_amdgcn_global_load_lds((const unsigned*)((const char*)(gbase) + (voff)[_i]), (LAS unsigned*)(lds + (bufoff) + ldsw + _i * 8192), 16, 0, 0); } while (0)
; #define PG8_LDA(dst, b, h) do { _Pragma("unroll") for (int m = 0; m < 4; ++m) _Pragma("unroll") for (int k = 0; k < 2; ++k) dst[m][k] = *(const LAS bf16x8*)(lds + PG8_SA(b, h) + aoff + m * 2048 + k * 1024); } while (0)
; #define PG8_MMA(ai, bj, At, Bt) do { __builtin_amdgcn_s_setprio(1); _Pragma("unroll") for (int m = 0; m < 4; ++m) _Pragma("unroll") for (int n = 0; n < 2; ++n) _Pragma("unroll") for (int k = 0; k < 2; ++k) \
;         acc[ai][bj][m][n] = __builtin_amdgcn_mfma_f32_16x16x32_bf16(Bt[n][k], At[m][k], acc[ai][bj][m][n], 0, 0, 0); __builtin_amdgcn_s_setprio(0); } while (0)
; #define PG8_WAIT_V(n) asm volatile("s_waitcnt vmcnt(" #n ")" ::: "memory")
; #define PG8_WAIT_L(n) asm volatile("s_waitcnt lgkmcnt(" #n ")" ::: "memory")
; #define PG8_BAR __builtin_amdgcn_s_barrier()
; #define PG8_SCHED __builtin_amdgcn_sched_barrier(0)
; template <class Epi, bool PERMA = false, bool DUAL = false, bool ALIGN_EPI = true, bool SP2 = true>
; __device__ __forceinline__ void gemm_phase(LAS unsigned char* lds, const Gemm g, const StaticOrder& S, const Epi& E) {
;     ...
;             PG8_LDA(At, 1, 1); PG8_STAGE(PG8_SB(1, 0), b3, voffB); PG8_STAGE(PG8_SB(1, 1), b3 + hstepB, voffB); PG8_STAGE(PG8_SA(1, 0), a3, voffA);
;             PG8_WAIT_V(8); PG8_WAIT_L(0); PG8_BAR; PG8_MMA(1, 0, At, B0); PG8_MMA(1, 1, At, B1); PG8_BAR; PG8_SCHED;
;     ...
;         if constexpr (ALIGN_EPI) { if (wr == 0) PG8_BAR; }
	s_setprio 0
	s_add_i32 s16, s36, s18
	v_lshl_add_u64 v[194:195], v[194:195], 0, s[46:47]
	s_mov_b32 m0, s16
	ds_read_b128 v[178:181], v191 offset:49152
	ds_read_b128 v[182:185], v191 offset:50176
	ds_read_b128 v[186:189], v191 offset:51200
	ds_read_b128 v[206:209], v191 offset:52224
	ds_read_b128 v[210:213], v191 offset:53248
	ds_read_b128 v[214:217], v191 offset:54272
	ds_read_b128 v[218:221], v191 offset:55296
	ds_read_b128 v[222:225], v191 offset:56320
	global_load_lds_dwordx4 v[194:195], off
	s_add_i32 m0, s16, 0x2000
	s_add_u32 s14, s14, 0x80080
	v_lshl_add_u64 v[194:195], v[196:197], 0, s[46:47]
	s_addc_u32 s15, s15, 0
	s_add_i32 s16, s37, s18
	global_load_lds_dwordx4 v[194:195], off
	v_lshl_add_u64 v[194:195], s[14:15], 0, v[164:165]
	s_mov_b32 m0, s16
	s_nop 0
	global_load_lds_dwordx4 v[194:195], off
	v_lshl_add_u64 v[194:195], s[14:15], 0, v[160:161]
	s_add_i32 m0, s16, 0x2000
	s_nop 0
	global_load_lds_dwordx4 v[194:195], off
	v_lshl_add_u64 v[194:195], v[226:227], 0, s[46:47]
	s_mov_b32 m0, s25
	s_nop 0
	global_load_lds_dwordx4 v[194:195], off
	v_lshl_add_u64 v[194:195], v[228:229], 0, s[46:47]
	s_mov_b32 m0, s26
	s_nop 0
	global_load_lds_dwordx4 v[194:195], off
	s_waitcnt vmcnt(8)
	s_waitcnt lgkmcnt(0)
	s_setprio 1
	s_barrier
	s_waitcnt lgkmcnt(0)
	v_mfma_f32_16x16x32_bf16 v[60:63], v[120:123], v[178:181], v[60:63]
	v_mfma_f32_16x16x32_bf16 v[56:59], v[132:135], v[178:181], v[56:59]
	v_mfma_f32_16x16x32_bf16 v[44:47], v[120:123], v[186:189], v[44:47]
	v_mfma_f32_16x16x32_bf16 v[40:43], v[132:135], v[186:189], v[40:43]
	v_mfma_f32_16x16x32_bf16 v[28:31], v[120:123], v[210:213], v[28:31]
	v_mfma_f32_16x16x32_bf16 v[24:27], v[132:135], v[210:213], v[24:27]
	v_mfma_f32_16x16x32_bf16 v[12:15], v[120:123], v[218:221], v[12:15]
	v_mfma_f32_16x16x32_bf16 v[8:11], v[132:135], v[218:221], v[8:11]
	v_mfma_f32_16x16x32_bf16 v[60:63], v[128:131], v[182:185], v[60:63]
	v_mfma_f32_16x16x32_bf16 v[56:59], v[140:143], v[182:185], v[56:59]
	v_mfma_f32_16x16x32_bf16 v[44:47], v[128:131], v[206:209], v[44:47]
	v_mfma_f32_16x16x32_bf16 v[40:43], v[140:143], v[206:209], v[40:43]
	v_mfma_f32_16x16x32_bf16 v[28:31], v[128:131], v[214:217], v[28:31]
	v_mfma_f32_16x16x32_bf16 v[24:27], v[140:143], v[214:217], v[24:27]
	v_mfma_f32_16x16x32_bf16 v[12:15], v[128:131], v[222:225], v[12:15]
	v_mfma_f32_16x16x32_bf16 v[8:11], v[140:143], v[222:225], v[8:11]
	v_mfma_f32_16x16x32_bf16 v[52:55], v[144:147], v[178:181], v[52:55]
	v_mfma_f32_16x16x32_bf16 v[48:51], v[152:155], v[178:181], v[48:51]
	v_mfma_f32_16x16x32_bf16 v[36:39], v[144:147], v[186:189], v[36:39]
	v_mfma_f32_16x16x32_bf16 v[32:35], v[152:155], v[186:189], v[32:35]
	v_mfma_f32_16x16x32_bf16 v[20:23], v[144:147], v[210:213], v[20:23]
	v_mfma_f32_16x16x32_bf16 v[16:19], v[152:155], v[210:213], v[16:19]
	v_mfma_f32_16x16x32_bf16 v[0:3], v[144:147], v[218:221], v[0:3]
	v_mfma_f32_16x16x32_bf16 v[4:7], v[152:155], v[218:221], v[4:7]
	v_mfma_f32_16x16x32_bf16 v[52:55], v[148:151], v[182:185], v[52:55]
	v_mfma_f32_16x16x32_bf16 v[48:51], v[156:159], v[182:185], v[48:51]
	v_mfma_f32_16x16x32_bf16 v[36:39], v[148:151], v[206:209], v[36:39]
	v_mfma_f32_16x16x32_bf16 v[32:35], v[156:159], v[206:209], v[32:35]
	v_mfma_f32_16x16x32_bf16 v[20:23], v[148:151], v[214:217], v[20:23]
	v_mfma_f32_16x16x32_bf16 v[16:19], v[156:159], v[214:217], v[16:19]
	v_mfma_f32_16x16x32_bf16 v[0:3], v[148:151], v[222:225], v[0:3]
	v_mfma_f32_16x16x32_bf16 v[4:7], v[156:159], v[222:225], v[4:7]
	s_barrier
	s_setprio 0
	s_add_i32 s35, s35, 2
	s_add_u32 s12, s12, 0x100
	s_addc_u32 s13, s13, 0
	s_add_u32 s33, s33, 0x100
	s_addc_u32 s34, s34, 0
	s_cmp_gt_u32 s35, 29
	s_cbranch_scc0 .LBB0_790
	s_and_b64 vcc, exec, s[2:3]
	s_cbranch_vccz .LBB0_793
	s_barrier
